# steady K-loop MFMA blocks: no-op counted lgkmcnt waits and setprio 0/1 pair removed (lgkmcnt(0) already precedes the block barrier)
# baseline (speedup 1.0000x reference)
.LBB0_257:
	s_or_b64 exec, exec, s[50:51]
	s_add_u32 s0, s12, s6
	ds_read_b128 v[146:149], v137
	ds_read_b128 v[150:153], v137 offset:1024
	ds_read_b128 v[154:157], v137 offset:2048
	ds_read_b128 v[158:161], v137 offset:3072
	ds_read_b128 v[162:165], v138
	ds_read_b128 v[166:169], v138 offset:1024
	ds_read_b128 v[170:173], v138 offset:2048
	ds_read_b128 v[174:177], v138 offset:3072
	s_addc_u32 s1, s13, s7
	s_add_u32 s50, s0, 0x20000
	s_addc_u32 s51, s1, 0
	s_add_u32 s52, s93, s6
	s_addc_u32 s53, s94, s7
	s_cmp_eq_u32 s6, 0x60000
	s_cselect_b32 s62, s95, s50
	s_cselect_b32 s63, s31, s51
	s_cselect_b32 s51, s29, s53
	s_cselect_b32 s50, s96, s52
	s_add_u32 s52, s62, 0x8000
	s_addc_u32 s53, s63, 0
	s_add_u32 s54, s50, 0x8000
	s_addc_u32 s55, s51, 0
	ds_read_b128 v[178:181], v139
	ds_read_b128 v[182:185], v139 offset:1024
	ds_read_b128 v[186:189], v139 offset:2048
	ds_read_b128 v[190:193], v139 offset:3072
	ds_read_b128 v[198:201], v139 offset:4096
	ds_read_b128 v[202:205], v139 offset:5120
	ds_read_b128 v[206:209], v139 offset:6144
	ds_read_b128 v[212:215], v139 offset:7168
	s_add_u32 s0, s0, 0x1c000
	s_addc_u32 s1, s1, 0
	s_mov_b32 m0, s78
	s_nop 0
	global_load_lds_dwordx4 v134, s[0:1]
	s_add_u32 m0, s78, 0x2000
	s_nop 0
	global_load_lds_dwordx4 v135, s[0:1]
	s_waitcnt vmcnt(8)
	s_waitcnt lgkmcnt(0)
	s_setprio 1
	s_barrier
	v_mfma_f32_16x16x32_bf16 v[122:125], v[146:149], v[178:181], v[122:125]
	v_mfma_f32_16x16x32_bf16 v[122:125], v[150:153], v[182:185], v[122:125]
	v_mfma_f32_16x16x32_bf16 v[114:117], v[154:157], v[178:181], v[114:117]
	v_mfma_f32_16x16x32_bf16 v[114:117], v[158:161], v[182:185], v[114:117]
	v_mfma_f32_16x16x32_bf16 v[106:109], v[146:149], v[186:189], v[106:109]
	v_mfma_f32_16x16x32_bf16 v[106:109], v[150:153], v[190:193], v[106:109]
	v_mfma_f32_16x16x32_bf16 v[98:101], v[154:157], v[186:189], v[98:101]
	v_mfma_f32_16x16x32_bf16 v[98:101], v[158:161], v[190:193], v[98:101]
	v_mfma_f32_16x16x32_bf16 v[90:93], v[146:149], v[198:201], v[90:93]
	v_mfma_f32_16x16x32_bf16 v[90:93], v[150:153], v[202:205], v[90:93]
	v_mfma_f32_16x16x32_bf16 v[82:85], v[154:157], v[198:201], v[82:85]
	v_mfma_f32_16x16x32_bf16 v[82:85], v[158:161], v[202:205], v[82:85]
	v_mfma_f32_16x16x32_bf16 v[74:77], v[146:149], v[206:209], v[74:77]
	v_mfma_f32_16x16x32_bf16 v[74:77], v[150:153], v[212:215], v[74:77]
	v_mfma_f32_16x16x32_bf16 v[66:69], v[154:157], v[206:209], v[66:69]
	v_mfma_f32_16x16x32_bf16 v[66:69], v[158:161], v[212:215], v[66:69]
	v_mfma_f32_16x16x32_bf16 v[126:129], v[162:165], v[178:181], v[126:129]
	v_mfma_f32_16x16x32_bf16 v[126:129], v[166:169], v[182:185], v[126:129]
	v_mfma_f32_16x16x32_bf16 v[118:121], v[170:173], v[178:181], v[118:121]
	v_mfma_f32_16x16x32_bf16 v[118:121], v[174:177], v[182:185], v[118:121]
	v_mfma_f32_16x16x32_bf16 v[110:113], v[162:165], v[186:189], v[110:113]
	v_mfma_f32_16x16x32_bf16 v[110:113], v[166:169], v[190:193], v[110:113]
	v_mfma_f32_16x16x32_bf16 v[102:105], v[170:173], v[186:189], v[102:105]
	v_mfma_f32_16x16x32_bf16 v[102:105], v[174:177], v[190:193], v[102:105]
	v_mfma_f32_16x16x32_bf16 v[94:97], v[162:165], v[198:201], v[94:97]
	v_mfma_f32_16x16x32_bf16 v[94:97], v[166:169], v[202:205], v[94:97]
	v_mfma_f32_16x16x32_bf16 v[86:89], v[170:173], v[198:201], v[86:89]
	v_mfma_f32_16x16x32_bf16 v[86:89], v[174:177], v[202:205], v[86:89]
	v_mfma_f32_16x16x32_bf16 v[78:81], v[162:165], v[206:209], v[78:81]
	v_mfma_f32_16x16x32_bf16 v[78:81], v[166:169], v[212:215], v[78:81]
	s_setprio 2
	s_barrier
	v_mfma_f32_16x16x32_bf16 v[70:73], v[170:173], v[206:209], v[70:73]
	v_mfma_f32_16x16x32_bf16 v[70:73], v[174:177], v[212:215], v[70:73]
	s_setprio 0
	s_nop 0
	ds_read_b128 v[178:181], v139 offset:16384
	ds_read_b128 v[182:185], v139 offset:17408
	ds_read_b128 v[186:189], v139 offset:18432
	ds_read_b128 v[190:193], v139 offset:19456
	ds_read_b128 v[198:201], v139 offset:20480
	ds_read_b128 v[202:205], v139 offset:21504
	ds_read_b128 v[206:209], v139 offset:22528
	ds_read_b128 v[212:215], v139 offset:23552
	s_mov_b32 m0, s11
	s_nop 0
	global_load_lds_dwordx4 v134, s[50:51]
	s_add_u32 m0, s11, 0x2000
	s_nop 0
	global_load_lds_dwordx4 v135, s[50:51]
	s_add_u32 s0, s50, 0x4000
	s_addc_u32 s1, s51, 0
	s_mov_b32 m0, s68
	s_nop 0
	global_load_lds_dwordx4 v134, s[0:1]
	s_add_u32 m0, s68, 0x2000
	s_nop 0
	global_load_lds_dwordx4 v135, s[0:1]
	s_nop 0
	s_mov_b32 m0, s65
	s_nop 0
	global_load_lds_dwordx4 v134, s[62:63]
	s_add_u32 m0, s65, 0x2000
	s_nop 0
	global_load_lds_dwordx4 v135, s[62:63]
	s_waitcnt vmcnt(8)
	s_waitcnt lgkmcnt(0)
	s_setprio 1
	s_barrier
	v_mfma_f32_16x16x32_bf16 v[58:61], v[146:149], v[178:181], v[58:61]
	v_mfma_f32_16x16x32_bf16 v[58:61], v[150:153], v[182:185], v[58:61]
	v_mfma_f32_16x16x32_bf16 v[50:53], v[154:157], v[178:181], v[50:53]
	v_mfma_f32_16x16x32_bf16 v[50:53], v[158:161], v[182:185], v[50:53]
	v_mfma_f32_16x16x32_bf16 v[42:45], v[146:149], v[186:189], v[42:45]
	v_mfma_f32_16x16x32_bf16 v[42:45], v[150:153], v[190:193], v[42:45]
	v_mfma_f32_16x16x32_bf16 v[34:37], v[154:157], v[186:189], v[34:37]
	v_mfma_f32_16x16x32_bf16 v[34:37], v[158:161], v[190:193], v[34:37]
	v_mfma_f32_16x16x32_bf16 v[26:29], v[146:149], v[198:201], v[26:29]
	v_mfma_f32_16x16x32_bf16 v[26:29], v[150:153], v[202:205], v[26:29]
	v_mfma_f32_16x16x32_bf16 v[18:21], v[154:157], v[198:201], v[18:21]
	v_mfma_f32_16x16x32_bf16 v[18:21], v[158:161], v[202:205], v[18:21]
	v_mfma_f32_16x16x32_bf16 v[10:13], v[146:149], v[206:209], v[10:13]
	v_mfma_f32_16x16x32_bf16 v[10:13], v[150:153], v[212:215], v[10:13]
	v_mfma_f32_16x16x32_bf16 v[2:5], v[154:157], v[206:209], v[2:5]
	v_mfma_f32_16x16x32_bf16 v[2:5], v[158:161], v[212:215], v[2:5]
	v_mfma_f32_16x16x32_bf16 v[62:65], v[162:165], v[178:181], v[62:65]
	v_mfma_f32_16x16x32_bf16 v[62:65], v[166:169], v[182:185], v[62:65]
	v_mfma_f32_16x16x32_bf16 v[54:57], v[170:173], v[178:181], v[54:57]
	v_mfma_f32_16x16x32_bf16 v[54:57], v[174:177], v[182:185], v[54:57]
	v_mfma_f32_16x16x32_bf16 v[46:49], v[162:165], v[186:189], v[46:49]
	v_mfma_f32_16x16x32_bf16 v[46:49], v[166:169], v[190:193], v[46:49]
	v_mfma_f32_16x16x32_bf16 v[38:41], v[170:173], v[186:189], v[38:41]
	v_mfma_f32_16x16x32_bf16 v[38:41], v[174:177], v[190:193], v[38:41]
	v_mfma_f32_16x16x32_bf16 v[30:33], v[162:165], v[198:201], v[30:33]
	v_mfma_f32_16x16x32_bf16 v[30:33], v[166:169], v[202:205], v[30:33]
	v_mfma_f32_16x16x32_bf16 v[22:25], v[170:173], v[198:201], v[22:25]
	v_mfma_f32_16x16x32_bf16 v[22:25], v[174:177], v[202:205], v[22:25]
	v_mfma_f32_16x16x32_bf16 v[14:17], v[162:165], v[206:209], v[14:17]
	v_mfma_f32_16x16x32_bf16 v[14:17], v[166:169], v[212:215], v[14:17]
	s_setprio 2
	s_barrier
	v_mfma_f32_16x16x32_bf16 v[6:9], v[170:173], v[206:209], v[6:9]
	v_mfma_f32_16x16x32_bf16 v[6:9], v[174:177], v[212:215], v[6:9]
	s_setprio 0
	s_nop 0
	ds_read_b128 v[146:149], v140
	ds_read_b128 v[150:153], v140 offset:1024
	ds_read_b128 v[154:157], v140 offset:2048
	ds_read_b128 v[158:161], v140 offset:3072
	ds_read_b128 v[162:165], v141
	ds_read_b128 v[166:169], v141 offset:1024
	ds_read_b128 v[170:173], v141 offset:2048
	ds_read_b128 v[174:177], v141 offset:3072
	ds_read_b128 v[178:181], v139 offset:32768
	ds_read_b128 v[182:185], v139 offset:33792
	ds_read_b128 v[186:189], v139 offset:34816
	ds_read_b128 v[190:193], v139 offset:35840
	ds_read_b128 v[198:201], v139 offset:36864
	ds_read_b128 v[202:205], v139 offset:37888
	ds_read_b128 v[206:209], v139 offset:38912
	ds_read_b128 v[212:215], v139 offset:39936
	s_add_u32 s0, s62, 0x4000
	s_addc_u32 s1, s63, 0
	s_mov_b32 m0, s69
	s_nop 0
	global_load_lds_dwordx4 v134, s[0:1]
	s_add_u32 m0, s69, 0x2000
	s_nop 0
	global_load_lds_dwordx4 v135, s[0:1]
	s_waitcnt vmcnt(8)
	s_waitcnt lgkmcnt(0)
	s_setprio 1
	s_barrier
	v_mfma_f32_16x16x32_bf16 v[122:125], v[146:149], v[178:181], v[122:125]
	v_mfma_f32_16x16x32_bf16 v[122:125], v[150:153], v[182:185], v[122:125]
	v_mfma_f32_16x16x32_bf16 v[114:117], v[154:157], v[178:181], v[114:117]
	v_mfma_f32_16x16x32_bf16 v[114:117], v[158:161], v[182:185], v[114:117]
	v_mfma_f32_16x16x32_bf16 v[106:109], v[146:149], v[186:189], v[106:109]
	v_mfma_f32_16x16x32_bf16 v[106:109], v[150:153], v[190:193], v[106:109]
	v_mfma_f32_16x16x32_bf16 v[98:101], v[154:157], v[186:189], v[98:101]
	v_mfma_f32_16x16x32_bf16 v[98:101], v[158:161], v[190:193], v[98:101]
	v_mfma_f32_16x16x32_bf16 v[90:93], v[146:149], v[198:201], v[90:93]
	v_mfma_f32_16x16x32_bf16 v[90:93], v[150:153], v[202:205], v[90:93]
	v_mfma_f32_16x16x32_bf16 v[82:85], v[154:157], v[198:201], v[82:85]
	v_mfma_f32_16x16x32_bf16 v[82:85], v[158:161], v[202:205], v[82:85]
	v_mfma_f32_16x16x32_bf16 v[74:77], v[146:149], v[206:209], v[74:77]
	v_mfma_f32_16x16x32_bf16 v[74:77], v[150:153], v[212:215], v[74:77]
	v_mfma_f32_16x16x32_bf16 v[66:69], v[154:157], v[206:209], v[66:69]
	v_mfma_f32_16x16x32_bf16 v[66:69], v[158:161], v[212:215], v[66:69]
	v_mfma_f32_16x16x32_bf16 v[126:129], v[162:165], v[178:181], v[126:129]
	v_mfma_f32_16x16x32_bf16 v[126:129], v[166:169], v[182:185], v[126:129]
	v_mfma_f32_16x16x32_bf16 v[118:121], v[170:173], v[178:181], v[118:121]
	v_mfma_f32_16x16x32_bf16 v[118:121], v[174:177], v[182:185], v[118:121]
	v_mfma_f32_16x16x32_bf16 v[110:113], v[162:165], v[186:189], v[110:113]
	v_mfma_f32_16x16x32_bf16 v[110:113], v[166:169], v[190:193], v[110:113]
	v_mfma_f32_16x16x32_bf16 v[102:105], v[170:173], v[186:189], v[102:105]
	v_mfma_f32_16x16x32_bf16 v[102:105], v[174:177], v[190:193], v[102:105]
	v_mfma_f32_16x16x32_bf16 v[94:97], v[162:165], v[198:201], v[94:97]
	v_mfma_f32_16x16x32_bf16 v[94:97], v[166:169], v[202:205], v[94:97]
	v_mfma_f32_16x16x32_bf16 v[86:89], v[170:173], v[198:201], v[86:89]
	v_mfma_f32_16x16x32_bf16 v[86:89], v[174:177], v[202:205], v[86:89]
	v_mfma_f32_16x16x32_bf16 v[78:81], v[162:165], v[206:209], v[78:81]
	v_mfma_f32_16x16x32_bf16 v[78:81], v[166:169], v[212:215], v[78:81]
	s_setprio 2
	s_barrier
	v_mfma_f32_16x16x32_bf16 v[70:73], v[170:173], v[206:209], v[70:73]
	v_mfma_f32_16x16x32_bf16 v[70:73], v[174:177], v[212:215], v[70:73]
	s_setprio 0
	s_nop 0
	ds_read_b128 v[178:181], v139 offset:49152
	ds_read_b128 v[182:185], v139 offset:50176
	ds_read_b128 v[186:189], v139 offset:51200
	ds_read_b128 v[190:193], v139 offset:52224
	ds_read_b128 v[198:201], v139 offset:53248
	ds_read_b128 v[202:205], v139 offset:54272
	ds_read_b128 v[206:209], v139 offset:55296
	ds_read_b128 v[212:215], v139 offset:56320
	s_mov_b32 m0, s74
	s_nop 0
	global_load_lds_dwordx4 v134, s[54:55]
	s_add_u32 m0, s74, 0x2000
	s_nop 0
	global_load_lds_dwordx4 v135, s[54:55]
	s_add_u32 s0, s50, 0xc000
	s_addc_u32 s1, s51, 0
	s_mov_b32 m0, s77
	s_nop 0
	global_load_lds_dwordx4 v134, s[0:1]
	s_add_u32 m0, s77, 0x2000
	s_nop 0
	global_load_lds_dwordx4 v135, s[0:1]
	s_nop 0
	s_mov_b32 m0, s76
	s_nop 0
	global_load_lds_dwordx4 v134, s[52:53]
	s_add_u32 m0, s76, 0x2000
	s_nop 0
	global_load_lds_dwordx4 v135, s[52:53]
	s_waitcnt vmcnt(8)
	s_waitcnt lgkmcnt(0)
	s_setprio 1
	s_barrier
	v_mfma_f32_16x16x32_bf16 v[58:61], v[146:149], v[178:181], v[58:61]
	v_mfma_f32_16x16x32_bf16 v[58:61], v[150:153], v[182:185], v[58:61]
	v_mfma_f32_16x16x32_bf16 v[50:53], v[154:157], v[178:181], v[50:53]
	v_mfma_f32_16x16x32_bf16 v[50:53], v[158:161], v[182:185], v[50:53]
	v_mfma_f32_16x16x32_bf16 v[42:45], v[146:149], v[186:189], v[42:45]
	v_mfma_f32_16x16x32_bf16 v[42:45], v[150:153], v[190:193], v[42:45]
	v_mfma_f32_16x16x32_bf16 v[34:37], v[154:157], v[186:189], v[34:37]
	v_mfma_f32_16x16x32_bf16 v[34:37], v[158:161], v[190:193], v[34:37]
	v_mfma_f32_16x16x32_bf16 v[26:29], v[146:149], v[198:201], v[26:29]
	v_mfma_f32_16x16x32_bf16 v[26:29], v[150:153], v[202:205], v[26:29]
	v_mfma_f32_16x16x32_bf16 v[18:21], v[154:157], v[198:201], v[18:21]
	v_mfma_f32_16x16x32_bf16 v[18:21], v[158:161], v[202:205], v[18:21]
	v_mfma_f32_16x16x32_bf16 v[10:13], v[146:149], v[206:209], v[10:13]
	v_mfma_f32_16x16x32_bf16 v[10:13], v[150:153], v[212:215], v[10:13]
	v_mfma_f32_16x16x32_bf16 v[2:5], v[154:157], v[206:209], v[2:5]
	v_mfma_f32_16x16x32_bf16 v[2:5], v[158:161], v[212:215], v[2:5]
	v_mfma_f32_16x16x32_bf16 v[62:65], v[162:165], v[178:181], v[62:65]
	v_mfma_f32_16x16x32_bf16 v[62:65], v[166:169], v[182:185], v[62:65]
	v_mfma_f32_16x16x32_bf16 v[54:57], v[170:173], v[178:181], v[54:57]
	v_mfma_f32_16x16x32_bf16 v[54:57], v[174:177], v[182:185], v[54:57]
	v_mfma_f32_16x16x32_bf16 v[46:49], v[162:165], v[186:189], v[46:49]
	v_mfma_f32_16x16x32_bf16 v[46:49], v[166:169], v[190:193], v[46:49]
	v_mfma_f32_16x16x32_bf16 v[38:41], v[170:173], v[186:189], v[38:41]
	v_mfma_f32_16x16x32_bf16 v[38:41], v[174:177], v[190:193], v[38:41]
	v_mfma_f32_16x16x32_bf16 v[30:33], v[162:165], v[198:201], v[30:33]
	v_mfma_f32_16x16x32_bf16 v[30:33], v[166:169], v[202:205], v[30:33]
	v_mfma_f32_16x16x32_bf16 v[22:25], v[170:173], v[198:201], v[22:25]
	v_mfma_f32_16x16x32_bf16 v[22:25], v[174:177], v[202:205], v[22:25]
	v_mfma_f32_16x16x32_bf16 v[14:17], v[162:165], v[206:209], v[14:17]
	v_mfma_f32_16x16x32_bf16 v[14:17], v[166:169], v[212:215], v[14:17]
	s_setprio 2
	s_barrier
	v_mfma_f32_16x16x32_bf16 v[6:9], v[170:173], v[206:209], v[6:9]
	v_mfma_f32_16x16x32_bf16 v[6:9], v[174:177], v[212:215], v[6:9]
	s_setprio 0
	s_nop 0
	s_add_i32 s97, s97, 2
	s_add_u32 s6, s6, 0x10000
	s_addc_u32 s7, s7, 0
	s_cmp_gt_u32 s97, 13
	s_cbranch_scc1 .LBB0_259
	v_mov_b32_e32 v145, v130
	s_branch .LBB0_255

.LBB0_364:
	s_add_i32 s26, s93, 2
	s_lshl_b64 s[62:63], s[26:27], 15
	s_add_u32 s64, s18, s62
	s_addc_u32 s65, s19, s63
	s_and_b64 s[52:53], s[50:51], exec
	s_cselect_b32 s53, s65, s39
	s_cselect_b32 s52, s64, s38
	s_add_u32 s62, s20, s62
	s_waitcnt vmcnt(8)
	s_addc_u32 s63, s21, s63
	s_waitcnt lgkmcnt(0)
	s_and_b64 s[50:51], s[50:51], exec
	s_cselect_b32 s51, s63, s49
	s_cselect_b32 s50, s62, s48
	s_setprio 1
	s_barrier
	v_mfma_f32_16x16x32_bf16 v[126:129], v[146:149], v[186:189], v[126:129]
	v_mfma_f32_16x16x32_bf16 v[126:129], v[150:153], v[190:193], v[126:129]
	v_mfma_f32_16x16x32_bf16 v[122:125], v[154:157], v[186:189], v[122:125]
	v_mfma_f32_16x16x32_bf16 v[122:125], v[158:161], v[190:193], v[122:125]
	v_mfma_f32_16x16x32_bf16 v[118:121], v[146:149], v[178:181], v[118:121]
	v_mfma_f32_16x16x32_bf16 v[118:121], v[150:153], v[182:185], v[118:121]
	v_mfma_f32_16x16x32_bf16 v[114:117], v[154:157], v[178:181], v[114:117]
	v_mfma_f32_16x16x32_bf16 v[114:117], v[158:161], v[182:185], v[114:117]
	v_mfma_f32_16x16x32_bf16 v[110:113], v[146:149], v[170:173], v[110:113]
	v_mfma_f32_16x16x32_bf16 v[110:113], v[150:153], v[174:177], v[110:113]
	v_mfma_f32_16x16x32_bf16 v[106:109], v[154:157], v[170:173], v[106:109]
	v_mfma_f32_16x16x32_bf16 v[106:109], v[158:161], v[174:177], v[106:109]
	v_mfma_f32_16x16x32_bf16 v[102:105], v[146:149], v[162:165], v[102:105]
	v_mfma_f32_16x16x32_bf16 v[102:105], v[150:153], v[166:169], v[102:105]
	v_mfma_f32_16x16x32_bf16 v[98:101], v[154:157], v[162:165], v[98:101]
	v_mfma_f32_16x16x32_bf16 v[98:101], v[158:161], v[166:169], v[98:101]
	v_mfma_f32_16x16x32_bf16 v[94:97], v[130:133], v[186:189], v[94:97]
	v_mfma_f32_16x16x32_bf16 v[94:97], v[134:137], v[190:193], v[94:97]
	v_mfma_f32_16x16x32_bf16 v[90:93], v[138:141], v[186:189], v[90:93]
	v_mfma_f32_16x16x32_bf16 v[90:93], v[142:145], v[190:193], v[90:93]
	v_mfma_f32_16x16x32_bf16 v[86:89], v[130:133], v[178:181], v[86:89]
	v_mfma_f32_16x16x32_bf16 v[86:89], v[134:137], v[182:185], v[86:89]
	v_mfma_f32_16x16x32_bf16 v[82:85], v[138:141], v[178:181], v[82:85]
	v_mfma_f32_16x16x32_bf16 v[82:85], v[142:145], v[182:185], v[82:85]
	v_mfma_f32_16x16x32_bf16 v[78:81], v[130:133], v[170:173], v[78:81]
	v_mfma_f32_16x16x32_bf16 v[78:81], v[134:137], v[174:177], v[78:81]
	v_mfma_f32_16x16x32_bf16 v[74:77], v[138:141], v[170:173], v[74:77]
	v_mfma_f32_16x16x32_bf16 v[74:77], v[142:145], v[174:177], v[74:77]
	v_mfma_f32_16x16x32_bf16 v[70:73], v[130:133], v[162:165], v[70:73]
	v_mfma_f32_16x16x32_bf16 v[70:73], v[134:137], v[166:169], v[70:73]
	s_setprio 2
	s_barrier
	v_mfma_f32_16x16x32_bf16 v[66:69], v[138:141], v[162:165], v[66:69]
	v_mfma_f32_16x16x32_bf16 v[66:69], v[142:145], v[166:169], v[66:69]
	s_setprio 0
	s_nop 0
	ds_read_b128 v[186:189], v219 offset:16384
	ds_read_b128 v[190:193], v219 offset:17408
	ds_read_b128 v[178:181], v219 offset:18432
	ds_read_b128 v[182:185], v219 offset:19456
	ds_read_b128 v[170:173], v219 offset:20480
	ds_read_b128 v[174:177], v219 offset:21504
	ds_read_b128 v[162:165], v219 offset:22528
	ds_read_b128 v[166:169], v219 offset:23552
	s_mov_b32 m0, s74
	s_nop 0
	global_load_lds_dwordx4 v195, s[50:51]
	s_add_u32 m0, s74, 0x2000
	s_nop 0
	global_load_lds_dwordx4 v212, s[50:51]
	s_add_u32 s62, s50, 0x4000
	s_addc_u32 s63, s51, 0
	s_mov_b32 m0, s75
	s_nop 0
	global_load_lds_dwordx4 v195, s[62:63]
	s_add_u32 m0, s75, 0x2000
	s_nop 0
	global_load_lds_dwordx4 v212, s[62:63]
	s_andn2_b64 vcc, exec, s[54:55]
	s_mov_b32 m0, s73
	s_nop 0
	global_load_lds_dwordx4 v195, s[52:53]
	s_add_u32 m0, s73, 0x2000
	s_nop 0
	global_load_lds_dwordx4 v212, s[52:53]
	s_cbranch_vccnz .LBB0_366
	v_mov_b32_e32 v2, 0
	v_mov_b32_e32 v3, v2
	v_mov_b32_e32 v4, v2
	v_mov_b32_e32 v5, v2
	v_mov_b32_e32 v6, v2
	v_mov_b32_e32 v7, v2
	v_mov_b32_e32 v8, v2
	v_mov_b32_e32 v9, v2
	v_mov_b32_e32 v10, v2
	v_mov_b32_e32 v11, v2
	v_mov_b32_e32 v12, v2
	v_mov_b32_e32 v13, v2
	v_mov_b32_e32 v14, v2
	v_mov_b32_e32 v15, v2
	v_mov_b32_e32 v16, v2
	v_mov_b32_e32 v17, v2
	v_mov_b32_e32 v18, v2
	v_mov_b32_e32 v19, v2
	v_mov_b32_e32 v20, v2
	v_mov_b32_e32 v21, v2
	v_mov_b32_e32 v22, v2
	v_mov_b32_e32 v23, v2
	v_mov_b32_e32 v24, v2
	v_mov_b32_e32 v25, v2
	v_mov_b32_e32 v26, v2
	v_mov_b32_e32 v27, v2
	v_mov_b32_e32 v28, v2
	v_mov_b32_e32 v29, v2
	v_mov_b32_e32 v30, v2
	v_mov_b32_e32 v31, v2
	v_mov_b32_e32 v32, v2
	v_mov_b32_e32 v33, v2
	v_mov_b32_e32 v34, v2
	v_mov_b32_e32 v35, v2
	v_mov_b32_e32 v36, v2
	v_mov_b32_e32 v37, v2
	v_mov_b32_e32 v38, v2
	v_mov_b32_e32 v39, v2
	v_mov_b32_e32 v40, v2
	v_mov_b32_e32 v41, v2
	v_mov_b32_e32 v42, v2
	v_mov_b32_e32 v43, v2
	v_mov_b32_e32 v44, v2
	v_mov_b32_e32 v45, v2
	v_mov_b32_e32 v46, v2
	v_mov_b32_e32 v47, v2
	v_mov_b32_e32 v48, v2
	v_mov_b32_e32 v49, v2
	v_mov_b32_e32 v50, v2
	v_mov_b32_e32 v51, v2
	v_mov_b32_e32 v52, v2
	v_mov_b32_e32 v53, v2
	v_mov_b32_e32 v54, v2
	v_mov_b32_e32 v55, v2
	v_mov_b32_e32 v56, v2
	v_mov_b32_e32 v57, v2
	v_mov_b32_e32 v58, v2
	v_mov_b32_e32 v59, v2
	v_mov_b32_e32 v60, v2
	v_mov_b32_e32 v61, v2
	v_mov_b32_e32 v62, v2
	v_mov_b32_e32 v63, v2
	v_mov_b32_e32 v64, v2
	v_mov_b32_e32 v65, v2
.LBB0_366:
	s_waitcnt vmcnt(8)
	s_add_u32 s54, s52, 0x8000
	s_waitcnt lgkmcnt(0)
	s_addc_u32 s55, s53, 0
	s_add_u32 s62, s50, 0x8000
	s_addc_u32 s63, s51, 0
	s_setprio 1
	s_barrier
	v_mfma_f32_16x16x32_bf16 v[62:65], v[146:149], v[186:189], v[62:65]
	v_mfma_f32_16x16x32_bf16 v[62:65], v[150:153], v[190:193], v[62:65]
	v_mfma_f32_16x16x32_bf16 v[58:61], v[154:157], v[186:189], v[58:61]
	v_mfma_f32_16x16x32_bf16 v[58:61], v[158:161], v[190:193], v[58:61]
	v_mfma_f32_16x16x32_bf16 v[54:57], v[146:149], v[178:181], v[54:57]
	v_mfma_f32_16x16x32_bf16 v[54:57], v[150:153], v[182:185], v[54:57]
	v_mfma_f32_16x16x32_bf16 v[50:53], v[154:157], v[178:181], v[50:53]
	v_mfma_f32_16x16x32_bf16 v[50:53], v[158:161], v[182:185], v[50:53]
	v_mfma_f32_16x16x32_bf16 v[46:49], v[146:149], v[170:173], v[46:49]
	v_mfma_f32_16x16x32_bf16 v[46:49], v[150:153], v[174:177], v[46:49]
	v_mfma_f32_16x16x32_bf16 v[42:45], v[154:157], v[170:173], v[42:45]
	v_mfma_f32_16x16x32_bf16 v[42:45], v[158:161], v[174:177], v[42:45]
	v_mfma_f32_16x16x32_bf16 v[38:41], v[146:149], v[162:165], v[38:41]
	v_mfma_f32_16x16x32_bf16 v[38:41], v[150:153], v[166:169], v[38:41]
	v_mfma_f32_16x16x32_bf16 v[34:37], v[154:157], v[162:165], v[34:37]
	v_mfma_f32_16x16x32_bf16 v[34:37], v[158:161], v[166:169], v[34:37]
	v_mfma_f32_16x16x32_bf16 v[30:33], v[130:133], v[186:189], v[30:33]
	v_mfma_f32_16x16x32_bf16 v[30:33], v[134:137], v[190:193], v[30:33]
	v_mfma_f32_16x16x32_bf16 v[26:29], v[138:141], v[186:189], v[26:29]
	v_mfma_f32_16x16x32_bf16 v[26:29], v[142:145], v[190:193], v[26:29]
	v_mfma_f32_16x16x32_bf16 v[22:25], v[130:133], v[178:181], v[22:25]
	v_mfma_f32_16x16x32_bf16 v[22:25], v[134:137], v[182:185], v[22:25]
	v_mfma_f32_16x16x32_bf16 v[18:21], v[138:141], v[178:181], v[18:21]
	v_mfma_f32_16x16x32_bf16 v[18:21], v[142:145], v[182:185], v[18:21]
	v_mfma_f32_16x16x32_bf16 v[14:17], v[130:133], v[170:173], v[14:17]
	v_mfma_f32_16x16x32_bf16 v[14:17], v[134:137], v[174:177], v[14:17]
	v_mfma_f32_16x16x32_bf16 v[10:13], v[138:141], v[170:173], v[10:13]
	v_mfma_f32_16x16x32_bf16 v[10:13], v[142:145], v[174:177], v[10:13]
	v_mfma_f32_16x16x32_bf16 v[6:9], v[130:133], v[162:165], v[6:9]
	v_mfma_f32_16x16x32_bf16 v[6:9], v[134:137], v[166:169], v[6:9]
	s_setprio 2
	s_barrier
	v_mfma_f32_16x16x32_bf16 v[2:5], v[138:141], v[162:165], v[2:5]
	v_mfma_f32_16x16x32_bf16 v[2:5], v[142:145], v[166:169], v[2:5]
	s_setprio 0
	s_nop 0
	v_add_u32_e32 v142, 0x18000, v218
	v_add_u32_e32 v158, 0x1c000, v218
	ds_read_b128 v[130:133], v142
	ds_read_b128 v[134:137], v142 offset:1024
	ds_read_b128 v[138:141], v142 offset:2048
	ds_read_b128 v[142:145], v142 offset:3072
	ds_read_b128 v[146:149], v158
	ds_read_b128 v[150:153], v158 offset:1024
	ds_read_b128 v[154:157], v158 offset:2048
	ds_read_b128 v[158:161], v158 offset:3072
	ds_read_b128 v[162:165], v219 offset:32768
	ds_read_b128 v[166:169], v219 offset:33792
	ds_read_b128 v[170:173], v219 offset:34816
	ds_read_b128 v[174:177], v219 offset:35840
	ds_read_b128 v[178:181], v219 offset:36864
	ds_read_b128 v[182:185], v219 offset:37888
	ds_read_b128 v[186:189], v219 offset:38912
	ds_read_b128 v[190:193], v219 offset:39936
	s_add_u32 s52, s52, 0x4000
	s_addc_u32 s53, s53, 0
	s_mov_b32 m0, s76
	s_nop 0
	global_load_lds_dwordx4 v195, s[52:53]
	s_add_u32 m0, s76, 0x2000
	s_nop 0
	global_load_lds_dwordx4 v212, s[52:53]
	s_waitcnt vmcnt(8)
	s_waitcnt lgkmcnt(0)
	s_setprio 1
	s_barrier
	v_mfma_f32_16x16x32_bf16 v[126:129], v[130:133], v[162:165], v[126:129]
	v_mfma_f32_16x16x32_bf16 v[126:129], v[134:137], v[166:169], v[126:129]
	v_mfma_f32_16x16x32_bf16 v[122:125], v[138:141], v[162:165], v[122:125]
	v_mfma_f32_16x16x32_bf16 v[122:125], v[142:145], v[166:169], v[122:125]
	v_mfma_f32_16x16x32_bf16 v[118:121], v[130:133], v[170:173], v[118:121]
	v_mfma_f32_16x16x32_bf16 v[118:121], v[134:137], v[174:177], v[118:121]
	v_mfma_f32_16x16x32_bf16 v[114:117], v[138:141], v[170:173], v[114:117]
	v_mfma_f32_16x16x32_bf16 v[114:117], v[142:145], v[174:177], v[114:117]
	v_mfma_f32_16x16x32_bf16 v[110:113], v[130:133], v[178:181], v[110:113]
	v_mfma_f32_16x16x32_bf16 v[110:113], v[134:137], v[182:185], v[110:113]
	v_mfma_f32_16x16x32_bf16 v[106:109], v[138:141], v[178:181], v[106:109]
	v_mfma_f32_16x16x32_bf16 v[106:109], v[142:145], v[182:185], v[106:109]
	v_mfma_f32_16x16x32_bf16 v[102:105], v[130:133], v[186:189], v[102:105]
	v_mfma_f32_16x16x32_bf16 v[102:105], v[134:137], v[190:193], v[102:105]
	v_mfma_f32_16x16x32_bf16 v[98:101], v[138:141], v[186:189], v[98:101]
	v_mfma_f32_16x16x32_bf16 v[98:101], v[142:145], v[190:193], v[98:101]
	v_mfma_f32_16x16x32_bf16 v[94:97], v[146:149], v[162:165], v[94:97]
	v_mfma_f32_16x16x32_bf16 v[94:97], v[150:153], v[166:169], v[94:97]
	v_mfma_f32_16x16x32_bf16 v[90:93], v[154:157], v[162:165], v[90:93]
	v_mfma_f32_16x16x32_bf16 v[90:93], v[158:161], v[166:169], v[90:93]
	v_mfma_f32_16x16x32_bf16 v[86:89], v[146:149], v[170:173], v[86:89]
	v_mfma_f32_16x16x32_bf16 v[86:89], v[150:153], v[174:177], v[86:89]
	v_mfma_f32_16x16x32_bf16 v[82:85], v[154:157], v[170:173], v[82:85]
	v_mfma_f32_16x16x32_bf16 v[82:85], v[158:161], v[174:177], v[82:85]
	v_mfma_f32_16x16x32_bf16 v[78:81], v[146:149], v[178:181], v[78:81]
	v_mfma_f32_16x16x32_bf16 v[78:81], v[150:153], v[182:185], v[78:81]
	v_mfma_f32_16x16x32_bf16 v[74:77], v[154:157], v[178:181], v[74:77]
	v_mfma_f32_16x16x32_bf16 v[74:77], v[158:161], v[182:185], v[74:77]
	v_mfma_f32_16x16x32_bf16 v[70:73], v[146:149], v[186:189], v[70:73]
	v_mfma_f32_16x16x32_bf16 v[70:73], v[150:153], v[190:193], v[70:73]
	s_setprio 2
	s_barrier
	v_mfma_f32_16x16x32_bf16 v[66:69], v[154:157], v[186:189], v[66:69]
	v_mfma_f32_16x16x32_bf16 v[66:69], v[158:161], v[190:193], v[66:69]
	s_setprio 0
	s_nop 0
	ds_read_b128 v[162:165], v219 offset:49152
	ds_read_b128 v[166:169], v219 offset:50176
	ds_read_b128 v[170:173], v219 offset:51200
	ds_read_b128 v[174:177], v219 offset:52224
	ds_read_b128 v[178:181], v219 offset:53248
	ds_read_b128 v[182:185], v219 offset:54272
	ds_read_b128 v[186:189], v219 offset:55296
	ds_read_b128 v[190:193], v219 offset:56320
	s_mov_b32 m0, s80
	s_nop 0
	global_load_lds_dwordx4 v195, s[62:63]
	s_add_u32 m0, s80, 0x2000
	s_nop 0
	global_load_lds_dwordx4 v212, s[62:63]
	s_add_u32 s50, s50, 0xc000
	s_addc_u32 s51, s51, 0
	s_mov_b32 m0, s82
	s_nop 0
	global_load_lds_dwordx4 v195, s[50:51]
	s_add_u32 m0, s82, 0x2000
	s_nop 0
	global_load_lds_dwordx4 v212, s[50:51]
	s_nop 0
	s_mov_b32 m0, s81
	s_nop 0
	global_load_lds_dwordx4 v195, s[54:55]
	s_add_u32 m0, s81, 0x2000
	s_nop 0
	global_load_lds_dwordx4 v212, s[54:55]
	s_waitcnt vmcnt(8)
	s_waitcnt lgkmcnt(0)
	s_setprio 1
	s_barrier
	v_mfma_f32_16x16x32_bf16 v[62:65], v[130:133], v[162:165], v[62:65]
	v_mfma_f32_16x16x32_bf16 v[62:65], v[134:137], v[166:169], v[62:65]
	v_mfma_f32_16x16x32_bf16 v[58:61], v[138:141], v[162:165], v[58:61]
	v_mfma_f32_16x16x32_bf16 v[58:61], v[142:145], v[166:169], v[58:61]
	v_mfma_f32_16x16x32_bf16 v[54:57], v[130:133], v[170:173], v[54:57]
	v_mfma_f32_16x16x32_bf16 v[54:57], v[134:137], v[174:177], v[54:57]
	v_mfma_f32_16x16x32_bf16 v[50:53], v[138:141], v[170:173], v[50:53]
	v_mfma_f32_16x16x32_bf16 v[50:53], v[142:145], v[174:177], v[50:53]
	v_mfma_f32_16x16x32_bf16 v[46:49], v[130:133], v[178:181], v[46:49]
	v_mfma_f32_16x16x32_bf16 v[46:49], v[134:137], v[182:185], v[46:49]
	v_mfma_f32_16x16x32_bf16 v[42:45], v[138:141], v[178:181], v[42:45]
	v_mfma_f32_16x16x32_bf16 v[42:45], v[142:145], v[182:185], v[42:45]
	v_mfma_f32_16x16x32_bf16 v[38:41], v[130:133], v[186:189], v[38:41]
	v_mfma_f32_16x16x32_bf16 v[38:41], v[134:137], v[190:193], v[38:41]
	v_mfma_f32_16x16x32_bf16 v[34:37], v[138:141], v[186:189], v[34:37]
	v_mfma_f32_16x16x32_bf16 v[34:37], v[142:145], v[190:193], v[34:37]
	v_mfma_f32_16x16x32_bf16 v[30:33], v[146:149], v[162:165], v[30:33]
	v_mfma_f32_16x16x32_bf16 v[30:33], v[150:153], v[166:169], v[30:33]
	v_mfma_f32_16x16x32_bf16 v[26:29], v[154:157], v[162:165], v[26:29]
	v_mfma_f32_16x16x32_bf16 v[26:29], v[158:161], v[166:169], v[26:29]
	v_mfma_f32_16x16x32_bf16 v[22:25], v[146:149], v[170:173], v[22:25]
	v_mfma_f32_16x16x32_bf16 v[22:25], v[150:153], v[174:177], v[22:25]
	v_mfma_f32_16x16x32_bf16 v[18:21], v[154:157], v[170:173], v[18:21]
	v_mfma_f32_16x16x32_bf16 v[18:21], v[158:161], v[174:177], v[18:21]
	v_mfma_f32_16x16x32_bf16 v[14:17], v[146:149], v[178:181], v[14:17]
	v_mfma_f32_16x16x32_bf16 v[14:17], v[150:153], v[182:185], v[14:17]
	v_mfma_f32_16x16x32_bf16 v[10:13], v[154:157], v[178:181], v[10:13]
	v_mfma_f32_16x16x32_bf16 v[10:13], v[158:161], v[182:185], v[10:13]
	v_mfma_f32_16x16x32_bf16 v[6:9], v[146:149], v[186:189], v[6:9]
	v_mfma_f32_16x16x32_bf16 v[6:9], v[150:153], v[190:193], v[6:9]
	s_setprio 2
	s_barrier
	v_mfma_f32_16x16x32_bf16 v[2:5], v[154:157], v[186:189], v[2:5]
	v_mfma_f32_16x16x32_bf16 v[2:5], v[158:161], v[190:193], v[2:5]
	s_setprio 0
	s_nop 0
	s_cmp_gt_u32 s93, 41
	s_cbranch_scc1 .LBB0_368
	v_mov_b32_e32 v130, v198
	s_mov_b32 s93, s26
	s_branch .LBB0_343

.LBB0_519:
	ds_read_b128 v[130:133], v141
	ds_read_b128 v[134:137], v141 offset:1024
	ds_read_b128 v[146:149], v141 offset:2048
	ds_read_b128 v[150:153], v141 offset:3072
	ds_read_b128 v[154:157], v142
	ds_read_b128 v[158:161], v142 offset:1024
	ds_read_b128 v[162:165], v142 offset:2048
	ds_read_b128 v[166:169], v142 offset:3072
	s_add_u32 s24, s26, 0x10000
	s_addc_u32 s25, s27, 0
	s_cmp_eq_u32 s77, 12
	s_cselect_b32 s48, s17, s24
	s_cselect_b32 s49, s1, s25
	s_cselect_b32 s30, s23, s75
	s_cselect_b32 s31, s15, s76
	s_add_u32 s28, s48, 0x8000
	s_addc_u32 s29, s49, 0
	ds_read_b128 v[170:173], v143
	ds_read_b128 v[174:177], v143 offset:1024
	ds_read_b128 v[178:181], v143 offset:2048
	ds_read_b128 v[182:185], v143 offset:3072
	ds_read_b128 v[186:189], v143 offset:4096
	ds_read_b128 v[190:193], v143 offset:5120
	ds_read_b128 v[198:201], v143 offset:6144
	ds_read_b128 v[202:205], v143 offset:7168
	s_add_u32 s38, s30, 0x8000
	s_addc_u32 s39, s31, 0
	s_add_u32 s26, s26, 0xc000
	s_addc_u32 s27, s27, 0
	s_mov_b32 m0, s72
	s_nop 0
	global_load_lds_dwordx4 v195, s[26:27]
	s_add_u32 m0, s72, 0x2000
	s_nop 0
	global_load_lds_dwordx4 v212, s[26:27]
	s_waitcnt vmcnt(8)
	s_waitcnt lgkmcnt(0)
	s_setprio 1
	s_barrier
	v_mfma_f32_16x16x32_bf16 v[122:125], v[130:133], v[170:173], v[122:125]
	v_mfma_f32_16x16x32_bf16 v[122:125], v[134:137], v[174:177], v[122:125]
	v_mfma_f32_16x16x32_bf16 v[126:129], v[146:149], v[170:173], v[126:129]
	v_mfma_f32_16x16x32_bf16 v[126:129], v[150:153], v[174:177], v[126:129]
	v_mfma_f32_16x16x32_bf16 v[110:113], v[130:133], v[178:181], v[110:113]
	v_mfma_f32_16x16x32_bf16 v[110:113], v[134:137], v[182:185], v[110:113]
	v_mfma_f32_16x16x32_bf16 v[106:109], v[146:149], v[178:181], v[106:109]
	v_mfma_f32_16x16x32_bf16 v[106:109], v[150:153], v[182:185], v[106:109]
	v_mfma_f32_16x16x32_bf16 v[94:97], v[130:133], v[186:189], v[94:97]
	v_mfma_f32_16x16x32_bf16 v[94:97], v[134:137], v[190:193], v[94:97]
	v_mfma_f32_16x16x32_bf16 v[90:93], v[146:149], v[186:189], v[90:93]
	v_mfma_f32_16x16x32_bf16 v[90:93], v[150:153], v[190:193], v[90:93]
	v_mfma_f32_16x16x32_bf16 v[78:81], v[130:133], v[198:201], v[78:81]
	v_mfma_f32_16x16x32_bf16 v[78:81], v[134:137], v[202:205], v[78:81]
	v_mfma_f32_16x16x32_bf16 v[74:77], v[146:149], v[198:201], v[74:77]
	v_mfma_f32_16x16x32_bf16 v[74:77], v[150:153], v[202:205], v[74:77]
	v_mfma_f32_16x16x32_bf16 v[114:117], v[154:157], v[170:173], v[114:117]
	v_mfma_f32_16x16x32_bf16 v[114:117], v[158:161], v[174:177], v[114:117]
	v_mfma_f32_16x16x32_bf16 v[118:121], v[162:165], v[170:173], v[118:121]
	v_mfma_f32_16x16x32_bf16 v[118:121], v[166:169], v[174:177], v[118:121]
	v_mfma_f32_16x16x32_bf16 v[98:101], v[154:157], v[178:181], v[98:101]
	v_mfma_f32_16x16x32_bf16 v[98:101], v[158:161], v[182:185], v[98:101]
	v_mfma_f32_16x16x32_bf16 v[102:105], v[162:165], v[178:181], v[102:105]
	v_mfma_f32_16x16x32_bf16 v[102:105], v[166:169], v[182:185], v[102:105]
	v_mfma_f32_16x16x32_bf16 v[82:85], v[154:157], v[186:189], v[82:85]
	v_mfma_f32_16x16x32_bf16 v[82:85], v[158:161], v[190:193], v[82:85]
	v_mfma_f32_16x16x32_bf16 v[86:89], v[162:165], v[186:189], v[86:89]
	v_mfma_f32_16x16x32_bf16 v[86:89], v[166:169], v[190:193], v[86:89]
	v_mfma_f32_16x16x32_bf16 v[66:69], v[154:157], v[198:201], v[66:69]
	v_mfma_f32_16x16x32_bf16 v[66:69], v[158:161], v[202:205], v[66:69]
	s_setprio 2
	s_barrier
	v_mfma_f32_16x16x32_bf16 v[70:73], v[162:165], v[198:201], v[70:73]
	v_mfma_f32_16x16x32_bf16 v[70:73], v[166:169], v[202:205], v[70:73]
	s_setprio 0
	s_nop 0
	ds_read_b128 v[170:173], v143 offset:16384
	ds_read_b128 v[174:177], v143 offset:17408
	ds_read_b128 v[178:181], v143 offset:18432
	ds_read_b128 v[182:185], v143 offset:19456
	ds_read_b128 v[186:189], v143 offset:20480
	ds_read_b128 v[190:193], v143 offset:21504
	ds_read_b128 v[198:201], v143 offset:22528
	ds_read_b128 v[202:205], v143 offset:23552
	s_mov_b32 m0, s55
	s_nop 0
	global_load_lds_dwordx4 v195, s[30:31]
	s_add_u32 m0, s55, 0x2000
	s_nop 0
	global_load_lds_dwordx4 v212, s[30:31]
	s_add_u32 s26, s30, 0x4000
	s_addc_u32 s27, s31, 0
	s_mov_b32 m0, s62
	s_nop 0
	global_load_lds_dwordx4 v195, s[26:27]
	s_add_u32 m0, s62, 0x2000
	s_nop 0
	global_load_lds_dwordx4 v212, s[26:27]
	s_nop 0
	s_mov_b32 m0, s54
	s_nop 0
	global_load_lds_dwordx4 v195, s[48:49]
	s_add_u32 m0, s54, 0x2000
	s_nop 0
	global_load_lds_dwordx4 v212, s[48:49]
	s_waitcnt vmcnt(8)
	s_waitcnt lgkmcnt(0)
	s_setprio 1
	s_barrier
	v_mfma_f32_16x16x32_bf16 v[62:65], v[130:133], v[170:173], v[62:65]
	v_mfma_f32_16x16x32_bf16 v[62:65], v[134:137], v[174:177], v[62:65]
	v_mfma_f32_16x16x32_bf16 v[58:61], v[146:149], v[170:173], v[58:61]
	v_mfma_f32_16x16x32_bf16 v[58:61], v[150:153], v[174:177], v[58:61]
	v_mfma_f32_16x16x32_bf16 v[46:49], v[130:133], v[178:181], v[46:49]
	v_mfma_f32_16x16x32_bf16 v[46:49], v[134:137], v[182:185], v[46:49]
	v_mfma_f32_16x16x32_bf16 v[42:45], v[146:149], v[178:181], v[42:45]
	v_mfma_f32_16x16x32_bf16 v[42:45], v[150:153], v[182:185], v[42:45]
	v_mfma_f32_16x16x32_bf16 v[30:33], v[130:133], v[186:189], v[30:33]
	v_mfma_f32_16x16x32_bf16 v[30:33], v[134:137], v[190:193], v[30:33]
	v_mfma_f32_16x16x32_bf16 v[26:29], v[146:149], v[186:189], v[26:29]
	v_mfma_f32_16x16x32_bf16 v[26:29], v[150:153], v[190:193], v[26:29]
	v_mfma_f32_16x16x32_bf16 v[14:17], v[130:133], v[198:201], v[14:17]
	v_mfma_f32_16x16x32_bf16 v[14:17], v[134:137], v[202:205], v[14:17]
	v_mfma_f32_16x16x32_bf16 v[10:13], v[146:149], v[198:201], v[10:13]
	v_mfma_f32_16x16x32_bf16 v[10:13], v[150:153], v[202:205], v[10:13]
	v_mfma_f32_16x16x32_bf16 v[50:53], v[154:157], v[170:173], v[50:53]
	v_mfma_f32_16x16x32_bf16 v[50:53], v[158:161], v[174:177], v[50:53]
	v_mfma_f32_16x16x32_bf16 v[54:57], v[162:165], v[170:173], v[54:57]
	v_mfma_f32_16x16x32_bf16 v[54:57], v[166:169], v[174:177], v[54:57]
	v_mfma_f32_16x16x32_bf16 v[34:37], v[154:157], v[178:181], v[34:37]
	v_mfma_f32_16x16x32_bf16 v[34:37], v[158:161], v[182:185], v[34:37]
	v_mfma_f32_16x16x32_bf16 v[38:41], v[162:165], v[178:181], v[38:41]
	v_mfma_f32_16x16x32_bf16 v[38:41], v[166:169], v[182:185], v[38:41]
	v_mfma_f32_16x16x32_bf16 v[18:21], v[154:157], v[186:189], v[18:21]
	v_mfma_f32_16x16x32_bf16 v[18:21], v[158:161], v[190:193], v[18:21]
	v_mfma_f32_16x16x32_bf16 v[22:25], v[162:165], v[186:189], v[22:25]
	v_mfma_f32_16x16x32_bf16 v[22:25], v[166:169], v[190:193], v[22:25]
	v_mfma_f32_16x16x32_bf16 v[2:5], v[154:157], v[198:201], v[2:5]
	v_mfma_f32_16x16x32_bf16 v[2:5], v[158:161], v[202:205], v[2:5]
	s_setprio 2
	s_barrier
	v_mfma_f32_16x16x32_bf16 v[6:9], v[162:165], v[198:201], v[6:9]
	v_mfma_f32_16x16x32_bf16 v[6:9], v[166:169], v[202:205], v[6:9]
	s_setprio 0
	s_nop 0
	ds_read_b128 v[130:133], v144
	ds_read_b128 v[134:137], v144 offset:1024
	ds_read_b128 v[146:149], v144 offset:2048
	ds_read_b128 v[150:153], v144 offset:3072
	ds_read_b128 v[154:157], v145
	ds_read_b128 v[158:161], v145 offset:1024
	ds_read_b128 v[162:165], v145 offset:2048
	ds_read_b128 v[166:169], v145 offset:3072
	ds_read_b128 v[170:173], v143 offset:32768
	ds_read_b128 v[174:177], v143 offset:33792
	ds_read_b128 v[178:181], v143 offset:34816
	ds_read_b128 v[182:185], v143 offset:35840
	ds_read_b128 v[186:189], v143 offset:36864
	ds_read_b128 v[190:193], v143 offset:37888
	ds_read_b128 v[198:201], v143 offset:38912
	ds_read_b128 v[202:205], v143 offset:39936
	s_add_u32 s26, s48, 0x4000
	s_addc_u32 s27, s49, 0
	s_mov_b32 m0, s63
	s_nop 0
	global_load_lds_dwordx4 v195, s[26:27]
	s_add_u32 m0, s63, 0x2000
	s_nop 0
	global_load_lds_dwordx4 v212, s[26:27]
	s_waitcnt vmcnt(8)
	s_waitcnt lgkmcnt(0)
	s_setprio 1
	s_barrier
	v_mfma_f32_16x16x32_bf16 v[122:125], v[130:133], v[170:173], v[122:125]
	v_mfma_f32_16x16x32_bf16 v[122:125], v[134:137], v[174:177], v[122:125]
	v_mfma_f32_16x16x32_bf16 v[126:129], v[146:149], v[170:173], v[126:129]
	v_mfma_f32_16x16x32_bf16 v[126:129], v[150:153], v[174:177], v[126:129]
	v_mfma_f32_16x16x32_bf16 v[110:113], v[130:133], v[178:181], v[110:113]
	v_mfma_f32_16x16x32_bf16 v[110:113], v[134:137], v[182:185], v[110:113]
	v_mfma_f32_16x16x32_bf16 v[106:109], v[146:149], v[178:181], v[106:109]
	v_mfma_f32_16x16x32_bf16 v[106:109], v[150:153], v[182:185], v[106:109]
	v_mfma_f32_16x16x32_bf16 v[94:97], v[130:133], v[186:189], v[94:97]
	v_mfma_f32_16x16x32_bf16 v[94:97], v[134:137], v[190:193], v[94:97]
	v_mfma_f32_16x16x32_bf16 v[90:93], v[146:149], v[186:189], v[90:93]
	v_mfma_f32_16x16x32_bf16 v[90:93], v[150:153], v[190:193], v[90:93]
	v_mfma_f32_16x16x32_bf16 v[78:81], v[130:133], v[198:201], v[78:81]
	v_mfma_f32_16x16x32_bf16 v[78:81], v[134:137], v[202:205], v[78:81]
	v_mfma_f32_16x16x32_bf16 v[74:77], v[146:149], v[198:201], v[74:77]
	v_mfma_f32_16x16x32_bf16 v[74:77], v[150:153], v[202:205], v[74:77]
	v_mfma_f32_16x16x32_bf16 v[114:117], v[154:157], v[170:173], v[114:117]
	v_mfma_f32_16x16x32_bf16 v[114:117], v[158:161], v[174:177], v[114:117]
	v_mfma_f32_16x16x32_bf16 v[118:121], v[162:165], v[170:173], v[118:121]
	v_mfma_f32_16x16x32_bf16 v[118:121], v[166:169], v[174:177], v[118:121]
	v_mfma_f32_16x16x32_bf16 v[98:101], v[154:157], v[178:181], v[98:101]
	v_mfma_f32_16x16x32_bf16 v[98:101], v[158:161], v[182:185], v[98:101]
	v_mfma_f32_16x16x32_bf16 v[102:105], v[162:165], v[178:181], v[102:105]
	v_mfma_f32_16x16x32_bf16 v[102:105], v[166:169], v[182:185], v[102:105]
	v_mfma_f32_16x16x32_bf16 v[82:85], v[154:157], v[186:189], v[82:85]
	v_mfma_f32_16x16x32_bf16 v[82:85], v[158:161], v[190:193], v[82:85]
	v_mfma_f32_16x16x32_bf16 v[86:89], v[162:165], v[186:189], v[86:89]
	v_mfma_f32_16x16x32_bf16 v[86:89], v[166:169], v[190:193], v[86:89]
	v_mfma_f32_16x16x32_bf16 v[66:69], v[154:157], v[198:201], v[66:69]
	v_mfma_f32_16x16x32_bf16 v[66:69], v[158:161], v[202:205], v[66:69]
	s_setprio 2
	s_barrier
	v_mfma_f32_16x16x32_bf16 v[70:73], v[162:165], v[198:201], v[70:73]
	v_mfma_f32_16x16x32_bf16 v[70:73], v[166:169], v[202:205], v[70:73]
	s_setprio 0
	s_nop 0
	ds_read_b128 v[170:173], v143 offset:49152
	ds_read_b128 v[174:177], v143 offset:50176
	ds_read_b128 v[178:181], v143 offset:51200
	ds_read_b128 v[182:185], v143 offset:52224
	ds_read_b128 v[186:189], v143 offset:53248
	ds_read_b128 v[190:193], v143 offset:54272
	ds_read_b128 v[198:201], v143 offset:55296
	ds_read_b128 v[202:205], v143 offset:56320
	s_mov_b32 m0, s69
	s_nop 0
	global_load_lds_dwordx4 v195, s[38:39]
	s_add_u32 m0, s69, 0x2000
	s_nop 0
	global_load_lds_dwordx4 v212, s[38:39]
	s_add_u32 s26, s30, 0xc000
	s_addc_u32 s27, s31, 0
	s_mov_b32 m0, s71
	s_nop 0
	global_load_lds_dwordx4 v195, s[26:27]
	s_add_u32 m0, s71, 0x2000
	s_nop 0
	global_load_lds_dwordx4 v212, s[26:27]
	s_nop 0
	s_mov_b32 m0, s70
	s_nop 0
	global_load_lds_dwordx4 v195, s[28:29]
	s_add_u32 m0, s70, 0x2000
	s_nop 0
	global_load_lds_dwordx4 v212, s[28:29]
	s_waitcnt vmcnt(8)
	s_waitcnt lgkmcnt(0)
	s_setprio 1
	s_barrier
	v_mfma_f32_16x16x32_bf16 v[62:65], v[130:133], v[170:173], v[62:65]
	v_mfma_f32_16x16x32_bf16 v[62:65], v[134:137], v[174:177], v[62:65]
	v_mfma_f32_16x16x32_bf16 v[58:61], v[146:149], v[170:173], v[58:61]
	v_mfma_f32_16x16x32_bf16 v[58:61], v[150:153], v[174:177], v[58:61]
	v_mfma_f32_16x16x32_bf16 v[46:49], v[130:133], v[178:181], v[46:49]
	v_mfma_f32_16x16x32_bf16 v[46:49], v[134:137], v[182:185], v[46:49]
	v_mfma_f32_16x16x32_bf16 v[42:45], v[146:149], v[178:181], v[42:45]
	v_mfma_f32_16x16x32_bf16 v[42:45], v[150:153], v[182:185], v[42:45]
	v_mfma_f32_16x16x32_bf16 v[30:33], v[130:133], v[186:189], v[30:33]
	v_mfma_f32_16x16x32_bf16 v[30:33], v[134:137], v[190:193], v[30:33]
	v_mfma_f32_16x16x32_bf16 v[26:29], v[146:149], v[186:189], v[26:29]
	v_mfma_f32_16x16x32_bf16 v[26:29], v[150:153], v[190:193], v[26:29]
	v_mfma_f32_16x16x32_bf16 v[14:17], v[130:133], v[198:201], v[14:17]
	v_mfma_f32_16x16x32_bf16 v[14:17], v[134:137], v[202:205], v[14:17]
	v_mfma_f32_16x16x32_bf16 v[10:13], v[146:149], v[198:201], v[10:13]
	v_mfma_f32_16x16x32_bf16 v[10:13], v[150:153], v[202:205], v[10:13]
	v_mfma_f32_16x16x32_bf16 v[50:53], v[154:157], v[170:173], v[50:53]
	v_mfma_f32_16x16x32_bf16 v[50:53], v[158:161], v[174:177], v[50:53]
	v_mfma_f32_16x16x32_bf16 v[54:57], v[162:165], v[170:173], v[54:57]
	v_mfma_f32_16x16x32_bf16 v[54:57], v[166:169], v[174:177], v[54:57]
	v_mfma_f32_16x16x32_bf16 v[34:37], v[154:157], v[178:181], v[34:37]
	v_mfma_f32_16x16x32_bf16 v[34:37], v[158:161], v[182:185], v[34:37]
	v_mfma_f32_16x16x32_bf16 v[38:41], v[162:165], v[178:181], v[38:41]
	v_mfma_f32_16x16x32_bf16 v[38:41], v[166:169], v[182:185], v[38:41]
	v_mfma_f32_16x16x32_bf16 v[18:21], v[154:157], v[186:189], v[18:21]
	v_mfma_f32_16x16x32_bf16 v[18:21], v[158:161], v[190:193], v[18:21]
	v_mfma_f32_16x16x32_bf16 v[22:25], v[162:165], v[186:189], v[22:25]
	v_mfma_f32_16x16x32_bf16 v[22:25], v[166:169], v[190:193], v[22:25]
	v_mfma_f32_16x16x32_bf16 v[2:5], v[154:157], v[198:201], v[2:5]
	v_mfma_f32_16x16x32_bf16 v[2:5], v[158:161], v[202:205], v[2:5]
	s_setprio 2
	s_barrier
	v_mfma_f32_16x16x32_bf16 v[6:9], v[162:165], v[198:201], v[6:9]
	v_mfma_f32_16x16x32_bf16 v[6:9], v[166:169], v[202:205], v[6:9]
	s_setprio 0
	s_nop 0
	s_add_i32 s77, s77, 2
	s_add_u32 s75, s75, 0x10000
	s_addc_u32 s76, s76, 0
	s_cmp_gt_u32 s77, 13
	s_mov_b64 s[26:27], s[24:25]
	s_cbranch_scc0 .LBB0_519
	s_and_b64 vcc, exec, s[10:11]
	s_cbranch_vccz .LBB0_522
	s_barrier
	s_setprio 1

.LBB0_635:
	s_add_u32 s28, s24, 0x10000
	s_addc_u32 s29, s25, 0
	s_and_b64 s[24:25], s[22:23], exec
	s_cselect_b32 s25, s29, s15
	s_cselect_b32 s24, s28, s33
	s_add_u32 s3, s52, s3
	s_addc_u32 s28, s53, 0
	s_add_u32 s3, s3, 0x10000
	s_waitcnt vmcnt(8)
	s_addc_u32 s28, s28, 0
	s_waitcnt lgkmcnt(0)
	s_and_b64 s[22:23], s[22:23], exec
	s_cselect_b32 s23, s28, s13
	s_cselect_b32 s22, s3, s70
	s_setprio 1
	s_barrier
	v_mfma_f32_16x16x32_bf16 v[126:129], v[146:149], v[186:189], v[126:129]
	v_mfma_f32_16x16x32_bf16 v[126:129], v[150:153], v[190:193], v[126:129]
	v_mfma_f32_16x16x32_bf16 v[122:125], v[154:157], v[186:189], v[122:125]
	v_mfma_f32_16x16x32_bf16 v[122:125], v[158:161], v[190:193], v[122:125]
	v_mfma_f32_16x16x32_bf16 v[118:121], v[146:149], v[178:181], v[118:121]
	v_mfma_f32_16x16x32_bf16 v[118:121], v[150:153], v[182:185], v[118:121]
	v_mfma_f32_16x16x32_bf16 v[114:117], v[154:157], v[178:181], v[114:117]
	v_mfma_f32_16x16x32_bf16 v[114:117], v[158:161], v[182:185], v[114:117]
	v_mfma_f32_16x16x32_bf16 v[110:113], v[146:149], v[170:173], v[110:113]
	v_mfma_f32_16x16x32_bf16 v[110:113], v[150:153], v[174:177], v[110:113]
	v_mfma_f32_16x16x32_bf16 v[106:109], v[154:157], v[170:173], v[106:109]
	v_mfma_f32_16x16x32_bf16 v[106:109], v[158:161], v[174:177], v[106:109]
	v_mfma_f32_16x16x32_bf16 v[102:105], v[146:149], v[162:165], v[102:105]
	v_mfma_f32_16x16x32_bf16 v[102:105], v[150:153], v[166:169], v[102:105]
	v_mfma_f32_16x16x32_bf16 v[98:101], v[154:157], v[162:165], v[98:101]
	v_mfma_f32_16x16x32_bf16 v[98:101], v[158:161], v[166:169], v[98:101]
	v_mfma_f32_16x16x32_bf16 v[94:97], v[130:133], v[186:189], v[94:97]
	v_mfma_f32_16x16x32_bf16 v[94:97], v[134:137], v[190:193], v[94:97]
	v_mfma_f32_16x16x32_bf16 v[90:93], v[138:141], v[186:189], v[90:93]
	v_mfma_f32_16x16x32_bf16 v[90:93], v[142:145], v[190:193], v[90:93]
	v_mfma_f32_16x16x32_bf16 v[86:89], v[130:133], v[178:181], v[86:89]
	v_mfma_f32_16x16x32_bf16 v[86:89], v[134:137], v[182:185], v[86:89]
	v_mfma_f32_16x16x32_bf16 v[82:85], v[138:141], v[178:181], v[82:85]
	v_mfma_f32_16x16x32_bf16 v[82:85], v[142:145], v[182:185], v[82:85]
	v_mfma_f32_16x16x32_bf16 v[78:81], v[130:133], v[170:173], v[78:81]
	v_mfma_f32_16x16x32_bf16 v[78:81], v[134:137], v[174:177], v[78:81]
	v_mfma_f32_16x16x32_bf16 v[74:77], v[138:141], v[170:173], v[74:77]
	v_mfma_f32_16x16x32_bf16 v[74:77], v[142:145], v[174:177], v[74:77]
	v_mfma_f32_16x16x32_bf16 v[70:73], v[130:133], v[162:165], v[70:73]
	v_mfma_f32_16x16x32_bf16 v[70:73], v[134:137], v[166:169], v[70:73]
	s_setprio 2
	s_barrier
	v_mfma_f32_16x16x32_bf16 v[66:69], v[138:141], v[162:165], v[66:69]
	v_mfma_f32_16x16x32_bf16 v[66:69], v[142:145], v[166:169], v[66:69]
	s_setprio 0
	s_nop 0
	ds_read_b128 v[186:189], v219 offset:16384
	ds_read_b128 v[190:193], v219 offset:17408
	ds_read_b128 v[178:181], v219 offset:18432
	ds_read_b128 v[182:185], v219 offset:19456
	ds_read_b128 v[170:173], v219 offset:20480
	ds_read_b128 v[174:177], v219 offset:21504
	ds_read_b128 v[162:165], v219 offset:22528
	ds_read_b128 v[166:169], v219 offset:23552
	s_mov_b32 m0, s89
	s_nop 0
	global_load_lds_dwordx4 v195, s[22:23]
	s_add_u32 m0, s89, 0x2000
	s_nop 0
	global_load_lds_dwordx4 v213, s[22:23]
	s_add_u32 s28, s22, 0x4000
	s_addc_u32 s29, s23, 0
	s_mov_b32 m0, s54
	s_nop 0
	global_load_lds_dwordx4 v195, s[28:29]
	s_add_u32 m0, s54, 0x2000
	s_nop 0
	global_load_lds_dwordx4 v213, s[28:29]
	s_andn2_b64 vcc, exec, s[26:27]
	s_mov_b32 m0, s39
	s_nop 0
	global_load_lds_dwordx4 v195, s[24:25]
	s_add_u32 m0, s39, 0x2000
	s_nop 0
	global_load_lds_dwordx4 v213, s[24:25]
	s_cbranch_vccnz .LBB0_637
	v_mov_b32_e32 v2, 0
	v_mov_b32_e32 v3, v2
	v_mov_b32_e32 v4, v2
	v_mov_b32_e32 v5, v2
	v_mov_b32_e32 v6, v2
	v_mov_b32_e32 v7, v2
	v_mov_b32_e32 v8, v2
	v_mov_b32_e32 v9, v2
	v_mov_b32_e32 v10, v2
	v_mov_b32_e32 v11, v2
	v_mov_b32_e32 v12, v2
	v_mov_b32_e32 v13, v2
	v_mov_b32_e32 v14, v2
	v_mov_b32_e32 v15, v2
	v_mov_b32_e32 v16, v2
	v_mov_b32_e32 v17, v2
	v_mov_b32_e32 v18, v2
	v_mov_b32_e32 v19, v2
	v_mov_b32_e32 v20, v2
	v_mov_b32_e32 v21, v2
	v_mov_b32_e32 v22, v2
	v_mov_b32_e32 v23, v2
	v_mov_b32_e32 v24, v2
	v_mov_b32_e32 v25, v2
	v_mov_b32_e32 v26, v2
	v_mov_b32_e32 v27, v2
	v_mov_b32_e32 v28, v2
	v_mov_b32_e32 v29, v2
	v_mov_b32_e32 v30, v2
	v_mov_b32_e32 v31, v2
	v_mov_b32_e32 v32, v2
	v_mov_b32_e32 v33, v2
	v_mov_b32_e32 v34, v2
	v_mov_b32_e32 v35, v2
	v_mov_b32_e32 v36, v2
	v_mov_b32_e32 v37, v2
	v_mov_b32_e32 v38, v2
	v_mov_b32_e32 v39, v2
	v_mov_b32_e32 v40, v2
	v_mov_b32_e32 v41, v2
	v_mov_b32_e32 v42, v2
	v_mov_b32_e32 v43, v2
	v_mov_b32_e32 v44, v2
	v_mov_b32_e32 v45, v2
	v_mov_b32_e32 v46, v2
	v_mov_b32_e32 v47, v2
	v_mov_b32_e32 v48, v2
	v_mov_b32_e32 v49, v2
	v_mov_b32_e32 v50, v2
	v_mov_b32_e32 v51, v2
	v_mov_b32_e32 v52, v2
	v_mov_b32_e32 v53, v2
	v_mov_b32_e32 v54, v2
	v_mov_b32_e32 v55, v2
	v_mov_b32_e32 v56, v2
	v_mov_b32_e32 v57, v2
	v_mov_b32_e32 v58, v2
	v_mov_b32_e32 v59, v2
	v_mov_b32_e32 v60, v2
	v_mov_b32_e32 v61, v2
	v_mov_b32_e32 v62, v2
	v_mov_b32_e32 v63, v2
	v_mov_b32_e32 v64, v2
	v_mov_b32_e32 v65, v2
.LBB0_637:
	s_waitcnt vmcnt(8)
	s_add_u32 s26, s24, 0x8000
	s_waitcnt lgkmcnt(0)
	s_addc_u32 s27, s25, 0
	s_add_u32 s28, s22, 0x8000
	s_addc_u32 s29, s23, 0
	s_setprio 1
	s_barrier
	v_mfma_f32_16x16x32_bf16 v[62:65], v[146:149], v[186:189], v[62:65]
	v_mfma_f32_16x16x32_bf16 v[62:65], v[150:153], v[190:193], v[62:65]
	v_mfma_f32_16x16x32_bf16 v[58:61], v[154:157], v[186:189], v[58:61]
	v_mfma_f32_16x16x32_bf16 v[58:61], v[158:161], v[190:193], v[58:61]
	v_mfma_f32_16x16x32_bf16 v[54:57], v[146:149], v[178:181], v[54:57]
	v_mfma_f32_16x16x32_bf16 v[54:57], v[150:153], v[182:185], v[54:57]
	v_mfma_f32_16x16x32_bf16 v[50:53], v[154:157], v[178:181], v[50:53]
	v_mfma_f32_16x16x32_bf16 v[50:53], v[158:161], v[182:185], v[50:53]
	v_mfma_f32_16x16x32_bf16 v[46:49], v[146:149], v[170:173], v[46:49]
	v_mfma_f32_16x16x32_bf16 v[46:49], v[150:153], v[174:177], v[46:49]
	v_mfma_f32_16x16x32_bf16 v[42:45], v[154:157], v[170:173], v[42:45]
	v_mfma_f32_16x16x32_bf16 v[42:45], v[158:161], v[174:177], v[42:45]
	v_mfma_f32_16x16x32_bf16 v[38:41], v[146:149], v[162:165], v[38:41]
	v_mfma_f32_16x16x32_bf16 v[38:41], v[150:153], v[166:169], v[38:41]
	v_mfma_f32_16x16x32_bf16 v[34:37], v[154:157], v[162:165], v[34:37]
	v_mfma_f32_16x16x32_bf16 v[34:37], v[158:161], v[166:169], v[34:37]
	v_mfma_f32_16x16x32_bf16 v[30:33], v[130:133], v[186:189], v[30:33]
	v_mfma_f32_16x16x32_bf16 v[30:33], v[134:137], v[190:193], v[30:33]
	v_mfma_f32_16x16x32_bf16 v[26:29], v[138:141], v[186:189], v[26:29]
	v_mfma_f32_16x16x32_bf16 v[26:29], v[142:145], v[190:193], v[26:29]
	v_mfma_f32_16x16x32_bf16 v[22:25], v[130:133], v[178:181], v[22:25]
	v_mfma_f32_16x16x32_bf16 v[22:25], v[134:137], v[182:185], v[22:25]
	v_mfma_f32_16x16x32_bf16 v[18:21], v[138:141], v[178:181], v[18:21]
	v_mfma_f32_16x16x32_bf16 v[18:21], v[142:145], v[182:185], v[18:21]
	v_mfma_f32_16x16x32_bf16 v[14:17], v[130:133], v[170:173], v[14:17]
	v_mfma_f32_16x16x32_bf16 v[14:17], v[134:137], v[174:177], v[14:17]
	v_mfma_f32_16x16x32_bf16 v[10:13], v[138:141], v[170:173], v[10:13]
	v_mfma_f32_16x16x32_bf16 v[10:13], v[142:145], v[174:177], v[10:13]
	v_mfma_f32_16x16x32_bf16 v[6:9], v[130:133], v[162:165], v[6:9]
	v_mfma_f32_16x16x32_bf16 v[6:9], v[134:137], v[166:169], v[6:9]
	s_setprio 2
	s_barrier
	v_mfma_f32_16x16x32_bf16 v[2:5], v[138:141], v[162:165], v[2:5]
	v_mfma_f32_16x16x32_bf16 v[2:5], v[142:145], v[166:169], v[2:5]
	s_setprio 0
	s_nop 0
	v_add_u32_e32 v142, 0x18000, v218
	v_add_u32_e32 v158, 0x1c000, v218
	ds_read_b128 v[130:133], v142
	ds_read_b128 v[134:137], v142 offset:1024
	ds_read_b128 v[138:141], v142 offset:2048
	ds_read_b128 v[142:145], v142 offset:3072
	ds_read_b128 v[146:149], v158
	ds_read_b128 v[150:153], v158 offset:1024
	ds_read_b128 v[154:157], v158 offset:2048
	ds_read_b128 v[158:161], v158 offset:3072
	ds_read_b128 v[162:165], v219 offset:32768
	ds_read_b128 v[166:169], v219 offset:33792
	ds_read_b128 v[170:173], v219 offset:34816
	ds_read_b128 v[174:177], v219 offset:35840
	ds_read_b128 v[178:181], v219 offset:36864
	ds_read_b128 v[182:185], v219 offset:37888
	ds_read_b128 v[186:189], v219 offset:38912
	ds_read_b128 v[190:193], v219 offset:39936
	s_add_u32 s24, s24, 0x4000
	s_addc_u32 s25, s25, 0
	s_mov_b32 m0, s55
	s_nop 0
	global_load_lds_dwordx4 v195, s[24:25]
	s_add_u32 m0, s55, 0x2000
	s_nop 0
	global_load_lds_dwordx4 v213, s[24:25]
	s_waitcnt vmcnt(8)
	s_waitcnt lgkmcnt(0)
	s_setprio 1
	s_barrier
	v_mfma_f32_16x16x32_bf16 v[126:129], v[130:133], v[162:165], v[126:129]
	v_mfma_f32_16x16x32_bf16 v[126:129], v[134:137], v[166:169], v[126:129]
	v_mfma_f32_16x16x32_bf16 v[122:125], v[138:141], v[162:165], v[122:125]
	v_mfma_f32_16x16x32_bf16 v[122:125], v[142:145], v[166:169], v[122:125]
	v_mfma_f32_16x16x32_bf16 v[118:121], v[130:133], v[170:173], v[118:121]
	v_mfma_f32_16x16x32_bf16 v[118:121], v[134:137], v[174:177], v[118:121]
	v_mfma_f32_16x16x32_bf16 v[114:117], v[138:141], v[170:173], v[114:117]
	v_mfma_f32_16x16x32_bf16 v[114:117], v[142:145], v[174:177], v[114:117]
	v_mfma_f32_16x16x32_bf16 v[110:113], v[130:133], v[178:181], v[110:113]
	v_mfma_f32_16x16x32_bf16 v[110:113], v[134:137], v[182:185], v[110:113]
	v_mfma_f32_16x16x32_bf16 v[106:109], v[138:141], v[178:181], v[106:109]
	v_mfma_f32_16x16x32_bf16 v[106:109], v[142:145], v[182:185], v[106:109]
	v_mfma_f32_16x16x32_bf16 v[102:105], v[130:133], v[186:189], v[102:105]
	v_mfma_f32_16x16x32_bf16 v[102:105], v[134:137], v[190:193], v[102:105]
	v_mfma_f32_16x16x32_bf16 v[98:101], v[138:141], v[186:189], v[98:101]
	v_mfma_f32_16x16x32_bf16 v[98:101], v[142:145], v[190:193], v[98:101]
	v_mfma_f32_16x16x32_bf16 v[94:97], v[146:149], v[162:165], v[94:97]
	v_mfma_f32_16x16x32_bf16 v[94:97], v[150:153], v[166:169], v[94:97]
	v_mfma_f32_16x16x32_bf16 v[90:93], v[154:157], v[162:165], v[90:93]
	v_mfma_f32_16x16x32_bf16 v[90:93], v[158:161], v[166:169], v[90:93]
	v_mfma_f32_16x16x32_bf16 v[86:89], v[146:149], v[170:173], v[86:89]
	v_mfma_f32_16x16x32_bf16 v[86:89], v[150:153], v[174:177], v[86:89]
	v_mfma_f32_16x16x32_bf16 v[82:85], v[154:157], v[170:173], v[82:85]
	v_mfma_f32_16x16x32_bf16 v[82:85], v[158:161], v[174:177], v[82:85]
	v_mfma_f32_16x16x32_bf16 v[78:81], v[146:149], v[178:181], v[78:81]
	v_mfma_f32_16x16x32_bf16 v[78:81], v[150:153], v[182:185], v[78:81]
	v_mfma_f32_16x16x32_bf16 v[74:77], v[154:157], v[178:181], v[74:77]
	v_mfma_f32_16x16x32_bf16 v[74:77], v[158:161], v[182:185], v[74:77]
	v_mfma_f32_16x16x32_bf16 v[70:73], v[146:149], v[186:189], v[70:73]
	v_mfma_f32_16x16x32_bf16 v[70:73], v[150:153], v[190:193], v[70:73]
	s_setprio 2
	s_barrier
	v_mfma_f32_16x16x32_bf16 v[66:69], v[154:157], v[186:189], v[66:69]
	v_mfma_f32_16x16x32_bf16 v[66:69], v[158:161], v[190:193], v[66:69]
	s_setprio 0
	s_nop 0
	ds_read_b128 v[162:165], v219 offset:49152
	ds_read_b128 v[166:169], v219 offset:50176
	ds_read_b128 v[170:173], v219 offset:51200
	ds_read_b128 v[174:177], v219 offset:52224
	ds_read_b128 v[178:181], v219 offset:53248
	ds_read_b128 v[182:185], v219 offset:54272
	ds_read_b128 v[186:189], v219 offset:55296
	ds_read_b128 v[190:193], v219 offset:56320
	s_mov_b32 m0, s83
	s_nop 0
	global_load_lds_dwordx4 v195, s[28:29]
	s_add_u32 m0, s83, 0x2000
	s_nop 0
	global_load_lds_dwordx4 v213, s[28:29]
	s_add_u32 s22, s22, 0xc000
	s_addc_u32 s23, s23, 0
	s_mov_b32 m0, s91
	s_nop 0
	global_load_lds_dwordx4 v195, s[22:23]
	s_add_u32 m0, s91, 0x2000
	s_nop 0
	global_load_lds_dwordx4 v213, s[22:23]
	s_nop 0
	s_mov_b32 m0, s90
	s_nop 0
	global_load_lds_dwordx4 v195, s[26:27]
	s_add_u32 m0, s90, 0x2000
	s_nop 0
	global_load_lds_dwordx4 v213, s[26:27]
	s_waitcnt vmcnt(8)
	s_waitcnt lgkmcnt(0)
	s_setprio 1
	s_barrier
	v_mfma_f32_16x16x32_bf16 v[62:65], v[130:133], v[162:165], v[62:65]
	v_mfma_f32_16x16x32_bf16 v[62:65], v[134:137], v[166:169], v[62:65]
	v_mfma_f32_16x16x32_bf16 v[58:61], v[138:141], v[162:165], v[58:61]
	v_mfma_f32_16x16x32_bf16 v[58:61], v[142:145], v[166:169], v[58:61]
	v_mfma_f32_16x16x32_bf16 v[54:57], v[130:133], v[170:173], v[54:57]
	v_mfma_f32_16x16x32_bf16 v[54:57], v[134:137], v[174:177], v[54:57]
	v_mfma_f32_16x16x32_bf16 v[50:53], v[138:141], v[170:173], v[50:53]
	v_mfma_f32_16x16x32_bf16 v[50:53], v[142:145], v[174:177], v[50:53]
	v_mfma_f32_16x16x32_bf16 v[46:49], v[130:133], v[178:181], v[46:49]
	v_mfma_f32_16x16x32_bf16 v[46:49], v[134:137], v[182:185], v[46:49]
	v_mfma_f32_16x16x32_bf16 v[42:45], v[138:141], v[178:181], v[42:45]
	v_mfma_f32_16x16x32_bf16 v[42:45], v[142:145], v[182:185], v[42:45]
	v_mfma_f32_16x16x32_bf16 v[38:41], v[130:133], v[186:189], v[38:41]
	v_mfma_f32_16x16x32_bf16 v[38:41], v[134:137], v[190:193], v[38:41]
	v_mfma_f32_16x16x32_bf16 v[34:37], v[138:141], v[186:189], v[34:37]
	v_mfma_f32_16x16x32_bf16 v[34:37], v[142:145], v[190:193], v[34:37]
	v_mfma_f32_16x16x32_bf16 v[30:33], v[146:149], v[162:165], v[30:33]
	v_mfma_f32_16x16x32_bf16 v[30:33], v[150:153], v[166:169], v[30:33]
	v_mfma_f32_16x16x32_bf16 v[26:29], v[154:157], v[162:165], v[26:29]
	v_mfma_f32_16x16x32_bf16 v[26:29], v[158:161], v[166:169], v[26:29]
	v_mfma_f32_16x16x32_bf16 v[22:25], v[146:149], v[170:173], v[22:25]
	v_mfma_f32_16x16x32_bf16 v[22:25], v[150:153], v[174:177], v[22:25]
	v_mfma_f32_16x16x32_bf16 v[18:21], v[154:157], v[170:173], v[18:21]
	v_mfma_f32_16x16x32_bf16 v[18:21], v[158:161], v[174:177], v[18:21]
	v_mfma_f32_16x16x32_bf16 v[14:17], v[146:149], v[178:181], v[14:17]
	v_mfma_f32_16x16x32_bf16 v[14:17], v[150:153], v[182:185], v[14:17]
	v_mfma_f32_16x16x32_bf16 v[10:13], v[154:157], v[178:181], v[10:13]
	v_mfma_f32_16x16x32_bf16 v[10:13], v[158:161], v[182:185], v[10:13]
	v_mfma_f32_16x16x32_bf16 v[6:9], v[146:149], v[186:189], v[6:9]
	v_mfma_f32_16x16x32_bf16 v[6:9], v[150:153], v[190:193], v[6:9]
	s_setprio 2
	s_barrier
	v_mfma_f32_16x16x32_bf16 v[2:5], v[154:157], v[186:189], v[2:5]
	v_mfma_f32_16x16x32_bf16 v[2:5], v[158:161], v[190:193], v[2:5]
	s_setprio 0
	s_nop 0
	s_add_i32 s3, s71, 2
	s_cmp_gt_u32 s71, 13
	s_cbranch_scc1 .LBB0_639
	s_mov_b32 s71, s3
	s_branch .LBB0_616

.LBB0_1068:
	s_or_b64 exec, exec, s[62:63]
	s_add_u32 s88, s12, s0
	ds_read_b128 v[132:135], v214
	ds_read_b128 v[136:139], v214 offset:1024
	ds_read_b128 v[140:143], v214 offset:2048
	ds_read_b128 v[144:147], v214 offset:3072
	ds_read_b128 v[154:157], v215
	ds_read_b128 v[158:161], v215 offset:1024
	ds_read_b128 v[162:165], v215 offset:2048
	ds_read_b128 v[166:169], v215 offset:3072
	s_addc_u32 s89, s13, s1
	s_add_u32 s62, s88, 0x20000
	s_addc_u32 s63, s89, 0
	s_add_u32 s64, s94, s0
	s_addc_u32 s65, s96, s1
	s_cmp_eq_u32 s0, 0x60000
	s_cselect_b32 s68, s53, s62
	s_cselect_b32 s69, s33, s63
	s_cselect_b32 s63, s51, s65
	s_cselect_b32 s62, s95, s64
	s_add_u32 s64, s68, 0x8000
	s_addc_u32 s65, s69, 0
	s_add_u32 s66, s62, 0x8000
	s_addc_u32 s67, s63, 0
	ds_read_b128 v[170:173], v216
	ds_read_b128 v[174:177], v216 offset:1024
	ds_read_b128 v[178:181], v216 offset:2048
	ds_read_b128 v[182:185], v216 offset:3072
	ds_read_b128 v[186:189], v216 offset:4096
	ds_read_b128 v[190:193], v216 offset:5120
	ds_read_b128 v[198:201], v216 offset:6144
	ds_read_b128 v[202:205], v216 offset:7168
	s_add_u32 s88, s88, 0x1c000
	s_addc_u32 s89, s89, 0
	s_mov_b32 m0, s79
	s_nop 0
	global_load_lds_dwordx4 v195, s[88:89]
	s_add_u32 m0, s79, 0x2000
	s_nop 0
	global_load_lds_dwordx4 v212, s[88:89]
	s_waitcnt vmcnt(8)
	s_waitcnt lgkmcnt(0)
	s_setprio 1
	s_barrier
	v_mfma_f32_16x16x32_bf16 v[126:129], v[132:135], v[170:173], v[126:129]
	v_mfma_f32_16x16x32_bf16 v[126:129], v[136:139], v[174:177], v[126:129]
	v_mfma_f32_16x16x32_bf16 v[122:125], v[140:143], v[170:173], v[122:125]
	v_mfma_f32_16x16x32_bf16 v[122:125], v[144:147], v[174:177], v[122:125]
	v_mfma_f32_16x16x32_bf16 v[110:113], v[132:135], v[178:181], v[110:113]
	v_mfma_f32_16x16x32_bf16 v[110:113], v[136:139], v[182:185], v[110:113]
	v_mfma_f32_16x16x32_bf16 v[106:109], v[140:143], v[178:181], v[106:109]
	v_mfma_f32_16x16x32_bf16 v[106:109], v[144:147], v[182:185], v[106:109]
	v_mfma_f32_16x16x32_bf16 v[94:97], v[132:135], v[186:189], v[94:97]
	v_mfma_f32_16x16x32_bf16 v[94:97], v[136:139], v[190:193], v[94:97]
	v_mfma_f32_16x16x32_bf16 v[90:93], v[140:143], v[186:189], v[90:93]
	v_mfma_f32_16x16x32_bf16 v[90:93], v[144:147], v[190:193], v[90:93]
	v_mfma_f32_16x16x32_bf16 v[78:81], v[132:135], v[198:201], v[78:81]
	v_mfma_f32_16x16x32_bf16 v[78:81], v[136:139], v[202:205], v[78:81]
	v_mfma_f32_16x16x32_bf16 v[74:77], v[140:143], v[198:201], v[74:77]
	v_mfma_f32_16x16x32_bf16 v[74:77], v[144:147], v[202:205], v[74:77]
	v_mfma_f32_16x16x32_bf16 v[118:121], v[154:157], v[170:173], v[118:121]
	v_mfma_f32_16x16x32_bf16 v[118:121], v[158:161], v[174:177], v[118:121]
	v_mfma_f32_16x16x32_bf16 v[114:117], v[162:165], v[170:173], v[114:117]
	v_mfma_f32_16x16x32_bf16 v[114:117], v[166:169], v[174:177], v[114:117]
	v_mfma_f32_16x16x32_bf16 v[102:105], v[154:157], v[178:181], v[102:105]
	v_mfma_f32_16x16x32_bf16 v[102:105], v[158:161], v[182:185], v[102:105]
	v_mfma_f32_16x16x32_bf16 v[98:101], v[162:165], v[178:181], v[98:101]
	v_mfma_f32_16x16x32_bf16 v[98:101], v[166:169], v[182:185], v[98:101]
	v_mfma_f32_16x16x32_bf16 v[86:89], v[154:157], v[186:189], v[86:89]
	v_mfma_f32_16x16x32_bf16 v[86:89], v[158:161], v[190:193], v[86:89]
	v_mfma_f32_16x16x32_bf16 v[82:85], v[162:165], v[186:189], v[82:85]
	v_mfma_f32_16x16x32_bf16 v[82:85], v[166:169], v[190:193], v[82:85]
	v_mfma_f32_16x16x32_bf16 v[70:73], v[154:157], v[198:201], v[70:73]
	v_mfma_f32_16x16x32_bf16 v[70:73], v[158:161], v[202:205], v[70:73]
	s_setprio 2
	s_barrier
	v_mfma_f32_16x16x32_bf16 v[66:69], v[162:165], v[198:201], v[66:69]
	v_mfma_f32_16x16x32_bf16 v[66:69], v[166:169], v[202:205], v[66:69]
	s_setprio 0
	s_nop 0
	ds_read_b128 v[170:173], v216 offset:16384
	ds_read_b128 v[174:177], v216 offset:17408
	ds_read_b128 v[178:181], v216 offset:18432
	ds_read_b128 v[182:185], v216 offset:19456
	ds_read_b128 v[186:189], v216 offset:20480
	ds_read_b128 v[190:193], v216 offset:21504
	ds_read_b128 v[198:201], v216 offset:22528
	ds_read_b128 v[202:205], v216 offset:23552
	s_mov_b32 m0, s3
	s_nop 0
	global_load_lds_dwordx4 v195, s[62:63]
	s_add_u32 m0, s3, 0x2000
	s_nop 0
	global_load_lds_dwordx4 v212, s[62:63]
	s_add_u32 s88, s62, 0x4000
	s_addc_u32 s89, s63, 0
	s_mov_b32 m0, s71
	s_nop 0
	global_load_lds_dwordx4 v195, s[88:89]
	s_add_u32 m0, s71, 0x2000
	s_nop 0
	global_load_lds_dwordx4 v212, s[88:89]
	s_nop 0
	s_mov_b32 m0, s70
	s_nop 0
	global_load_lds_dwordx4 v195, s[68:69]
	s_add_u32 m0, s70, 0x2000
	s_nop 0
	global_load_lds_dwordx4 v212, s[68:69]
	s_waitcnt vmcnt(8)
	s_waitcnt lgkmcnt(0)
	s_setprio 1
	s_barrier
	v_mfma_f32_16x16x32_bf16 v[62:65], v[132:135], v[170:173], v[62:65]
	v_mfma_f32_16x16x32_bf16 v[62:65], v[136:139], v[174:177], v[62:65]
	v_mfma_f32_16x16x32_bf16 v[58:61], v[140:143], v[170:173], v[58:61]
	v_mfma_f32_16x16x32_bf16 v[58:61], v[144:147], v[174:177], v[58:61]
	v_mfma_f32_16x16x32_bf16 v[46:49], v[132:135], v[178:181], v[46:49]
	v_mfma_f32_16x16x32_bf16 v[46:49], v[136:139], v[182:185], v[46:49]
	v_mfma_f32_16x16x32_bf16 v[42:45], v[140:143], v[178:181], v[42:45]
	v_mfma_f32_16x16x32_bf16 v[42:45], v[144:147], v[182:185], v[42:45]
	v_mfma_f32_16x16x32_bf16 v[30:33], v[132:135], v[186:189], v[30:33]
	v_mfma_f32_16x16x32_bf16 v[30:33], v[136:139], v[190:193], v[30:33]
	v_mfma_f32_16x16x32_bf16 v[26:29], v[140:143], v[186:189], v[26:29]
	v_mfma_f32_16x16x32_bf16 v[26:29], v[144:147], v[190:193], v[26:29]
	v_mfma_f32_16x16x32_bf16 v[14:17], v[132:135], v[198:201], v[14:17]
	v_mfma_f32_16x16x32_bf16 v[14:17], v[136:139], v[202:205], v[14:17]
	v_mfma_f32_16x16x32_bf16 v[10:13], v[140:143], v[198:201], v[10:13]
	v_mfma_f32_16x16x32_bf16 v[10:13], v[144:147], v[202:205], v[10:13]
	v_mfma_f32_16x16x32_bf16 v[54:57], v[154:157], v[170:173], v[54:57]
	v_mfma_f32_16x16x32_bf16 v[54:57], v[158:161], v[174:177], v[54:57]
	v_mfma_f32_16x16x32_bf16 v[50:53], v[162:165], v[170:173], v[50:53]
	v_mfma_f32_16x16x32_bf16 v[50:53], v[166:169], v[174:177], v[50:53]
	v_mfma_f32_16x16x32_bf16 v[38:41], v[154:157], v[178:181], v[38:41]
	v_mfma_f32_16x16x32_bf16 v[38:41], v[158:161], v[182:185], v[38:41]
	v_mfma_f32_16x16x32_bf16 v[34:37], v[162:165], v[178:181], v[34:37]
	v_mfma_f32_16x16x32_bf16 v[34:37], v[166:169], v[182:185], v[34:37]
	v_mfma_f32_16x16x32_bf16 v[22:25], v[154:157], v[186:189], v[22:25]
	v_mfma_f32_16x16x32_bf16 v[22:25], v[158:161], v[190:193], v[22:25]
	v_mfma_f32_16x16x32_bf16 v[18:21], v[162:165], v[186:189], v[18:21]
	v_mfma_f32_16x16x32_bf16 v[18:21], v[166:169], v[190:193], v[18:21]
	v_mfma_f32_16x16x32_bf16 v[6:9], v[154:157], v[198:201], v[6:9]
	v_mfma_f32_16x16x32_bf16 v[6:9], v[158:161], v[202:205], v[6:9]
	s_setprio 2
	s_barrier
	v_mfma_f32_16x16x32_bf16 v[2:5], v[162:165], v[198:201], v[2:5]
	v_mfma_f32_16x16x32_bf16 v[2:5], v[166:169], v[202:205], v[2:5]
	s_setprio 0
	s_nop 0
	ds_read_b128 v[132:135], v217
	ds_read_b128 v[136:139], v217 offset:1024
	ds_read_b128 v[140:143], v217 offset:2048
	ds_read_b128 v[144:147], v217 offset:3072
	ds_read_b128 v[154:157], v218
	ds_read_b128 v[158:161], v218 offset:1024
	ds_read_b128 v[162:165], v218 offset:2048
	ds_read_b128 v[166:169], v218 offset:3072
	ds_read_b128 v[170:173], v216 offset:32768
	ds_read_b128 v[174:177], v216 offset:33792
	ds_read_b128 v[178:181], v216 offset:34816
	ds_read_b128 v[182:185], v216 offset:35840
	ds_read_b128 v[186:189], v216 offset:36864
	ds_read_b128 v[190:193], v216 offset:37888
	ds_read_b128 v[198:201], v216 offset:38912
	ds_read_b128 v[202:205], v216 offset:39936
	s_add_u32 s68, s68, 0x4000
	s_addc_u32 s69, s69, 0
	s_mov_b32 m0, s72
	s_nop 0
	global_load_lds_dwordx4 v195, s[68:69]
	s_add_u32 m0, s72, 0x2000
	s_nop 0
	global_load_lds_dwordx4 v212, s[68:69]
	s_waitcnt vmcnt(8)
	s_waitcnt lgkmcnt(0)
	s_setprio 1
	s_barrier
	v_mfma_f32_16x16x32_bf16 v[126:129], v[132:135], v[170:173], v[126:129]
	v_mfma_f32_16x16x32_bf16 v[126:129], v[136:139], v[174:177], v[126:129]
	v_mfma_f32_16x16x32_bf16 v[122:125], v[140:143], v[170:173], v[122:125]
	v_mfma_f32_16x16x32_bf16 v[122:125], v[144:147], v[174:177], v[122:125]
	v_mfma_f32_16x16x32_bf16 v[110:113], v[132:135], v[178:181], v[110:113]
	v_mfma_f32_16x16x32_bf16 v[110:113], v[136:139], v[182:185], v[110:113]
	v_mfma_f32_16x16x32_bf16 v[106:109], v[140:143], v[178:181], v[106:109]
	v_mfma_f32_16x16x32_bf16 v[106:109], v[144:147], v[182:185], v[106:109]
	v_mfma_f32_16x16x32_bf16 v[94:97], v[132:135], v[186:189], v[94:97]
	v_mfma_f32_16x16x32_bf16 v[94:97], v[136:139], v[190:193], v[94:97]
	v_mfma_f32_16x16x32_bf16 v[90:93], v[140:143], v[186:189], v[90:93]
	v_mfma_f32_16x16x32_bf16 v[90:93], v[144:147], v[190:193], v[90:93]
	v_mfma_f32_16x16x32_bf16 v[78:81], v[132:135], v[198:201], v[78:81]
	v_mfma_f32_16x16x32_bf16 v[78:81], v[136:139], v[202:205], v[78:81]
	v_mfma_f32_16x16x32_bf16 v[74:77], v[140:143], v[198:201], v[74:77]
	v_mfma_f32_16x16x32_bf16 v[74:77], v[144:147], v[202:205], v[74:77]
	v_mfma_f32_16x16x32_bf16 v[118:121], v[154:157], v[170:173], v[118:121]
	v_mfma_f32_16x16x32_bf16 v[118:121], v[158:161], v[174:177], v[118:121]
	v_mfma_f32_16x16x32_bf16 v[114:117], v[162:165], v[170:173], v[114:117]
	v_mfma_f32_16x16x32_bf16 v[114:117], v[166:169], v[174:177], v[114:117]
	v_mfma_f32_16x16x32_bf16 v[102:105], v[154:157], v[178:181], v[102:105]
	v_mfma_f32_16x16x32_bf16 v[102:105], v[158:161], v[182:185], v[102:105]
	v_mfma_f32_16x16x32_bf16 v[98:101], v[162:165], v[178:181], v[98:101]
	v_mfma_f32_16x16x32_bf16 v[98:101], v[166:169], v[182:185], v[98:101]
	v_mfma_f32_16x16x32_bf16 v[86:89], v[154:157], v[186:189], v[86:89]
	v_mfma_f32_16x16x32_bf16 v[86:89], v[158:161], v[190:193], v[86:89]
	v_mfma_f32_16x16x32_bf16 v[82:85], v[162:165], v[186:189], v[82:85]
	v_mfma_f32_16x16x32_bf16 v[82:85], v[166:169], v[190:193], v[82:85]
	v_mfma_f32_16x16x32_bf16 v[70:73], v[154:157], v[198:201], v[70:73]
	v_mfma_f32_16x16x32_bf16 v[70:73], v[158:161], v[202:205], v[70:73]
	s_setprio 2
	s_barrier
	v_mfma_f32_16x16x32_bf16 v[66:69], v[162:165], v[198:201], v[66:69]
	v_mfma_f32_16x16x32_bf16 v[66:69], v[166:169], v[202:205], v[66:69]
	s_setprio 0
	s_nop 0
	ds_read_b128 v[170:173], v216 offset:49152
	ds_read_b128 v[174:177], v216 offset:50176
	ds_read_b128 v[178:181], v216 offset:51200
	ds_read_b128 v[182:185], v216 offset:52224
	ds_read_b128 v[186:189], v216 offset:53248
	ds_read_b128 v[190:193], v216 offset:54272
	ds_read_b128 v[198:201], v216 offset:55296
	ds_read_b128 v[202:205], v216 offset:56320
	s_mov_b32 m0, s76
	s_nop 0
	global_load_lds_dwordx4 v195, s[66:67]
	s_add_u32 m0, s76, 0x2000
	s_nop 0
	global_load_lds_dwordx4 v212, s[66:67]
	s_add_u32 s62, s62, 0xc000
	s_addc_u32 s63, s63, 0
	s_mov_b32 m0, s78
	s_nop 0
	global_load_lds_dwordx4 v195, s[62:63]
	s_add_u32 m0, s78, 0x2000
	s_nop 0
	global_load_lds_dwordx4 v212, s[62:63]
	s_nop 0
	s_mov_b32 m0, s77
	s_nop 0
	global_load_lds_dwordx4 v195, s[64:65]
	s_add_u32 m0, s77, 0x2000
	s_nop 0
	global_load_lds_dwordx4 v212, s[64:65]
	s_waitcnt vmcnt(8)
	s_waitcnt lgkmcnt(0)
	s_setprio 1
	s_barrier
	v_mfma_f32_16x16x32_bf16 v[62:65], v[132:135], v[170:173], v[62:65]
	v_mfma_f32_16x16x32_bf16 v[62:65], v[136:139], v[174:177], v[62:65]
	v_mfma_f32_16x16x32_bf16 v[58:61], v[140:143], v[170:173], v[58:61]
	v_mfma_f32_16x16x32_bf16 v[58:61], v[144:147], v[174:177], v[58:61]
	v_mfma_f32_16x16x32_bf16 v[46:49], v[132:135], v[178:181], v[46:49]
	v_mfma_f32_16x16x32_bf16 v[46:49], v[136:139], v[182:185], v[46:49]
	v_mfma_f32_16x16x32_bf16 v[42:45], v[140:143], v[178:181], v[42:45]
	v_mfma_f32_16x16x32_bf16 v[42:45], v[144:147], v[182:185], v[42:45]
	v_mfma_f32_16x16x32_bf16 v[30:33], v[132:135], v[186:189], v[30:33]
	v_mfma_f32_16x16x32_bf16 v[30:33], v[136:139], v[190:193], v[30:33]
	v_mfma_f32_16x16x32_bf16 v[26:29], v[140:143], v[186:189], v[26:29]
	v_mfma_f32_16x16x32_bf16 v[26:29], v[144:147], v[190:193], v[26:29]
	v_mfma_f32_16x16x32_bf16 v[14:17], v[132:135], v[198:201], v[14:17]
	v_mfma_f32_16x16x32_bf16 v[14:17], v[136:139], v[202:205], v[14:17]
	v_mfma_f32_16x16x32_bf16 v[10:13], v[140:143], v[198:201], v[10:13]
	v_mfma_f32_16x16x32_bf16 v[10:13], v[144:147], v[202:205], v[10:13]
	v_mfma_f32_16x16x32_bf16 v[54:57], v[154:157], v[170:173], v[54:57]
	v_mfma_f32_16x16x32_bf16 v[54:57], v[158:161], v[174:177], v[54:57]
	v_mfma_f32_16x16x32_bf16 v[50:53], v[162:165], v[170:173], v[50:53]
	v_mfma_f32_16x16x32_bf16 v[50:53], v[166:169], v[174:177], v[50:53]
	v_mfma_f32_16x16x32_bf16 v[38:41], v[154:157], v[178:181], v[38:41]
	v_mfma_f32_16x16x32_bf16 v[38:41], v[158:161], v[182:185], v[38:41]
	v_mfma_f32_16x16x32_bf16 v[34:37], v[162:165], v[178:181], v[34:37]
	v_mfma_f32_16x16x32_bf16 v[34:37], v[166:169], v[182:185], v[34:37]
	v_mfma_f32_16x16x32_bf16 v[22:25], v[154:157], v[186:189], v[22:25]
	v_mfma_f32_16x16x32_bf16 v[22:25], v[158:161], v[190:193], v[22:25]
	v_mfma_f32_16x16x32_bf16 v[18:21], v[162:165], v[186:189], v[18:21]
	v_mfma_f32_16x16x32_bf16 v[18:21], v[166:169], v[190:193], v[18:21]
	v_mfma_f32_16x16x32_bf16 v[6:9], v[154:157], v[198:201], v[6:9]
	v_mfma_f32_16x16x32_bf16 v[6:9], v[158:161], v[202:205], v[6:9]
	s_setprio 2
	s_barrier
	v_mfma_f32_16x16x32_bf16 v[2:5], v[162:165], v[198:201], v[2:5]
	v_mfma_f32_16x16x32_bf16 v[2:5], v[166:169], v[202:205], v[2:5]
	s_setprio 0
	s_nop 0
	s_add_i32 s97, s97, 2
	s_add_u32 s0, s0, 0x10000
	s_addc_u32 s1, s1, 0
	s_cmp_gt_u32 s97, 13
	s_cbranch_scc1 .LBB0_1070
	v_mov_b32_e32 v131, v130
	s_branch .LBB0_1066

.LBB0_1336:
	s_add_u32 s50, s46, 0x10000
	s_addc_u32 s51, s47, 0
	s_and_b64 s[46:47], s[42:43], exec
	s_cselect_b32 s47, s51, s23
	s_cselect_b32 s46, s50, s75
	s_add_u32 s13, s16, s13
	s_addc_u32 s50, s17, 0
	s_add_u32 s13, s13, 0x10000
	s_waitcnt vmcnt(8)
	s_addc_u32 s50, s50, 0
	s_waitcnt lgkmcnt(0)
	s_and_b64 s[42:43], s[42:43], exec
	s_cselect_b32 s43, s50, s25
	s_cselect_b32 s42, s13, s76
	s_setprio 1
	s_barrier
	v_mfma_f32_16x16x32_bf16 v[126:129], v[146:149], v[186:189], v[126:129]
	v_mfma_f32_16x16x32_bf16 v[126:129], v[150:153], v[190:193], v[126:129]
	v_mfma_f32_16x16x32_bf16 v[122:125], v[154:157], v[186:189], v[122:125]
	v_mfma_f32_16x16x32_bf16 v[122:125], v[158:161], v[190:193], v[122:125]
	v_mfma_f32_16x16x32_bf16 v[118:121], v[146:149], v[178:181], v[118:121]
	v_mfma_f32_16x16x32_bf16 v[118:121], v[150:153], v[182:185], v[118:121]
	v_mfma_f32_16x16x32_bf16 v[114:117], v[154:157], v[178:181], v[114:117]
	v_mfma_f32_16x16x32_bf16 v[114:117], v[158:161], v[182:185], v[114:117]
	v_mfma_f32_16x16x32_bf16 v[110:113], v[146:149], v[170:173], v[110:113]
	v_mfma_f32_16x16x32_bf16 v[110:113], v[150:153], v[174:177], v[110:113]
	v_mfma_f32_16x16x32_bf16 v[106:109], v[154:157], v[170:173], v[106:109]
	v_mfma_f32_16x16x32_bf16 v[106:109], v[158:161], v[174:177], v[106:109]
	v_mfma_f32_16x16x32_bf16 v[102:105], v[146:149], v[162:165], v[102:105]
	v_mfma_f32_16x16x32_bf16 v[102:105], v[150:153], v[166:169], v[102:105]
	v_mfma_f32_16x16x32_bf16 v[98:101], v[154:157], v[162:165], v[98:101]
	v_mfma_f32_16x16x32_bf16 v[98:101], v[158:161], v[166:169], v[98:101]
	v_mfma_f32_16x16x32_bf16 v[94:97], v[130:133], v[186:189], v[94:97]
	v_mfma_f32_16x16x32_bf16 v[94:97], v[134:137], v[190:193], v[94:97]
	v_mfma_f32_16x16x32_bf16 v[90:93], v[138:141], v[186:189], v[90:93]
	v_mfma_f32_16x16x32_bf16 v[90:93], v[142:145], v[190:193], v[90:93]
	v_mfma_f32_16x16x32_bf16 v[86:89], v[130:133], v[178:181], v[86:89]
	v_mfma_f32_16x16x32_bf16 v[86:89], v[134:137], v[182:185], v[86:89]
	v_mfma_f32_16x16x32_bf16 v[82:85], v[138:141], v[178:181], v[82:85]
	v_mfma_f32_16x16x32_bf16 v[82:85], v[142:145], v[182:185], v[82:85]
	v_mfma_f32_16x16x32_bf16 v[78:81], v[130:133], v[170:173], v[78:81]
	v_mfma_f32_16x16x32_bf16 v[78:81], v[134:137], v[174:177], v[78:81]
	v_mfma_f32_16x16x32_bf16 v[74:77], v[138:141], v[170:173], v[74:77]
	v_mfma_f32_16x16x32_bf16 v[74:77], v[142:145], v[174:177], v[74:77]
	v_mfma_f32_16x16x32_bf16 v[70:73], v[130:133], v[162:165], v[70:73]
	v_mfma_f32_16x16x32_bf16 v[70:73], v[134:137], v[166:169], v[70:73]
	s_setprio 2
	s_barrier
	v_mfma_f32_16x16x32_bf16 v[66:69], v[138:141], v[162:165], v[66:69]
	v_mfma_f32_16x16x32_bf16 v[66:69], v[142:145], v[166:169], v[66:69]
	s_setprio 0
	s_nop 0
	ds_read_b128 v[186:189], v208 offset:16384
	ds_read_b128 v[190:193], v208 offset:17408
	ds_read_b128 v[178:181], v208 offset:18432
	ds_read_b128 v[182:185], v208 offset:19456
	ds_read_b128 v[170:173], v208 offset:20480
	ds_read_b128 v[174:177], v208 offset:21504
	ds_read_b128 v[162:165], v208 offset:22528
	ds_read_b128 v[166:169], v208 offset:23552
	s_mov_b32 m0, s58
	s_nop 0
	global_load_lds_dwordx4 v202, s[42:43]
	s_add_u32 m0, s58, 0x2000
	s_nop 0
	global_load_lds_dwordx4 v203, s[42:43]
	s_add_u32 s50, s42, 0x4000
	s_addc_u32 s51, s43, 0
	s_mov_b32 m0, s59
	s_nop 0
	global_load_lds_dwordx4 v202, s[50:51]
	s_add_u32 m0, s59, 0x2000
	s_nop 0
	global_load_lds_dwordx4 v203, s[50:51]
	s_andn2_b64 vcc, exec, s[48:49]
	s_mov_b32 m0, s7
	s_nop 0
	global_load_lds_dwordx4 v202, s[46:47]
	s_add_u32 m0, s7, 0x2000
	s_nop 0
	global_load_lds_dwordx4 v203, s[46:47]
	s_cbranch_vccnz .LBB0_1338
	v_mov_b32_e32 v2, 0
	v_mov_b32_e32 v3, v2
	v_mov_b32_e32 v4, v2
	v_mov_b32_e32 v5, v2
	v_mov_b32_e32 v6, v2
	v_mov_b32_e32 v7, v2
	v_mov_b32_e32 v8, v2
	v_mov_b32_e32 v9, v2
	v_mov_b32_e32 v10, v2
	v_mov_b32_e32 v11, v2
	v_mov_b32_e32 v12, v2
	v_mov_b32_e32 v13, v2
	v_mov_b32_e32 v14, v2
	v_mov_b32_e32 v15, v2
	v_mov_b32_e32 v16, v2
	v_mov_b32_e32 v17, v2
	v_mov_b32_e32 v18, v2
	v_mov_b32_e32 v19, v2
	v_mov_b32_e32 v20, v2
	v_mov_b32_e32 v21, v2
	v_mov_b32_e32 v22, v2
	v_mov_b32_e32 v23, v2
	v_mov_b32_e32 v24, v2
	v_mov_b32_e32 v25, v2
	v_mov_b32_e32 v26, v2
	v_mov_b32_e32 v27, v2
	v_mov_b32_e32 v28, v2
	v_mov_b32_e32 v29, v2
	v_mov_b32_e32 v30, v2
	v_mov_b32_e32 v31, v2
	v_mov_b32_e32 v32, v2
	v_mov_b32_e32 v33, v2
	v_mov_b32_e32 v34, v2
	v_mov_b32_e32 v35, v2
	v_mov_b32_e32 v36, v2
	v_mov_b32_e32 v37, v2
	v_mov_b32_e32 v38, v2
	v_mov_b32_e32 v39, v2
	v_mov_b32_e32 v40, v2
	v_mov_b32_e32 v41, v2
	v_mov_b32_e32 v42, v2
	v_mov_b32_e32 v43, v2
	v_mov_b32_e32 v44, v2
	v_mov_b32_e32 v45, v2
	v_mov_b32_e32 v46, v2
	v_mov_b32_e32 v47, v2
	v_mov_b32_e32 v48, v2
	v_mov_b32_e32 v49, v2
	v_mov_b32_e32 v50, v2
	v_mov_b32_e32 v51, v2
	v_mov_b32_e32 v52, v2
	v_mov_b32_e32 v53, v2
	v_mov_b32_e32 v54, v2
	v_mov_b32_e32 v55, v2
	v_mov_b32_e32 v56, v2
	v_mov_b32_e32 v57, v2
	v_mov_b32_e32 v58, v2
	v_mov_b32_e32 v59, v2
	v_mov_b32_e32 v60, v2
	v_mov_b32_e32 v61, v2
	v_mov_b32_e32 v62, v2
	v_mov_b32_e32 v63, v2
	v_mov_b32_e32 v64, v2
	v_mov_b32_e32 v65, v2
.LBB0_1338:
	s_waitcnt vmcnt(8)
	s_add_u32 s48, s46, 0x8000
	s_waitcnt lgkmcnt(0)
	s_addc_u32 s49, s47, 0
	s_add_u32 s50, s42, 0x8000
	s_addc_u32 s51, s43, 0
	s_setprio 1
	s_barrier
	v_mfma_f32_16x16x32_bf16 v[62:65], v[146:149], v[186:189], v[62:65]
	v_mfma_f32_16x16x32_bf16 v[62:65], v[150:153], v[190:193], v[62:65]
	v_mfma_f32_16x16x32_bf16 v[58:61], v[154:157], v[186:189], v[58:61]
	v_mfma_f32_16x16x32_bf16 v[58:61], v[158:161], v[190:193], v[58:61]
	v_mfma_f32_16x16x32_bf16 v[54:57], v[146:149], v[178:181], v[54:57]
	v_mfma_f32_16x16x32_bf16 v[54:57], v[150:153], v[182:185], v[54:57]
	v_mfma_f32_16x16x32_bf16 v[50:53], v[154:157], v[178:181], v[50:53]
	v_mfma_f32_16x16x32_bf16 v[50:53], v[158:161], v[182:185], v[50:53]
	v_mfma_f32_16x16x32_bf16 v[46:49], v[146:149], v[170:173], v[46:49]
	v_mfma_f32_16x16x32_bf16 v[46:49], v[150:153], v[174:177], v[46:49]
	v_mfma_f32_16x16x32_bf16 v[42:45], v[154:157], v[170:173], v[42:45]
	v_mfma_f32_16x16x32_bf16 v[42:45], v[158:161], v[174:177], v[42:45]
	v_mfma_f32_16x16x32_bf16 v[38:41], v[146:149], v[162:165], v[38:41]
	v_mfma_f32_16x16x32_bf16 v[38:41], v[150:153], v[166:169], v[38:41]
	v_mfma_f32_16x16x32_bf16 v[34:37], v[154:157], v[162:165], v[34:37]
	v_mfma_f32_16x16x32_bf16 v[34:37], v[158:161], v[166:169], v[34:37]
	v_mfma_f32_16x16x32_bf16 v[30:33], v[130:133], v[186:189], v[30:33]
	v_mfma_f32_16x16x32_bf16 v[30:33], v[134:137], v[190:193], v[30:33]
	v_mfma_f32_16x16x32_bf16 v[26:29], v[138:141], v[186:189], v[26:29]
	v_mfma_f32_16x16x32_bf16 v[26:29], v[142:145], v[190:193], v[26:29]
	v_mfma_f32_16x16x32_bf16 v[22:25], v[130:133], v[178:181], v[22:25]
	v_mfma_f32_16x16x32_bf16 v[22:25], v[134:137], v[182:185], v[22:25]
	v_mfma_f32_16x16x32_bf16 v[18:21], v[138:141], v[178:181], v[18:21]
	v_mfma_f32_16x16x32_bf16 v[18:21], v[142:145], v[182:185], v[18:21]
	v_mfma_f32_16x16x32_bf16 v[14:17], v[130:133], v[170:173], v[14:17]
	v_mfma_f32_16x16x32_bf16 v[14:17], v[134:137], v[174:177], v[14:17]
	v_mfma_f32_16x16x32_bf16 v[10:13], v[138:141], v[170:173], v[10:13]
	v_mfma_f32_16x16x32_bf16 v[10:13], v[142:145], v[174:177], v[10:13]
	v_mfma_f32_16x16x32_bf16 v[6:9], v[130:133], v[162:165], v[6:9]
	v_mfma_f32_16x16x32_bf16 v[6:9], v[134:137], v[166:169], v[6:9]
	s_setprio 2
	s_barrier
	v_mfma_f32_16x16x32_bf16 v[2:5], v[138:141], v[162:165], v[2:5]
	v_mfma_f32_16x16x32_bf16 v[2:5], v[142:145], v[166:169], v[2:5]
	s_setprio 0
	s_nop 0
	v_add_u32_e32 v142, 0x18000, v207
	v_add_u32_e32 v158, 0x1c000, v207
	ds_read_b128 v[130:133], v142
	ds_read_b128 v[134:137], v142 offset:1024
	ds_read_b128 v[138:141], v142 offset:2048
	ds_read_b128 v[142:145], v142 offset:3072
	ds_read_b128 v[146:149], v158
	ds_read_b128 v[150:153], v158 offset:1024
	ds_read_b128 v[154:157], v158 offset:2048
	ds_read_b128 v[158:161], v158 offset:3072
	ds_read_b128 v[162:165], v208 offset:32768
	ds_read_b128 v[166:169], v208 offset:33792
	ds_read_b128 v[170:173], v208 offset:34816
	ds_read_b128 v[174:177], v208 offset:35840
	ds_read_b128 v[178:181], v208 offset:36864
	ds_read_b128 v[182:185], v208 offset:37888
	ds_read_b128 v[186:189], v208 offset:38912
	ds_read_b128 v[190:193], v208 offset:39936
	s_add_u32 s46, s46, 0x4000
	s_addc_u32 s47, s47, 0
	s_mov_b32 m0, s60
	s_nop 0
	global_load_lds_dwordx4 v202, s[46:47]
	s_add_u32 m0, s60, 0x2000
	s_nop 0
	global_load_lds_dwordx4 v203, s[46:47]
	s_waitcnt vmcnt(8)
	s_waitcnt lgkmcnt(0)
	s_setprio 1
	s_barrier
	v_mfma_f32_16x16x32_bf16 v[126:129], v[130:133], v[162:165], v[126:129]
	v_mfma_f32_16x16x32_bf16 v[126:129], v[134:137], v[166:169], v[126:129]
	v_mfma_f32_16x16x32_bf16 v[122:125], v[138:141], v[162:165], v[122:125]
	v_mfma_f32_16x16x32_bf16 v[122:125], v[142:145], v[166:169], v[122:125]
	v_mfma_f32_16x16x32_bf16 v[118:121], v[130:133], v[170:173], v[118:121]
	v_mfma_f32_16x16x32_bf16 v[118:121], v[134:137], v[174:177], v[118:121]
	v_mfma_f32_16x16x32_bf16 v[114:117], v[138:141], v[170:173], v[114:117]
	v_mfma_f32_16x16x32_bf16 v[114:117], v[142:145], v[174:177], v[114:117]
	v_mfma_f32_16x16x32_bf16 v[110:113], v[130:133], v[178:181], v[110:113]
	v_mfma_f32_16x16x32_bf16 v[110:113], v[134:137], v[182:185], v[110:113]
	v_mfma_f32_16x16x32_bf16 v[106:109], v[138:141], v[178:181], v[106:109]
	v_mfma_f32_16x16x32_bf16 v[106:109], v[142:145], v[182:185], v[106:109]
	v_mfma_f32_16x16x32_bf16 v[102:105], v[130:133], v[186:189], v[102:105]
	v_mfma_f32_16x16x32_bf16 v[102:105], v[134:137], v[190:193], v[102:105]
	v_mfma_f32_16x16x32_bf16 v[98:101], v[138:141], v[186:189], v[98:101]
	v_mfma_f32_16x16x32_bf16 v[98:101], v[142:145], v[190:193], v[98:101]
	v_mfma_f32_16x16x32_bf16 v[94:97], v[146:149], v[162:165], v[94:97]
	v_mfma_f32_16x16x32_bf16 v[94:97], v[150:153], v[166:169], v[94:97]
	v_mfma_f32_16x16x32_bf16 v[90:93], v[154:157], v[162:165], v[90:93]
	v_mfma_f32_16x16x32_bf16 v[90:93], v[158:161], v[166:169], v[90:93]
	v_mfma_f32_16x16x32_bf16 v[86:89], v[146:149], v[170:173], v[86:89]
	v_mfma_f32_16x16x32_bf16 v[86:89], v[150:153], v[174:177], v[86:89]
	v_mfma_f32_16x16x32_bf16 v[82:85], v[154:157], v[170:173], v[82:85]
	v_mfma_f32_16x16x32_bf16 v[82:85], v[158:161], v[174:177], v[82:85]
	v_mfma_f32_16x16x32_bf16 v[78:81], v[146:149], v[178:181], v[78:81]
	v_mfma_f32_16x16x32_bf16 v[78:81], v[150:153], v[182:185], v[78:81]
	v_mfma_f32_16x16x32_bf16 v[74:77], v[154:157], v[178:181], v[74:77]
	v_mfma_f32_16x16x32_bf16 v[74:77], v[158:161], v[182:185], v[74:77]
	v_mfma_f32_16x16x32_bf16 v[70:73], v[146:149], v[186:189], v[70:73]
	v_mfma_f32_16x16x32_bf16 v[70:73], v[150:153], v[190:193], v[70:73]
	s_setprio 2
	s_barrier
	v_mfma_f32_16x16x32_bf16 v[66:69], v[154:157], v[186:189], v[66:69]
	v_mfma_f32_16x16x32_bf16 v[66:69], v[158:161], v[190:193], v[66:69]
	s_setprio 0
	s_nop 0
	ds_read_b128 v[162:165], v208 offset:49152
	ds_read_b128 v[166:169], v208 offset:50176
	ds_read_b128 v[170:173], v208 offset:51200
	ds_read_b128 v[174:177], v208 offset:52224
	ds_read_b128 v[178:181], v208 offset:53248
	ds_read_b128 v[182:185], v208 offset:54272
	ds_read_b128 v[186:189], v208 offset:55296
	ds_read_b128 v[190:193], v208 offset:56320
	s_mov_b32 m0, s64
	s_nop 0
	global_load_lds_dwordx4 v202, s[50:51]
	s_add_u32 m0, s64, 0x2000
	s_nop 0
	global_load_lds_dwordx4 v203, s[50:51]
	s_add_u32 s42, s42, 0xc000
	s_addc_u32 s43, s43, 0
	s_mov_b32 m0, s66
	s_nop 0
	global_load_lds_dwordx4 v202, s[42:43]
	s_add_u32 m0, s66, 0x2000
	s_nop 0
	global_load_lds_dwordx4 v203, s[42:43]
	s_nop 0
	s_mov_b32 m0, s65
	s_nop 0
	global_load_lds_dwordx4 v202, s[48:49]
	s_add_u32 m0, s65, 0x2000
	s_nop 0
	global_load_lds_dwordx4 v203, s[48:49]
	s_waitcnt vmcnt(8)
	s_waitcnt lgkmcnt(0)
	s_setprio 1
	s_barrier
	v_mfma_f32_16x16x32_bf16 v[62:65], v[130:133], v[162:165], v[62:65]
	v_mfma_f32_16x16x32_bf16 v[62:65], v[134:137], v[166:169], v[62:65]
	v_mfma_f32_16x16x32_bf16 v[58:61], v[138:141], v[162:165], v[58:61]
	v_mfma_f32_16x16x32_bf16 v[58:61], v[142:145], v[166:169], v[58:61]
	v_mfma_f32_16x16x32_bf16 v[54:57], v[130:133], v[170:173], v[54:57]
	v_mfma_f32_16x16x32_bf16 v[54:57], v[134:137], v[174:177], v[54:57]
	v_mfma_f32_16x16x32_bf16 v[50:53], v[138:141], v[170:173], v[50:53]
	v_mfma_f32_16x16x32_bf16 v[50:53], v[142:145], v[174:177], v[50:53]
	v_mfma_f32_16x16x32_bf16 v[46:49], v[130:133], v[178:181], v[46:49]
	v_mfma_f32_16x16x32_bf16 v[46:49], v[134:137], v[182:185], v[46:49]
	v_mfma_f32_16x16x32_bf16 v[42:45], v[138:141], v[178:181], v[42:45]
	v_mfma_f32_16x16x32_bf16 v[42:45], v[142:145], v[182:185], v[42:45]
	v_mfma_f32_16x16x32_bf16 v[38:41], v[130:133], v[186:189], v[38:41]
	v_mfma_f32_16x16x32_bf16 v[38:41], v[134:137], v[190:193], v[38:41]
	v_mfma_f32_16x16x32_bf16 v[34:37], v[138:141], v[186:189], v[34:37]
	v_mfma_f32_16x16x32_bf16 v[34:37], v[142:145], v[190:193], v[34:37]
	v_mfma_f32_16x16x32_bf16 v[30:33], v[146:149], v[162:165], v[30:33]
	v_mfma_f32_16x16x32_bf16 v[30:33], v[150:153], v[166:169], v[30:33]
	v_mfma_f32_16x16x32_bf16 v[26:29], v[154:157], v[162:165], v[26:29]
	v_mfma_f32_16x16x32_bf16 v[26:29], v[158:161], v[166:169], v[26:29]
	v_mfma_f32_16x16x32_bf16 v[22:25], v[146:149], v[170:173], v[22:25]
	v_mfma_f32_16x16x32_bf16 v[22:25], v[150:153], v[174:177], v[22:25]
	v_mfma_f32_16x16x32_bf16 v[18:21], v[154:157], v[170:173], v[18:21]
	v_mfma_f32_16x16x32_bf16 v[18:21], v[158:161], v[174:177], v[18:21]
	v_mfma_f32_16x16x32_bf16 v[14:17], v[146:149], v[178:181], v[14:17]
	v_mfma_f32_16x16x32_bf16 v[14:17], v[150:153], v[182:185], v[14:17]
	v_mfma_f32_16x16x32_bf16 v[10:13], v[154:157], v[178:181], v[10:13]
	v_mfma_f32_16x16x32_bf16 v[10:13], v[158:161], v[182:185], v[10:13]
	v_mfma_f32_16x16x32_bf16 v[6:9], v[146:149], v[186:189], v[6:9]
	v_mfma_f32_16x16x32_bf16 v[6:9], v[150:153], v[190:193], v[6:9]
	s_setprio 2
	s_barrier
	v_mfma_f32_16x16x32_bf16 v[2:5], v[154:157], v[186:189], v[2:5]
	v_mfma_f32_16x16x32_bf16 v[2:5], v[158:161], v[190:193], v[2:5]
	s_setprio 0
	s_nop 0
	s_add_i32 s13, s77, 2
	s_cmp_gt_u32 s77, 5
	s_cbranch_scc1 .LBB0_1340
	s_mov_b32 s77, s13
	s_branch .LBB0_1317

.LBB0_1374:
	s_or_b64 exec, exec, s[40:41]
	s_add_u32 s76, s16, s6
	ds_read_b128 v[132:135], v168
	ds_read_b128 v[136:139], v168 offset:1024
	ds_read_b128 v[140:143], v168 offset:2048
	ds_read_b128 v[144:147], v168 offset:3072
	ds_read_b128 v[148:151], v169
	ds_read_b128 v[158:161], v169 offset:1024
	ds_read_b128 v[162:165], v169 offset:2048
	ds_read_b128 v[174:177], v169 offset:3072
	s_addc_u32 s77, s17, s7
	s_add_u32 s40, s76, 0x20000
	s_addc_u32 s41, s77, 0
	s_add_u32 s42, s71, s6
	s_addc_u32 s43, s72, s7
	s_cmp_eq_u32 s6, 0x20000
	s_cselect_b32 s48, s73, s40
	s_cselect_b32 s49, s27, s41
	s_cselect_b32 s41, s25, s43
	s_cselect_b32 s40, s74, s42
	s_add_u32 s42, s48, 0x8000
	s_addc_u32 s43, s49, 0
	s_add_u32 s46, s40, 0x8000
	s_addc_u32 s47, s41, 0
	ds_read_b128 v[178:181], v170
	ds_read_b128 v[182:185], v170 offset:1024
	ds_read_b128 v[186:189], v170 offset:2048
	ds_read_b128 v[190:193], v170 offset:3072
	ds_read_b128 v[198:201], v170 offset:4096
	ds_read_b128 v[204:207], v170 offset:5120
	ds_read_b128 v[212:215], v170 offset:6144
	ds_read_b128 v[216:219], v170 offset:7168
	s_add_u32 s76, s76, 0x1c000
	s_addc_u32 s77, s77, 0
	s_mov_b32 m0, s63
	s_nop 0
	global_load_lds_dwordx4 v202, s[76:77]
	s_add_u32 m0, s63, 0x2000
	s_nop 0
	global_load_lds_dwordx4 v203, s[76:77]
	s_waitcnt vmcnt(8)
	s_waitcnt lgkmcnt(0)
	s_setprio 1
	s_barrier
	v_mfma_f32_16x16x32_bf16 v[126:129], v[132:135], v[178:181], v[126:129]
	v_mfma_f32_16x16x32_bf16 v[126:129], v[136:139], v[182:185], v[126:129]
	v_mfma_f32_16x16x32_bf16 v[122:125], v[140:143], v[178:181], v[122:125]
	v_mfma_f32_16x16x32_bf16 v[122:125], v[144:147], v[182:185], v[122:125]
	v_mfma_f32_16x16x32_bf16 v[110:113], v[132:135], v[186:189], v[110:113]
	v_mfma_f32_16x16x32_bf16 v[110:113], v[136:139], v[190:193], v[110:113]
	v_mfma_f32_16x16x32_bf16 v[106:109], v[140:143], v[186:189], v[106:109]
	v_mfma_f32_16x16x32_bf16 v[106:109], v[144:147], v[190:193], v[106:109]
	v_mfma_f32_16x16x32_bf16 v[94:97], v[132:135], v[198:201], v[94:97]
	v_mfma_f32_16x16x32_bf16 v[94:97], v[136:139], v[204:207], v[94:97]
	v_mfma_f32_16x16x32_bf16 v[90:93], v[140:143], v[198:201], v[90:93]
	v_mfma_f32_16x16x32_bf16 v[90:93], v[144:147], v[204:207], v[90:93]
	v_mfma_f32_16x16x32_bf16 v[78:81], v[132:135], v[212:215], v[78:81]
	v_mfma_f32_16x16x32_bf16 v[78:81], v[136:139], v[216:219], v[78:81]
	v_mfma_f32_16x16x32_bf16 v[74:77], v[140:143], v[212:215], v[74:77]
	v_mfma_f32_16x16x32_bf16 v[74:77], v[144:147], v[216:219], v[74:77]
	v_mfma_f32_16x16x32_bf16 v[118:121], v[148:151], v[178:181], v[118:121]
	v_mfma_f32_16x16x32_bf16 v[118:121], v[158:161], v[182:185], v[118:121]
	v_mfma_f32_16x16x32_bf16 v[114:117], v[162:165], v[178:181], v[114:117]
	v_mfma_f32_16x16x32_bf16 v[114:117], v[174:177], v[182:185], v[114:117]
	v_mfma_f32_16x16x32_bf16 v[102:105], v[148:151], v[186:189], v[102:105]
	v_mfma_f32_16x16x32_bf16 v[102:105], v[158:161], v[190:193], v[102:105]
	v_mfma_f32_16x16x32_bf16 v[98:101], v[162:165], v[186:189], v[98:101]
	v_mfma_f32_16x16x32_bf16 v[98:101], v[174:177], v[190:193], v[98:101]
	v_mfma_f32_16x16x32_bf16 v[86:89], v[148:151], v[198:201], v[86:89]
	v_mfma_f32_16x16x32_bf16 v[86:89], v[158:161], v[204:207], v[86:89]
	v_mfma_f32_16x16x32_bf16 v[82:85], v[162:165], v[198:201], v[82:85]
	v_mfma_f32_16x16x32_bf16 v[82:85], v[174:177], v[204:207], v[82:85]
	v_mfma_f32_16x16x32_bf16 v[70:73], v[148:151], v[212:215], v[70:73]
	v_mfma_f32_16x16x32_bf16 v[70:73], v[158:161], v[216:219], v[70:73]
	s_setprio 2
	s_barrier
	v_mfma_f32_16x16x32_bf16 v[66:69], v[162:165], v[212:215], v[66:69]
	v_mfma_f32_16x16x32_bf16 v[66:69], v[174:177], v[216:219], v[66:69]
	s_setprio 0
	s_nop 0
	ds_read_b128 v[178:181], v170 offset:16384
	ds_read_b128 v[182:185], v170 offset:17408
	ds_read_b128 v[186:189], v170 offset:18432
	ds_read_b128 v[190:193], v170 offset:19456
	ds_read_b128 v[198:201], v170 offset:20480
	ds_read_b128 v[204:207], v170 offset:21504
	ds_read_b128 v[212:215], v170 offset:22528
	ds_read_b128 v[216:219], v170 offset:23552
	s_mov_b32 m0, s13
	s_nop 0
	global_load_lds_dwordx4 v202, s[40:41]
	s_add_u32 m0, s13, 0x2000
	s_nop 0
	global_load_lds_dwordx4 v203, s[40:41]
	s_add_u32 s76, s40, 0x4000
	s_addc_u32 s77, s41, 0
	s_mov_b32 m0, s55
	s_nop 0
	global_load_lds_dwordx4 v202, s[76:77]
	s_add_u32 m0, s55, 0x2000
	s_nop 0
	global_load_lds_dwordx4 v203, s[76:77]
	s_nop 0
	s_mov_b32 m0, s54
	s_nop 0
	global_load_lds_dwordx4 v202, s[48:49]
	s_add_u32 m0, s54, 0x2000
	s_nop 0
	global_load_lds_dwordx4 v203, s[48:49]
	s_waitcnt vmcnt(8)
	s_waitcnt lgkmcnt(0)
	s_setprio 1
	s_barrier
	v_mfma_f32_16x16x32_bf16 v[62:65], v[132:135], v[178:181], v[62:65]
	v_mfma_f32_16x16x32_bf16 v[62:65], v[136:139], v[182:185], v[62:65]
	v_mfma_f32_16x16x32_bf16 v[58:61], v[140:143], v[178:181], v[58:61]
	v_mfma_f32_16x16x32_bf16 v[58:61], v[144:147], v[182:185], v[58:61]
	v_mfma_f32_16x16x32_bf16 v[46:49], v[132:135], v[186:189], v[46:49]
	v_mfma_f32_16x16x32_bf16 v[46:49], v[136:139], v[190:193], v[46:49]
	v_mfma_f32_16x16x32_bf16 v[42:45], v[140:143], v[186:189], v[42:45]
	v_mfma_f32_16x16x32_bf16 v[42:45], v[144:147], v[190:193], v[42:45]
	v_mfma_f32_16x16x32_bf16 v[30:33], v[132:135], v[198:201], v[30:33]
	v_mfma_f32_16x16x32_bf16 v[30:33], v[136:139], v[204:207], v[30:33]
	v_mfma_f32_16x16x32_bf16 v[26:29], v[140:143], v[198:201], v[26:29]
	v_mfma_f32_16x16x32_bf16 v[26:29], v[144:147], v[204:207], v[26:29]
	v_mfma_f32_16x16x32_bf16 v[14:17], v[132:135], v[212:215], v[14:17]
	v_mfma_f32_16x16x32_bf16 v[14:17], v[136:139], v[216:219], v[14:17]
	v_mfma_f32_16x16x32_bf16 v[10:13], v[140:143], v[212:215], v[10:13]
	v_mfma_f32_16x16x32_bf16 v[10:13], v[144:147], v[216:219], v[10:13]
	v_mfma_f32_16x16x32_bf16 v[54:57], v[148:151], v[178:181], v[54:57]
	v_mfma_f32_16x16x32_bf16 v[54:57], v[158:161], v[182:185], v[54:57]
	v_mfma_f32_16x16x32_bf16 v[50:53], v[162:165], v[178:181], v[50:53]
	v_mfma_f32_16x16x32_bf16 v[50:53], v[174:177], v[182:185], v[50:53]
	v_mfma_f32_16x16x32_bf16 v[38:41], v[148:151], v[186:189], v[38:41]
	v_mfma_f32_16x16x32_bf16 v[38:41], v[158:161], v[190:193], v[38:41]
	v_mfma_f32_16x16x32_bf16 v[34:37], v[162:165], v[186:189], v[34:37]
	v_mfma_f32_16x16x32_bf16 v[34:37], v[174:177], v[190:193], v[34:37]
	v_mfma_f32_16x16x32_bf16 v[22:25], v[148:151], v[198:201], v[22:25]
	v_mfma_f32_16x16x32_bf16 v[22:25], v[158:161], v[204:207], v[22:25]
	v_mfma_f32_16x16x32_bf16 v[18:21], v[162:165], v[198:201], v[18:21]
	v_mfma_f32_16x16x32_bf16 v[18:21], v[174:177], v[204:207], v[18:21]
	v_mfma_f32_16x16x32_bf16 v[6:9], v[148:151], v[212:215], v[6:9]
	v_mfma_f32_16x16x32_bf16 v[6:9], v[158:161], v[216:219], v[6:9]
	s_setprio 2
	s_barrier
	v_mfma_f32_16x16x32_bf16 v[2:5], v[162:165], v[212:215], v[2:5]
	v_mfma_f32_16x16x32_bf16 v[2:5], v[174:177], v[216:219], v[2:5]
	s_setprio 0
	s_nop 0
	ds_read_b128 v[132:135], v171
	ds_read_b128 v[136:139], v171 offset:1024
	ds_read_b128 v[140:143], v171 offset:2048
	ds_read_b128 v[144:147], v171 offset:3072
	ds_read_b128 v[148:151], v172
	ds_read_b128 v[158:161], v172 offset:1024
	ds_read_b128 v[162:165], v172 offset:2048
	ds_read_b128 v[174:177], v172 offset:3072
	ds_read_b128 v[178:181], v170 offset:32768
	ds_read_b128 v[182:185], v170 offset:33792
	ds_read_b128 v[186:189], v170 offset:34816
	ds_read_b128 v[190:193], v170 offset:35840
	ds_read_b128 v[198:201], v170 offset:36864
	ds_read_b128 v[204:207], v170 offset:37888
	ds_read_b128 v[212:215], v170 offset:38912
	ds_read_b128 v[216:219], v170 offset:39936
	s_add_u32 s48, s48, 0x4000
	s_addc_u32 s49, s49, 0
	s_mov_b32 m0, s56
	s_nop 0
	global_load_lds_dwordx4 v202, s[48:49]
	s_add_u32 m0, s56, 0x2000
	s_nop 0
	global_load_lds_dwordx4 v203, s[48:49]
	s_waitcnt vmcnt(8)
	s_waitcnt lgkmcnt(0)
	s_setprio 1
	s_barrier
	v_mfma_f32_16x16x32_bf16 v[126:129], v[132:135], v[178:181], v[126:129]
	v_mfma_f32_16x16x32_bf16 v[126:129], v[136:139], v[182:185], v[126:129]
	v_mfma_f32_16x16x32_bf16 v[122:125], v[140:143], v[178:181], v[122:125]
	v_mfma_f32_16x16x32_bf16 v[122:125], v[144:147], v[182:185], v[122:125]
	v_mfma_f32_16x16x32_bf16 v[110:113], v[132:135], v[186:189], v[110:113]
	v_mfma_f32_16x16x32_bf16 v[110:113], v[136:139], v[190:193], v[110:113]
	v_mfma_f32_16x16x32_bf16 v[106:109], v[140:143], v[186:189], v[106:109]
	v_mfma_f32_16x16x32_bf16 v[106:109], v[144:147], v[190:193], v[106:109]
	v_mfma_f32_16x16x32_bf16 v[94:97], v[132:135], v[198:201], v[94:97]
	v_mfma_f32_16x16x32_bf16 v[94:97], v[136:139], v[204:207], v[94:97]
	v_mfma_f32_16x16x32_bf16 v[90:93], v[140:143], v[198:201], v[90:93]
	v_mfma_f32_16x16x32_bf16 v[90:93], v[144:147], v[204:207], v[90:93]
	v_mfma_f32_16x16x32_bf16 v[78:81], v[132:135], v[212:215], v[78:81]
	v_mfma_f32_16x16x32_bf16 v[78:81], v[136:139], v[216:219], v[78:81]
	v_mfma_f32_16x16x32_bf16 v[74:77], v[140:143], v[212:215], v[74:77]
	v_mfma_f32_16x16x32_bf16 v[74:77], v[144:147], v[216:219], v[74:77]
	v_mfma_f32_16x16x32_bf16 v[118:121], v[148:151], v[178:181], v[118:121]
	v_mfma_f32_16x16x32_bf16 v[118:121], v[158:161], v[182:185], v[118:121]
	v_mfma_f32_16x16x32_bf16 v[114:117], v[162:165], v[178:181], v[114:117]
	v_mfma_f32_16x16x32_bf16 v[114:117], v[174:177], v[182:185], v[114:117]
	v_mfma_f32_16x16x32_bf16 v[102:105], v[148:151], v[186:189], v[102:105]
	v_mfma_f32_16x16x32_bf16 v[102:105], v[158:161], v[190:193], v[102:105]
	v_mfma_f32_16x16x32_bf16 v[98:101], v[162:165], v[186:189], v[98:101]
	v_mfma_f32_16x16x32_bf16 v[98:101], v[174:177], v[190:193], v[98:101]
	v_mfma_f32_16x16x32_bf16 v[86:89], v[148:151], v[198:201], v[86:89]
	v_mfma_f32_16x16x32_bf16 v[86:89], v[158:161], v[204:207], v[86:89]
	v_mfma_f32_16x16x32_bf16 v[82:85], v[162:165], v[198:201], v[82:85]
	v_mfma_f32_16x16x32_bf16 v[82:85], v[174:177], v[204:207], v[82:85]
	v_mfma_f32_16x16x32_bf16 v[70:73], v[148:151], v[212:215], v[70:73]
	v_mfma_f32_16x16x32_bf16 v[70:73], v[158:161], v[216:219], v[70:73]
	s_setprio 2
	s_barrier
	v_mfma_f32_16x16x32_bf16 v[66:69], v[162:165], v[212:215], v[66:69]
	v_mfma_f32_16x16x32_bf16 v[66:69], v[174:177], v[216:219], v[66:69]
	s_setprio 0
	s_nop 0
	ds_read_b128 v[178:181], v170 offset:49152
	ds_read_b128 v[182:185], v170 offset:50176
	ds_read_b128 v[186:189], v170 offset:51200
	ds_read_b128 v[190:193], v170 offset:52224
	ds_read_b128 v[198:201], v170 offset:53248
	ds_read_b128 v[204:207], v170 offset:54272
	ds_read_b128 v[212:215], v170 offset:55296
	ds_read_b128 v[216:219], v170 offset:56320
	s_mov_b32 m0, s59
	s_nop 0
	global_load_lds_dwordx4 v202, s[46:47]
	s_add_u32 m0, s59, 0x2000
	s_nop 0
	global_load_lds_dwordx4 v203, s[46:47]
	s_add_u32 s40, s40, 0xc000
	s_addc_u32 s41, s41, 0
	s_mov_b32 m0, s62
	s_nop 0
	global_load_lds_dwordx4 v202, s[40:41]
	s_add_u32 m0, s62, 0x2000
	s_nop 0
	global_load_lds_dwordx4 v203, s[40:41]
	s_nop 0
	s_mov_b32 m0, s61
	s_nop 0
	global_load_lds_dwordx4 v202, s[42:43]
	s_add_u32 m0, s61, 0x2000
	s_nop 0
	global_load_lds_dwordx4 v203, s[42:43]
	s_waitcnt vmcnt(8)
	s_waitcnt lgkmcnt(0)
	s_setprio 1
	s_barrier
	v_mfma_f32_16x16x32_bf16 v[62:65], v[132:135], v[178:181], v[62:65]
	v_mfma_f32_16x16x32_bf16 v[62:65], v[136:139], v[182:185], v[62:65]
	v_mfma_f32_16x16x32_bf16 v[58:61], v[140:143], v[178:181], v[58:61]
	v_mfma_f32_16x16x32_bf16 v[58:61], v[144:147], v[182:185], v[58:61]
	v_mfma_f32_16x16x32_bf16 v[46:49], v[132:135], v[186:189], v[46:49]
	v_mfma_f32_16x16x32_bf16 v[46:49], v[136:139], v[190:193], v[46:49]
	v_mfma_f32_16x16x32_bf16 v[42:45], v[140:143], v[186:189], v[42:45]
	v_mfma_f32_16x16x32_bf16 v[42:45], v[144:147], v[190:193], v[42:45]
	v_mfma_f32_16x16x32_bf16 v[30:33], v[132:135], v[198:201], v[30:33]
	v_mfma_f32_16x16x32_bf16 v[30:33], v[136:139], v[204:207], v[30:33]
	v_mfma_f32_16x16x32_bf16 v[26:29], v[140:143], v[198:201], v[26:29]
	v_mfma_f32_16x16x32_bf16 v[26:29], v[144:147], v[204:207], v[26:29]
	v_mfma_f32_16x16x32_bf16 v[14:17], v[132:135], v[212:215], v[14:17]
	v_mfma_f32_16x16x32_bf16 v[14:17], v[136:139], v[216:219], v[14:17]
	v_mfma_f32_16x16x32_bf16 v[10:13], v[140:143], v[212:215], v[10:13]
	v_mfma_f32_16x16x32_bf16 v[10:13], v[144:147], v[216:219], v[10:13]
	v_mfma_f32_16x16x32_bf16 v[54:57], v[148:151], v[178:181], v[54:57]
	v_mfma_f32_16x16x32_bf16 v[54:57], v[158:161], v[182:185], v[54:57]
	v_mfma_f32_16x16x32_bf16 v[50:53], v[162:165], v[178:181], v[50:53]
	v_mfma_f32_16x16x32_bf16 v[50:53], v[174:177], v[182:185], v[50:53]
	v_mfma_f32_16x16x32_bf16 v[38:41], v[148:151], v[186:189], v[38:41]
	v_mfma_f32_16x16x32_bf16 v[38:41], v[158:161], v[190:193], v[38:41]
	v_mfma_f32_16x16x32_bf16 v[34:37], v[162:165], v[186:189], v[34:37]
	v_mfma_f32_16x16x32_bf16 v[34:37], v[174:177], v[190:193], v[34:37]
	v_mfma_f32_16x16x32_bf16 v[22:25], v[148:151], v[198:201], v[22:25]
	v_mfma_f32_16x16x32_bf16 v[22:25], v[158:161], v[204:207], v[22:25]
	v_mfma_f32_16x16x32_bf16 v[18:21], v[162:165], v[198:201], v[18:21]
	v_mfma_f32_16x16x32_bf16 v[18:21], v[174:177], v[204:207], v[18:21]
	v_mfma_f32_16x16x32_bf16 v[6:9], v[148:151], v[212:215], v[6:9]
	v_mfma_f32_16x16x32_bf16 v[6:9], v[158:161], v[216:219], v[6:9]
	s_setprio 2
	s_barrier
	v_mfma_f32_16x16x32_bf16 v[2:5], v[162:165], v[212:215], v[2:5]
	v_mfma_f32_16x16x32_bf16 v[2:5], v[174:177], v[216:219], v[2:5]
	s_setprio 0
	s_nop 0
	s_add_i32 s75, s75, 2
	s_add_u32 s6, s6, 0x10000
	s_addc_u32 s7, s7, 0
	s_cmp_gt_u32 s75, 5
	s_cbranch_scc1 .LBB0_1376
	v_mov_b32_e32 v131, v130
	s_branch .LBB0_1372

.LBB0_1519:
	s_add_i32 s26, s58, 2
	s_lshl_b64 s[54:55], s[26:27], 15
	s_add_u32 s17, s18, s54
	s_addc_u32 s59, s19, s55
	s_and_b64 s[50:51], s[12:13], exec
	s_cselect_b32 s51, s59, s41
	s_cselect_b32 s50, s17, s56
	s_add_u32 s17, s20, s54
	s_waitcnt vmcnt(8)
	s_addc_u32 s54, s21, s55
	s_waitcnt lgkmcnt(0)
	s_and_b64 s[12:13], s[12:13], exec
	s_cselect_b32 s13, s54, s39
	s_cselect_b32 s12, s17, s57
	s_setprio 1
	s_barrier
	v_mfma_f32_16x16x32_bf16 v[126:129], v[146:149], v[186:189], v[126:129]
	v_mfma_f32_16x16x32_bf16 v[126:129], v[150:153], v[190:193], v[126:129]
	v_mfma_f32_16x16x32_bf16 v[122:125], v[154:157], v[186:189], v[122:125]
	v_mfma_f32_16x16x32_bf16 v[122:125], v[158:161], v[190:193], v[122:125]
	v_mfma_f32_16x16x32_bf16 v[118:121], v[146:149], v[178:181], v[118:121]
	v_mfma_f32_16x16x32_bf16 v[118:121], v[150:153], v[182:185], v[118:121]
	v_mfma_f32_16x16x32_bf16 v[114:117], v[154:157], v[178:181], v[114:117]
	v_mfma_f32_16x16x32_bf16 v[114:117], v[158:161], v[182:185], v[114:117]
	v_mfma_f32_16x16x32_bf16 v[110:113], v[146:149], v[170:173], v[110:113]
	v_mfma_f32_16x16x32_bf16 v[110:113], v[150:153], v[174:177], v[110:113]
	v_mfma_f32_16x16x32_bf16 v[106:109], v[154:157], v[170:173], v[106:109]
	v_mfma_f32_16x16x32_bf16 v[106:109], v[158:161], v[174:177], v[106:109]
	v_mfma_f32_16x16x32_bf16 v[102:105], v[146:149], v[162:165], v[102:105]
	v_mfma_f32_16x16x32_bf16 v[102:105], v[150:153], v[166:169], v[102:105]
	v_mfma_f32_16x16x32_bf16 v[98:101], v[154:157], v[162:165], v[98:101]
	v_mfma_f32_16x16x32_bf16 v[98:101], v[158:161], v[166:169], v[98:101]
	v_mfma_f32_16x16x32_bf16 v[94:97], v[130:133], v[186:189], v[94:97]
	v_mfma_f32_16x16x32_bf16 v[94:97], v[134:137], v[190:193], v[94:97]
	v_mfma_f32_16x16x32_bf16 v[90:93], v[138:141], v[186:189], v[90:93]
	v_mfma_f32_16x16x32_bf16 v[90:93], v[142:145], v[190:193], v[90:93]
	v_mfma_f32_16x16x32_bf16 v[86:89], v[130:133], v[178:181], v[86:89]
	v_mfma_f32_16x16x32_bf16 v[86:89], v[134:137], v[182:185], v[86:89]
	v_mfma_f32_16x16x32_bf16 v[82:85], v[138:141], v[178:181], v[82:85]
	v_mfma_f32_16x16x32_bf16 v[82:85], v[142:145], v[182:185], v[82:85]
	v_mfma_f32_16x16x32_bf16 v[78:81], v[130:133], v[170:173], v[78:81]
	v_mfma_f32_16x16x32_bf16 v[78:81], v[134:137], v[174:177], v[78:81]
	v_mfma_f32_16x16x32_bf16 v[74:77], v[138:141], v[170:173], v[74:77]
	v_mfma_f32_16x16x32_bf16 v[74:77], v[142:145], v[174:177], v[74:77]
	v_mfma_f32_16x16x32_bf16 v[70:73], v[130:133], v[162:165], v[70:73]
	v_mfma_f32_16x16x32_bf16 v[70:73], v[134:137], v[166:169], v[70:73]
	s_setprio 2
	s_barrier
	v_mfma_f32_16x16x32_bf16 v[66:69], v[138:141], v[162:165], v[66:69]
	v_mfma_f32_16x16x32_bf16 v[66:69], v[142:145], v[166:169], v[66:69]
	s_setprio 0
	s_nop 0
	ds_read_b128 v[186:189], v217 offset:16384
	ds_read_b128 v[190:193], v217 offset:17408
	ds_read_b128 v[178:181], v217 offset:18432
	ds_read_b128 v[182:185], v217 offset:19456
	ds_read_b128 v[170:173], v217 offset:20480
	ds_read_b128 v[174:177], v217 offset:21504
	ds_read_b128 v[162:165], v217 offset:22528
	ds_read_b128 v[166:169], v217 offset:23552
	s_mov_b32 m0, s66
	s_nop 0
	global_load_lds_dwordx4 v195, s[12:13]
	s_add_u32 m0, s66, 0x2000
	s_nop 0
	global_load_lds_dwordx4 v212, s[12:13]
	s_add_u32 s54, s12, 0x4000
	s_addc_u32 s55, s13, 0
	s_mov_b32 m0, s67
	s_nop 0
	global_load_lds_dwordx4 v195, s[54:55]
	s_add_u32 m0, s67, 0x2000
	s_nop 0
	global_load_lds_dwordx4 v212, s[54:55]
	s_andn2_b64 vcc, exec, s[52:53]
	s_mov_b32 m0, s15
	s_nop 0
	global_load_lds_dwordx4 v195, s[50:51]
	s_add_u32 m0, s15, 0x2000
	s_nop 0
	global_load_lds_dwordx4 v212, s[50:51]
	s_cbranch_vccnz .LBB0_1521
	v_mov_b32_e32 v2, 0
	v_mov_b32_e32 v3, v2
	v_mov_b32_e32 v4, v2
	v_mov_b32_e32 v5, v2
	v_mov_b32_e32 v6, v2
	v_mov_b32_e32 v7, v2
	v_mov_b32_e32 v8, v2
	v_mov_b32_e32 v9, v2
	v_mov_b32_e32 v10, v2
	v_mov_b32_e32 v11, v2
	v_mov_b32_e32 v12, v2
	v_mov_b32_e32 v13, v2
	v_mov_b32_e32 v14, v2
	v_mov_b32_e32 v15, v2
	v_mov_b32_e32 v16, v2
	v_mov_b32_e32 v17, v2
	v_mov_b32_e32 v18, v2
	v_mov_b32_e32 v19, v2
	v_mov_b32_e32 v20, v2
	v_mov_b32_e32 v21, v2
	v_mov_b32_e32 v22, v2
	v_mov_b32_e32 v23, v2
	v_mov_b32_e32 v24, v2
	v_mov_b32_e32 v25, v2
	v_mov_b32_e32 v26, v2
	v_mov_b32_e32 v27, v2
	v_mov_b32_e32 v28, v2
	v_mov_b32_e32 v29, v2
	v_mov_b32_e32 v30, v2
	v_mov_b32_e32 v31, v2
	v_mov_b32_e32 v32, v2
	v_mov_b32_e32 v33, v2
	v_mov_b32_e32 v34, v2
	v_mov_b32_e32 v35, v2
	v_mov_b32_e32 v36, v2
	v_mov_b32_e32 v37, v2
	v_mov_b32_e32 v38, v2
	v_mov_b32_e32 v39, v2
	v_mov_b32_e32 v40, v2
	v_mov_b32_e32 v41, v2
	v_mov_b32_e32 v42, v2
	v_mov_b32_e32 v43, v2
	v_mov_b32_e32 v44, v2
	v_mov_b32_e32 v45, v2
	v_mov_b32_e32 v46, v2
	v_mov_b32_e32 v47, v2
	v_mov_b32_e32 v48, v2
	v_mov_b32_e32 v49, v2
	v_mov_b32_e32 v50, v2
	v_mov_b32_e32 v51, v2
	v_mov_b32_e32 v52, v2
	v_mov_b32_e32 v53, v2
	v_mov_b32_e32 v54, v2
	v_mov_b32_e32 v55, v2
	v_mov_b32_e32 v56, v2
	v_mov_b32_e32 v57, v2
	v_mov_b32_e32 v58, v2
	v_mov_b32_e32 v59, v2
	v_mov_b32_e32 v60, v2
	v_mov_b32_e32 v61, v2
	v_mov_b32_e32 v62, v2
	v_mov_b32_e32 v63, v2
	v_mov_b32_e32 v64, v2
	v_mov_b32_e32 v65, v2
.LBB0_1521:
	s_waitcnt vmcnt(8)
	s_add_u32 s52, s50, 0x8000
	s_waitcnt lgkmcnt(0)
	s_addc_u32 s53, s51, 0
	s_add_u32 s54, s12, 0x8000
	s_addc_u32 s55, s13, 0
	s_setprio 1
	s_barrier
	v_mfma_f32_16x16x32_bf16 v[62:65], v[146:149], v[186:189], v[62:65]
	v_mfma_f32_16x16x32_bf16 v[62:65], v[150:153], v[190:193], v[62:65]
	v_mfma_f32_16x16x32_bf16 v[58:61], v[154:157], v[186:189], v[58:61]
	v_mfma_f32_16x16x32_bf16 v[58:61], v[158:161], v[190:193], v[58:61]
	v_mfma_f32_16x16x32_bf16 v[54:57], v[146:149], v[178:181], v[54:57]
	v_mfma_f32_16x16x32_bf16 v[54:57], v[150:153], v[182:185], v[54:57]
	v_mfma_f32_16x16x32_bf16 v[50:53], v[154:157], v[178:181], v[50:53]
	v_mfma_f32_16x16x32_bf16 v[50:53], v[158:161], v[182:185], v[50:53]
	v_mfma_f32_16x16x32_bf16 v[46:49], v[146:149], v[170:173], v[46:49]
	v_mfma_f32_16x16x32_bf16 v[46:49], v[150:153], v[174:177], v[46:49]
	v_mfma_f32_16x16x32_bf16 v[42:45], v[154:157], v[170:173], v[42:45]
	v_mfma_f32_16x16x32_bf16 v[42:45], v[158:161], v[174:177], v[42:45]
	v_mfma_f32_16x16x32_bf16 v[38:41], v[146:149], v[162:165], v[38:41]
	v_mfma_f32_16x16x32_bf16 v[38:41], v[150:153], v[166:169], v[38:41]
	v_mfma_f32_16x16x32_bf16 v[34:37], v[154:157], v[162:165], v[34:37]
	v_mfma_f32_16x16x32_bf16 v[34:37], v[158:161], v[166:169], v[34:37]
	v_mfma_f32_16x16x32_bf16 v[30:33], v[130:133], v[186:189], v[30:33]
	v_mfma_f32_16x16x32_bf16 v[30:33], v[134:137], v[190:193], v[30:33]
	v_mfma_f32_16x16x32_bf16 v[26:29], v[138:141], v[186:189], v[26:29]
	v_mfma_f32_16x16x32_bf16 v[26:29], v[142:145], v[190:193], v[26:29]
	v_mfma_f32_16x16x32_bf16 v[22:25], v[130:133], v[178:181], v[22:25]
	v_mfma_f32_16x16x32_bf16 v[22:25], v[134:137], v[182:185], v[22:25]
	v_mfma_f32_16x16x32_bf16 v[18:21], v[138:141], v[178:181], v[18:21]
	v_mfma_f32_16x16x32_bf16 v[18:21], v[142:145], v[182:185], v[18:21]
	v_mfma_f32_16x16x32_bf16 v[14:17], v[130:133], v[170:173], v[14:17]
	v_mfma_f32_16x16x32_bf16 v[14:17], v[134:137], v[174:177], v[14:17]
	v_mfma_f32_16x16x32_bf16 v[10:13], v[138:141], v[170:173], v[10:13]
	v_mfma_f32_16x16x32_bf16 v[10:13], v[142:145], v[174:177], v[10:13]
	v_mfma_f32_16x16x32_bf16 v[6:9], v[130:133], v[162:165], v[6:9]
	v_mfma_f32_16x16x32_bf16 v[6:9], v[134:137], v[166:169], v[6:9]
	s_setprio 2
	s_barrier
	v_mfma_f32_16x16x32_bf16 v[2:5], v[138:141], v[162:165], v[2:5]
	v_mfma_f32_16x16x32_bf16 v[2:5], v[142:145], v[166:169], v[2:5]
	s_setprio 0
	s_nop 0
	v_add_u32_e32 v142, 0x18000, v216
	v_add_u32_e32 v158, 0x1c000, v216
	ds_read_b128 v[130:133], v142
	ds_read_b128 v[134:137], v142 offset:1024
	ds_read_b128 v[138:141], v142 offset:2048
	ds_read_b128 v[142:145], v142 offset:3072
	ds_read_b128 v[146:149], v158
	ds_read_b128 v[150:153], v158 offset:1024
	ds_read_b128 v[154:157], v158 offset:2048
	ds_read_b128 v[158:161], v158 offset:3072
	ds_read_b128 v[162:165], v217 offset:32768
	ds_read_b128 v[166:169], v217 offset:33792
	ds_read_b128 v[170:173], v217 offset:34816
	ds_read_b128 v[174:177], v217 offset:35840
	ds_read_b128 v[178:181], v217 offset:36864
	ds_read_b128 v[182:185], v217 offset:37888
	ds_read_b128 v[186:189], v217 offset:38912
	ds_read_b128 v[190:193], v217 offset:39936
	s_add_u32 s50, s50, 0x4000
	s_addc_u32 s51, s51, 0
	s_mov_b32 m0, s68
	s_nop 0
	global_load_lds_dwordx4 v195, s[50:51]
	s_add_u32 m0, s68, 0x2000
	s_nop 0
	global_load_lds_dwordx4 v212, s[50:51]
	s_waitcnt vmcnt(8)
	s_waitcnt lgkmcnt(0)
	s_setprio 1
	s_barrier
	v_mfma_f32_16x16x32_bf16 v[126:129], v[130:133], v[162:165], v[126:129]
	v_mfma_f32_16x16x32_bf16 v[126:129], v[134:137], v[166:169], v[126:129]
	v_mfma_f32_16x16x32_bf16 v[122:125], v[138:141], v[162:165], v[122:125]
	v_mfma_f32_16x16x32_bf16 v[122:125], v[142:145], v[166:169], v[122:125]
	v_mfma_f32_16x16x32_bf16 v[118:121], v[130:133], v[170:173], v[118:121]
	v_mfma_f32_16x16x32_bf16 v[118:121], v[134:137], v[174:177], v[118:121]
	v_mfma_f32_16x16x32_bf16 v[114:117], v[138:141], v[170:173], v[114:117]
	v_mfma_f32_16x16x32_bf16 v[114:117], v[142:145], v[174:177], v[114:117]
	v_mfma_f32_16x16x32_bf16 v[110:113], v[130:133], v[178:181], v[110:113]
	v_mfma_f32_16x16x32_bf16 v[110:113], v[134:137], v[182:185], v[110:113]
	v_mfma_f32_16x16x32_bf16 v[106:109], v[138:141], v[178:181], v[106:109]
	v_mfma_f32_16x16x32_bf16 v[106:109], v[142:145], v[182:185], v[106:109]
	v_mfma_f32_16x16x32_bf16 v[102:105], v[130:133], v[186:189], v[102:105]
	v_mfma_f32_16x16x32_bf16 v[102:105], v[134:137], v[190:193], v[102:105]
	v_mfma_f32_16x16x32_bf16 v[98:101], v[138:141], v[186:189], v[98:101]
	v_mfma_f32_16x16x32_bf16 v[98:101], v[142:145], v[190:193], v[98:101]
	v_mfma_f32_16x16x32_bf16 v[94:97], v[146:149], v[162:165], v[94:97]
	v_mfma_f32_16x16x32_bf16 v[94:97], v[150:153], v[166:169], v[94:97]
	v_mfma_f32_16x16x32_bf16 v[90:93], v[154:157], v[162:165], v[90:93]
	v_mfma_f32_16x16x32_bf16 v[90:93], v[158:161], v[166:169], v[90:93]
	v_mfma_f32_16x16x32_bf16 v[86:89], v[146:149], v[170:173], v[86:89]
	v_mfma_f32_16x16x32_bf16 v[86:89], v[150:153], v[174:177], v[86:89]
	v_mfma_f32_16x16x32_bf16 v[82:85], v[154:157], v[170:173], v[82:85]
	v_mfma_f32_16x16x32_bf16 v[82:85], v[158:161], v[174:177], v[82:85]
	v_mfma_f32_16x16x32_bf16 v[78:81], v[146:149], v[178:181], v[78:81]
	v_mfma_f32_16x16x32_bf16 v[78:81], v[150:153], v[182:185], v[78:81]
	v_mfma_f32_16x16x32_bf16 v[74:77], v[154:157], v[178:181], v[74:77]
	v_mfma_f32_16x16x32_bf16 v[74:77], v[158:161], v[182:185], v[74:77]
	v_mfma_f32_16x16x32_bf16 v[70:73], v[146:149], v[186:189], v[70:73]
	v_mfma_f32_16x16x32_bf16 v[70:73], v[150:153], v[190:193], v[70:73]
	s_setprio 2
	s_barrier
	v_mfma_f32_16x16x32_bf16 v[66:69], v[154:157], v[186:189], v[66:69]
	v_mfma_f32_16x16x32_bf16 v[66:69], v[158:161], v[190:193], v[66:69]
	s_setprio 0
	s_nop 0
	ds_read_b128 v[162:165], v217 offset:49152
	ds_read_b128 v[166:169], v217 offset:50176
	ds_read_b128 v[170:173], v217 offset:51200
	ds_read_b128 v[174:177], v217 offset:52224
	ds_read_b128 v[178:181], v217 offset:53248
	ds_read_b128 v[182:185], v217 offset:54272
	ds_read_b128 v[186:189], v217 offset:55296
	ds_read_b128 v[190:193], v217 offset:56320
	s_mov_b32 m0, s72
	s_nop 0
	global_load_lds_dwordx4 v195, s[54:55]
	s_add_u32 m0, s72, 0x2000
	s_nop 0
	global_load_lds_dwordx4 v212, s[54:55]
	s_add_u32 s12, s12, 0xc000
	s_addc_u32 s13, s13, 0
	s_mov_b32 m0, s74
	s_nop 0
	global_load_lds_dwordx4 v195, s[12:13]
	s_add_u32 m0, s74, 0x2000
	s_nop 0
	global_load_lds_dwordx4 v212, s[12:13]
	s_nop 0
	s_mov_b32 m0, s73
	s_nop 0
	global_load_lds_dwordx4 v195, s[52:53]
	s_add_u32 m0, s73, 0x2000
	s_nop 0
	global_load_lds_dwordx4 v212, s[52:53]
	s_waitcnt vmcnt(8)
	s_waitcnt lgkmcnt(0)
	s_setprio 1
	s_barrier
	v_mfma_f32_16x16x32_bf16 v[62:65], v[130:133], v[162:165], v[62:65]
	v_mfma_f32_16x16x32_bf16 v[62:65], v[134:137], v[166:169], v[62:65]
	v_mfma_f32_16x16x32_bf16 v[58:61], v[138:141], v[162:165], v[58:61]
	v_mfma_f32_16x16x32_bf16 v[58:61], v[142:145], v[166:169], v[58:61]
	v_mfma_f32_16x16x32_bf16 v[54:57], v[130:133], v[170:173], v[54:57]
	v_mfma_f32_16x16x32_bf16 v[54:57], v[134:137], v[174:177], v[54:57]
	v_mfma_f32_16x16x32_bf16 v[50:53], v[138:141], v[170:173], v[50:53]
	v_mfma_f32_16x16x32_bf16 v[50:53], v[142:145], v[174:177], v[50:53]
	v_mfma_f32_16x16x32_bf16 v[46:49], v[130:133], v[178:181], v[46:49]
	v_mfma_f32_16x16x32_bf16 v[46:49], v[134:137], v[182:185], v[46:49]
	v_mfma_f32_16x16x32_bf16 v[42:45], v[138:141], v[178:181], v[42:45]
	v_mfma_f32_16x16x32_bf16 v[42:45], v[142:145], v[182:185], v[42:45]
	v_mfma_f32_16x16x32_bf16 v[38:41], v[130:133], v[186:189], v[38:41]
	v_mfma_f32_16x16x32_bf16 v[38:41], v[134:137], v[190:193], v[38:41]
	v_mfma_f32_16x16x32_bf16 v[34:37], v[138:141], v[186:189], v[34:37]
	v_mfma_f32_16x16x32_bf16 v[34:37], v[142:145], v[190:193], v[34:37]
	v_mfma_f32_16x16x32_bf16 v[30:33], v[146:149], v[162:165], v[30:33]
	v_mfma_f32_16x16x32_bf16 v[30:33], v[150:153], v[166:169], v[30:33]
	v_mfma_f32_16x16x32_bf16 v[26:29], v[154:157], v[162:165], v[26:29]
	v_mfma_f32_16x16x32_bf16 v[26:29], v[158:161], v[166:169], v[26:29]
	v_mfma_f32_16x16x32_bf16 v[22:25], v[146:149], v[170:173], v[22:25]
	v_mfma_f32_16x16x32_bf16 v[22:25], v[150:153], v[174:177], v[22:25]
	v_mfma_f32_16x16x32_bf16 v[18:21], v[154:157], v[170:173], v[18:21]
	v_mfma_f32_16x16x32_bf16 v[18:21], v[158:161], v[174:177], v[18:21]
	v_mfma_f32_16x16x32_bf16 v[14:17], v[146:149], v[178:181], v[14:17]
	v_mfma_f32_16x16x32_bf16 v[14:17], v[150:153], v[182:185], v[14:17]
	v_mfma_f32_16x16x32_bf16 v[10:13], v[154:157], v[178:181], v[10:13]
	v_mfma_f32_16x16x32_bf16 v[10:13], v[158:161], v[182:185], v[10:13]
	v_mfma_f32_16x16x32_bf16 v[6:9], v[146:149], v[186:189], v[6:9]
	v_mfma_f32_16x16x32_bf16 v[6:9], v[150:153], v[190:193], v[6:9]
	s_setprio 2
	s_barrier
	v_mfma_f32_16x16x32_bf16 v[2:5], v[154:157], v[186:189], v[2:5]
	v_mfma_f32_16x16x32_bf16 v[2:5], v[158:161], v[190:193], v[2:5]
	s_setprio 0
	s_nop 0
	s_cmp_gt_u32 s58, 13
	s_cbranch_scc1 .LBB0_1523
	v_mov_b32_e32 v130, v198
	s_mov_b32 s58, s26
	s_branch .LBB0_1498

.LBB0_1712:
	s_add_u32 s52, s48, 0x10000
	s_addc_u32 s53, s49, 0
	s_and_b64 s[48:49], s[46:47], exec
	s_cselect_b32 s49, s53, s25
	s_cselect_b32 s48, s52, s75
	s_add_u32 s13, s16, s13
	s_addc_u32 s52, s17, 0
	s_add_u32 s13, s13, 0x10000
	s_waitcnt vmcnt(8)
	s_addc_u32 s52, s52, 0
	s_waitcnt lgkmcnt(0)
	s_and_b64 s[46:47], s[46:47], exec
	s_cselect_b32 s47, s52, s27
	s_cselect_b32 s46, s13, s76
	s_setprio 1
	s_barrier
	v_mfma_f32_16x16x32_bf16 v[126:129], v[146:149], v[186:189], v[126:129]
	v_mfma_f32_16x16x32_bf16 v[126:129], v[150:153], v[190:193], v[126:129]
	v_mfma_f32_16x16x32_bf16 v[122:125], v[154:157], v[186:189], v[122:125]
	v_mfma_f32_16x16x32_bf16 v[122:125], v[158:161], v[190:193], v[122:125]
	v_mfma_f32_16x16x32_bf16 v[118:121], v[146:149], v[178:181], v[118:121]
	v_mfma_f32_16x16x32_bf16 v[118:121], v[150:153], v[182:185], v[118:121]
	v_mfma_f32_16x16x32_bf16 v[114:117], v[154:157], v[178:181], v[114:117]
	v_mfma_f32_16x16x32_bf16 v[114:117], v[158:161], v[182:185], v[114:117]
	v_mfma_f32_16x16x32_bf16 v[110:113], v[146:149], v[170:173], v[110:113]
	v_mfma_f32_16x16x32_bf16 v[110:113], v[150:153], v[174:177], v[110:113]
	v_mfma_f32_16x16x32_bf16 v[106:109], v[154:157], v[170:173], v[106:109]
	v_mfma_f32_16x16x32_bf16 v[106:109], v[158:161], v[174:177], v[106:109]
	v_mfma_f32_16x16x32_bf16 v[102:105], v[146:149], v[162:165], v[102:105]
	v_mfma_f32_16x16x32_bf16 v[102:105], v[150:153], v[166:169], v[102:105]
	v_mfma_f32_16x16x32_bf16 v[98:101], v[154:157], v[162:165], v[98:101]
	v_mfma_f32_16x16x32_bf16 v[98:101], v[158:161], v[166:169], v[98:101]
	v_mfma_f32_16x16x32_bf16 v[94:97], v[130:133], v[186:189], v[94:97]
	v_mfma_f32_16x16x32_bf16 v[94:97], v[134:137], v[190:193], v[94:97]
	v_mfma_f32_16x16x32_bf16 v[90:93], v[138:141], v[186:189], v[90:93]
	v_mfma_f32_16x16x32_bf16 v[90:93], v[142:145], v[190:193], v[90:93]
	v_mfma_f32_16x16x32_bf16 v[86:89], v[130:133], v[178:181], v[86:89]
	v_mfma_f32_16x16x32_bf16 v[86:89], v[134:137], v[182:185], v[86:89]
	v_mfma_f32_16x16x32_bf16 v[82:85], v[138:141], v[178:181], v[82:85]
	v_mfma_f32_16x16x32_bf16 v[82:85], v[142:145], v[182:185], v[82:85]
	v_mfma_f32_16x16x32_bf16 v[78:81], v[130:133], v[170:173], v[78:81]
	v_mfma_f32_16x16x32_bf16 v[78:81], v[134:137], v[174:177], v[78:81]
	v_mfma_f32_16x16x32_bf16 v[74:77], v[138:141], v[170:173], v[74:77]
	v_mfma_f32_16x16x32_bf16 v[74:77], v[142:145], v[174:177], v[74:77]
	v_mfma_f32_16x16x32_bf16 v[70:73], v[130:133], v[162:165], v[70:73]
	v_mfma_f32_16x16x32_bf16 v[70:73], v[134:137], v[166:169], v[70:73]
	s_setprio 2
	s_barrier
	v_mfma_f32_16x16x32_bf16 v[66:69], v[138:141], v[162:165], v[66:69]
	v_mfma_f32_16x16x32_bf16 v[66:69], v[142:145], v[166:169], v[66:69]
	s_setprio 0
	s_nop 0
	ds_read_b128 v[186:189], v209 offset:16384
	ds_read_b128 v[190:193], v209 offset:17408
	ds_read_b128 v[178:181], v209 offset:18432
	ds_read_b128 v[182:185], v209 offset:19456
	ds_read_b128 v[170:173], v209 offset:20480
	ds_read_b128 v[174:177], v209 offset:21504
	ds_read_b128 v[162:165], v209 offset:22528
	ds_read_b128 v[166:169], v209 offset:23552
	s_mov_b32 m0, s58
	s_nop 0
	global_load_lds_dwordx4 v195, s[46:47]
	s_add_u32 m0, s58, 0x2000
	s_nop 0
	global_load_lds_dwordx4 v203, s[46:47]
	s_add_u32 s52, s46, 0x4000
	s_addc_u32 s53, s47, 0
	s_mov_b32 m0, s59
	s_nop 0
	global_load_lds_dwordx4 v195, s[52:53]
	s_add_u32 m0, s59, 0x2000
	s_nop 0
	global_load_lds_dwordx4 v203, s[52:53]
	s_andn2_b64 vcc, exec, s[50:51]
	s_mov_b32 m0, s11
	s_nop 0
	global_load_lds_dwordx4 v195, s[48:49]
	s_add_u32 m0, s11, 0x2000
	s_nop 0
	global_load_lds_dwordx4 v203, s[48:49]
	s_cbranch_vccnz .LBB0_1714
	v_mov_b32_e32 v2, 0
	v_mov_b32_e32 v3, v2
	v_mov_b32_e32 v4, v2
	v_mov_b32_e32 v5, v2
	v_mov_b32_e32 v6, v2
	v_mov_b32_e32 v7, v2
	v_mov_b32_e32 v8, v2
	v_mov_b32_e32 v9, v2
	v_mov_b32_e32 v10, v2
	v_mov_b32_e32 v11, v2
	v_mov_b32_e32 v12, v2
	v_mov_b32_e32 v13, v2
	v_mov_b32_e32 v14, v2
	v_mov_b32_e32 v15, v2
	v_mov_b32_e32 v16, v2
	v_mov_b32_e32 v17, v2
	v_mov_b32_e32 v18, v2
	v_mov_b32_e32 v19, v2
	v_mov_b32_e32 v20, v2
	v_mov_b32_e32 v21, v2
	v_mov_b32_e32 v22, v2
	v_mov_b32_e32 v23, v2
	v_mov_b32_e32 v24, v2
	v_mov_b32_e32 v25, v2
	v_mov_b32_e32 v26, v2
	v_mov_b32_e32 v27, v2
	v_mov_b32_e32 v28, v2
	v_mov_b32_e32 v29, v2
	v_mov_b32_e32 v30, v2
	v_mov_b32_e32 v31, v2
	v_mov_b32_e32 v32, v2
	v_mov_b32_e32 v33, v2
	v_mov_b32_e32 v34, v2
	v_mov_b32_e32 v35, v2
	v_mov_b32_e32 v36, v2
	v_mov_b32_e32 v37, v2
	v_mov_b32_e32 v38, v2
	v_mov_b32_e32 v39, v2
	v_mov_b32_e32 v40, v2
	v_mov_b32_e32 v41, v2
	v_mov_b32_e32 v42, v2
	v_mov_b32_e32 v43, v2
	v_mov_b32_e32 v44, v2
	v_mov_b32_e32 v45, v2
	v_mov_b32_e32 v46, v2
	v_mov_b32_e32 v47, v2
	v_mov_b32_e32 v48, v2
	v_mov_b32_e32 v49, v2
	v_mov_b32_e32 v50, v2
	v_mov_b32_e32 v51, v2
	v_mov_b32_e32 v52, v2
	v_mov_b32_e32 v53, v2
	v_mov_b32_e32 v54, v2
	v_mov_b32_e32 v55, v2
	v_mov_b32_e32 v56, v2
	v_mov_b32_e32 v57, v2
	v_mov_b32_e32 v58, v2
	v_mov_b32_e32 v59, v2
	v_mov_b32_e32 v60, v2
	v_mov_b32_e32 v61, v2
	v_mov_b32_e32 v62, v2
	v_mov_b32_e32 v63, v2
	v_mov_b32_e32 v64, v2
	v_mov_b32_e32 v65, v2
.LBB0_1714:
	s_waitcnt vmcnt(8)
	s_add_u32 s50, s48, 0x8000
	s_waitcnt lgkmcnt(0)
	s_addc_u32 s51, s49, 0
	s_add_u32 s52, s46, 0x8000
	s_addc_u32 s53, s47, 0
	s_setprio 1
	s_barrier
	v_mfma_f32_16x16x32_bf16 v[62:65], v[146:149], v[186:189], v[62:65]
	v_mfma_f32_16x16x32_bf16 v[62:65], v[150:153], v[190:193], v[62:65]
	v_mfma_f32_16x16x32_bf16 v[58:61], v[154:157], v[186:189], v[58:61]
	v_mfma_f32_16x16x32_bf16 v[58:61], v[158:161], v[190:193], v[58:61]
	v_mfma_f32_16x16x32_bf16 v[54:57], v[146:149], v[178:181], v[54:57]
	v_mfma_f32_16x16x32_bf16 v[54:57], v[150:153], v[182:185], v[54:57]
	v_mfma_f32_16x16x32_bf16 v[50:53], v[154:157], v[178:181], v[50:53]
	v_mfma_f32_16x16x32_bf16 v[50:53], v[158:161], v[182:185], v[50:53]
	v_mfma_f32_16x16x32_bf16 v[46:49], v[146:149], v[170:173], v[46:49]
	v_mfma_f32_16x16x32_bf16 v[46:49], v[150:153], v[174:177], v[46:49]
	v_mfma_f32_16x16x32_bf16 v[42:45], v[154:157], v[170:173], v[42:45]
	v_mfma_f32_16x16x32_bf16 v[42:45], v[158:161], v[174:177], v[42:45]
	v_mfma_f32_16x16x32_bf16 v[38:41], v[146:149], v[162:165], v[38:41]
	v_mfma_f32_16x16x32_bf16 v[38:41], v[150:153], v[166:169], v[38:41]
	v_mfma_f32_16x16x32_bf16 v[34:37], v[154:157], v[162:165], v[34:37]
	v_mfma_f32_16x16x32_bf16 v[34:37], v[158:161], v[166:169], v[34:37]
	v_mfma_f32_16x16x32_bf16 v[30:33], v[130:133], v[186:189], v[30:33]
	v_mfma_f32_16x16x32_bf16 v[30:33], v[134:137], v[190:193], v[30:33]
	v_mfma_f32_16x16x32_bf16 v[26:29], v[138:141], v[186:189], v[26:29]
	v_mfma_f32_16x16x32_bf16 v[26:29], v[142:145], v[190:193], v[26:29]
	v_mfma_f32_16x16x32_bf16 v[22:25], v[130:133], v[178:181], v[22:25]
	v_mfma_f32_16x16x32_bf16 v[22:25], v[134:137], v[182:185], v[22:25]
	v_mfma_f32_16x16x32_bf16 v[18:21], v[138:141], v[178:181], v[18:21]
	v_mfma_f32_16x16x32_bf16 v[18:21], v[142:145], v[182:185], v[18:21]
	v_mfma_f32_16x16x32_bf16 v[14:17], v[130:133], v[170:173], v[14:17]
	v_mfma_f32_16x16x32_bf16 v[14:17], v[134:137], v[174:177], v[14:17]
	v_mfma_f32_16x16x32_bf16 v[10:13], v[138:141], v[170:173], v[10:13]
	v_mfma_f32_16x16x32_bf16 v[10:13], v[142:145], v[174:177], v[10:13]
	v_mfma_f32_16x16x32_bf16 v[6:9], v[130:133], v[162:165], v[6:9]
	v_mfma_f32_16x16x32_bf16 v[6:9], v[134:137], v[166:169], v[6:9]
	s_setprio 2
	s_barrier
	v_mfma_f32_16x16x32_bf16 v[2:5], v[138:141], v[162:165], v[2:5]
	v_mfma_f32_16x16x32_bf16 v[2:5], v[142:145], v[166:169], v[2:5]
	s_setprio 0
	s_nop 0
	v_add_u32_e32 v142, 0x18000, v208
	v_add_u32_e32 v158, 0x1c000, v208
	ds_read_b128 v[130:133], v142
	ds_read_b128 v[134:137], v142 offset:1024
	ds_read_b128 v[138:141], v142 offset:2048
	ds_read_b128 v[142:145], v142 offset:3072
	ds_read_b128 v[146:149], v158
	ds_read_b128 v[150:153], v158 offset:1024
	ds_read_b128 v[154:157], v158 offset:2048
	ds_read_b128 v[158:161], v158 offset:3072
	ds_read_b128 v[162:165], v209 offset:32768
	ds_read_b128 v[166:169], v209 offset:33792
	ds_read_b128 v[170:173], v209 offset:34816
	ds_read_b128 v[174:177], v209 offset:35840
	ds_read_b128 v[178:181], v209 offset:36864
	ds_read_b128 v[182:185], v209 offset:37888
	ds_read_b128 v[186:189], v209 offset:38912
	ds_read_b128 v[190:193], v209 offset:39936
	s_add_u32 s48, s48, 0x4000
	s_addc_u32 s49, s49, 0
	s_mov_b32 m0, s60
	s_nop 0
	global_load_lds_dwordx4 v195, s[48:49]
	s_add_u32 m0, s60, 0x2000
	s_nop 0
	global_load_lds_dwordx4 v203, s[48:49]
	s_waitcnt vmcnt(8)
	s_waitcnt lgkmcnt(0)
	s_setprio 1
	s_barrier
	v_mfma_f32_16x16x32_bf16 v[126:129], v[130:133], v[162:165], v[126:129]
	v_mfma_f32_16x16x32_bf16 v[126:129], v[134:137], v[166:169], v[126:129]
	v_mfma_f32_16x16x32_bf16 v[122:125], v[138:141], v[162:165], v[122:125]
	v_mfma_f32_16x16x32_bf16 v[122:125], v[142:145], v[166:169], v[122:125]
	v_mfma_f32_16x16x32_bf16 v[118:121], v[130:133], v[170:173], v[118:121]
	v_mfma_f32_16x16x32_bf16 v[118:121], v[134:137], v[174:177], v[118:121]
	v_mfma_f32_16x16x32_bf16 v[114:117], v[138:141], v[170:173], v[114:117]
	v_mfma_f32_16x16x32_bf16 v[114:117], v[142:145], v[174:177], v[114:117]
	v_mfma_f32_16x16x32_bf16 v[110:113], v[130:133], v[178:181], v[110:113]
	v_mfma_f32_16x16x32_bf16 v[110:113], v[134:137], v[182:185], v[110:113]
	v_mfma_f32_16x16x32_bf16 v[106:109], v[138:141], v[178:181], v[106:109]
	v_mfma_f32_16x16x32_bf16 v[106:109], v[142:145], v[182:185], v[106:109]
	v_mfma_f32_16x16x32_bf16 v[102:105], v[130:133], v[186:189], v[102:105]
	v_mfma_f32_16x16x32_bf16 v[102:105], v[134:137], v[190:193], v[102:105]
	v_mfma_f32_16x16x32_bf16 v[98:101], v[138:141], v[186:189], v[98:101]
	v_mfma_f32_16x16x32_bf16 v[98:101], v[142:145], v[190:193], v[98:101]
	v_mfma_f32_16x16x32_bf16 v[94:97], v[146:149], v[162:165], v[94:97]
	v_mfma_f32_16x16x32_bf16 v[94:97], v[150:153], v[166:169], v[94:97]
	v_mfma_f32_16x16x32_bf16 v[90:93], v[154:157], v[162:165], v[90:93]
	v_mfma_f32_16x16x32_bf16 v[90:93], v[158:161], v[166:169], v[90:93]
	v_mfma_f32_16x16x32_bf16 v[86:89], v[146:149], v[170:173], v[86:89]
	v_mfma_f32_16x16x32_bf16 v[86:89], v[150:153], v[174:177], v[86:89]
	v_mfma_f32_16x16x32_bf16 v[82:85], v[154:157], v[170:173], v[82:85]
	v_mfma_f32_16x16x32_bf16 v[82:85], v[158:161], v[174:177], v[82:85]
	v_mfma_f32_16x16x32_bf16 v[78:81], v[146:149], v[178:181], v[78:81]
	v_mfma_f32_16x16x32_bf16 v[78:81], v[150:153], v[182:185], v[78:81]
	v_mfma_f32_16x16x32_bf16 v[74:77], v[154:157], v[178:181], v[74:77]
	v_mfma_f32_16x16x32_bf16 v[74:77], v[158:161], v[182:185], v[74:77]
	v_mfma_f32_16x16x32_bf16 v[70:73], v[146:149], v[186:189], v[70:73]
	v_mfma_f32_16x16x32_bf16 v[70:73], v[150:153], v[190:193], v[70:73]
	s_setprio 2
	s_barrier
	v_mfma_f32_16x16x32_bf16 v[66:69], v[154:157], v[186:189], v[66:69]
	v_mfma_f32_16x16x32_bf16 v[66:69], v[158:161], v[190:193], v[66:69]
	s_setprio 0
	s_nop 0
	ds_read_b128 v[162:165], v209 offset:49152
	ds_read_b128 v[166:169], v209 offset:50176
	ds_read_b128 v[170:173], v209 offset:51200
	ds_read_b128 v[174:177], v209 offset:52224
	ds_read_b128 v[178:181], v209 offset:53248
	ds_read_b128 v[182:185], v209 offset:54272
	ds_read_b128 v[186:189], v209 offset:55296
	ds_read_b128 v[190:193], v209 offset:56320
	s_mov_b32 m0, s64
	s_nop 0
	global_load_lds_dwordx4 v195, s[52:53]
	s_add_u32 m0, s64, 0x2000
	s_nop 0
	global_load_lds_dwordx4 v203, s[52:53]
	s_add_u32 s46, s46, 0xc000
	s_addc_u32 s47, s47, 0
	s_mov_b32 m0, s66
	s_nop 0
	global_load_lds_dwordx4 v195, s[46:47]
	s_add_u32 m0, s66, 0x2000
	s_nop 0
	global_load_lds_dwordx4 v203, s[46:47]
	s_nop 0
	s_mov_b32 m0, s65
	s_nop 0
	global_load_lds_dwordx4 v195, s[50:51]
	s_add_u32 m0, s65, 0x2000
	s_nop 0
	global_load_lds_dwordx4 v203, s[50:51]
	s_waitcnt vmcnt(8)
	s_waitcnt lgkmcnt(0)
	s_setprio 1
	s_barrier
	v_mfma_f32_16x16x32_bf16 v[62:65], v[130:133], v[162:165], v[62:65]
	v_mfma_f32_16x16x32_bf16 v[62:65], v[134:137], v[166:169], v[62:65]
	v_mfma_f32_16x16x32_bf16 v[58:61], v[138:141], v[162:165], v[58:61]
	v_mfma_f32_16x16x32_bf16 v[58:61], v[142:145], v[166:169], v[58:61]
	v_mfma_f32_16x16x32_bf16 v[54:57], v[130:133], v[170:173], v[54:57]
	v_mfma_f32_16x16x32_bf16 v[54:57], v[134:137], v[174:177], v[54:57]
	v_mfma_f32_16x16x32_bf16 v[50:53], v[138:141], v[170:173], v[50:53]
	v_mfma_f32_16x16x32_bf16 v[50:53], v[142:145], v[174:177], v[50:53]
	v_mfma_f32_16x16x32_bf16 v[46:49], v[130:133], v[178:181], v[46:49]
	v_mfma_f32_16x16x32_bf16 v[46:49], v[134:137], v[182:185], v[46:49]
	v_mfma_f32_16x16x32_bf16 v[42:45], v[138:141], v[178:181], v[42:45]
	v_mfma_f32_16x16x32_bf16 v[42:45], v[142:145], v[182:185], v[42:45]
	v_mfma_f32_16x16x32_bf16 v[38:41], v[130:133], v[186:189], v[38:41]
	v_mfma_f32_16x16x32_bf16 v[38:41], v[134:137], v[190:193], v[38:41]
	v_mfma_f32_16x16x32_bf16 v[34:37], v[138:141], v[186:189], v[34:37]
	v_mfma_f32_16x16x32_bf16 v[34:37], v[142:145], v[190:193], v[34:37]
	v_mfma_f32_16x16x32_bf16 v[30:33], v[146:149], v[162:165], v[30:33]
	v_mfma_f32_16x16x32_bf16 v[30:33], v[150:153], v[166:169], v[30:33]
	v_mfma_f32_16x16x32_bf16 v[26:29], v[154:157], v[162:165], v[26:29]
	v_mfma_f32_16x16x32_bf16 v[26:29], v[158:161], v[166:169], v[26:29]
	v_mfma_f32_16x16x32_bf16 v[22:25], v[146:149], v[170:173], v[22:25]
	v_mfma_f32_16x16x32_bf16 v[22:25], v[150:153], v[174:177], v[22:25]
	v_mfma_f32_16x16x32_bf16 v[18:21], v[154:157], v[170:173], v[18:21]
	v_mfma_f32_16x16x32_bf16 v[18:21], v[158:161], v[174:177], v[18:21]
	v_mfma_f32_16x16x32_bf16 v[14:17], v[146:149], v[178:181], v[14:17]
	v_mfma_f32_16x16x32_bf16 v[14:17], v[150:153], v[182:185], v[14:17]
	v_mfma_f32_16x16x32_bf16 v[10:13], v[154:157], v[178:181], v[10:13]
	v_mfma_f32_16x16x32_bf16 v[10:13], v[158:161], v[182:185], v[10:13]
	v_mfma_f32_16x16x32_bf16 v[6:9], v[146:149], v[186:189], v[6:9]
	v_mfma_f32_16x16x32_bf16 v[6:9], v[150:153], v[190:193], v[6:9]
	s_setprio 2
	s_barrier
	v_mfma_f32_16x16x32_bf16 v[2:5], v[154:157], v[186:189], v[2:5]
	v_mfma_f32_16x16x32_bf16 v[2:5], v[158:161], v[190:193], v[2:5]
	s_setprio 0
	s_nop 0
	s_add_i32 s13, s77, 2
	s_cmp_gt_u32 s77, 13
	s_cbranch_scc1 .LBB0_1716
	s_mov_b32 s77, s13
	s_branch .LBB0_1693

.LBB0_1919:
	s_or_b64 exec, exec, s[10:11]
	s_add_u32 s50, s16, s6
	ds_read_b128 v[134:137], v201
	ds_read_b128 v[138:141], v201 offset:1024
	ds_read_b128 v[142:145], v201 offset:2048
	ds_read_b128 v[146:149], v201 offset:3072
	ds_read_b128 v[150:153], v202
	ds_read_b128 v[154:157], v202 offset:1024
	ds_read_b128 v[162:165], v202 offset:2048
	ds_read_b128 v[166:169], v202 offset:3072
	s_addc_u32 s51, s17, s7
	s_add_u32 s10, s50, 0x20000
	s_addc_u32 s11, s51, 0
	s_add_u32 s42, s75, s6
	s_addc_u32 s43, s76, s7
	s_cmp_eq_u32 s6, 0x60000
	s_cselect_b32 s46, s29, s10
	s_cselect_b32 s47, s20, s11
	s_cselect_b32 s11, s27, s43
	s_cselect_b32 s10, s48, s42
	s_add_u32 s42, s46, 0x8000
	s_addc_u32 s43, s47, 0
	s_add_u32 s44, s10, 0x8000
	s_addc_u32 s45, s11, 0
	ds_read_b128 v[170:173], v203
	ds_read_b128 v[174:177], v203 offset:1024
	ds_read_b128 v[178:181], v203 offset:2048
	ds_read_b128 v[182:185], v203 offset:3072
	ds_read_b128 v[186:189], v203 offset:4096
	ds_read_b128 v[190:193], v203 offset:5120
	ds_read_b128 v[212:215], v203 offset:6144
	ds_read_b128 v[216:219], v203 offset:7168
	s_add_u32 s50, s50, 0x1c000
	s_addc_u32 s51, s51, 0
	s_mov_b32 m0, s65
	s_nop 0
	global_load_lds_dwordx4 v195, s[50:51]
	s_add_u32 m0, s65, 0x2000
	s_nop 0
	global_load_lds_dwordx4 v197, s[50:51]
	s_waitcnt vmcnt(8)
	s_waitcnt lgkmcnt(0)
	s_setprio 1
	s_barrier
	v_mfma_f32_16x16x32_bf16 v[130:133], v[134:137], v[170:173], v[130:133]
	v_mfma_f32_16x16x32_bf16 v[126:129], v[142:145], v[170:173], v[126:129]
	s_waitcnt lgkmcnt(5)
	v_mfma_f32_16x16x32_bf16 v[110:113], v[134:137], v[178:181], v[110:113]
	v_mfma_f32_16x16x32_bf16 v[106:109], v[142:145], v[178:181], v[106:109]
	s_waitcnt lgkmcnt(3)
	v_mfma_f32_16x16x32_bf16 v[94:97], v[134:137], v[186:189], v[94:97]
	v_mfma_f32_16x16x32_bf16 v[90:93], v[142:145], v[186:189], v[90:93]
	s_waitcnt lgkmcnt(1)
	v_mfma_f32_16x16x32_bf16 v[78:81], v[134:137], v[212:215], v[78:81]
	v_mfma_f32_16x16x32_bf16 v[74:77], v[142:145], v[212:215], v[74:77]
	v_mfma_f32_16x16x32_bf16 v[130:133], v[138:141], v[174:177], v[130:133]
	v_mfma_f32_16x16x32_bf16 v[126:129], v[146:149], v[174:177], v[126:129]
	v_mfma_f32_16x16x32_bf16 v[110:113], v[138:141], v[182:185], v[110:113]
	v_mfma_f32_16x16x32_bf16 v[106:109], v[146:149], v[182:185], v[106:109]
	v_mfma_f32_16x16x32_bf16 v[94:97], v[138:141], v[190:193], v[94:97]
	v_mfma_f32_16x16x32_bf16 v[90:93], v[146:149], v[190:193], v[90:93]
	s_waitcnt lgkmcnt(0)
	v_mfma_f32_16x16x32_bf16 v[78:81], v[138:141], v[216:219], v[78:81]
	v_mfma_f32_16x16x32_bf16 v[74:77], v[146:149], v[216:219], v[74:77]
	s_setprio 0
	s_setprio 1
	v_mfma_f32_16x16x32_bf16 v[122:125], v[150:153], v[170:173], v[122:125]
	v_mfma_f32_16x16x32_bf16 v[116:119], v[162:165], v[170:173], v[118:121]
	v_mfma_f32_16x16x32_bf16 v[102:105], v[150:153], v[178:181], v[102:105]
	v_mfma_f32_16x16x32_bf16 v[98:101], v[162:165], v[178:181], v[98:101]
	v_mfma_f32_16x16x32_bf16 v[86:89], v[150:153], v[186:189], v[86:89]
	v_mfma_f32_16x16x32_bf16 v[82:85], v[162:165], v[186:189], v[82:85]
	v_mfma_f32_16x16x32_bf16 v[70:73], v[150:153], v[212:215], v[70:73]
	v_mfma_f32_16x16x32_bf16 v[66:69], v[162:165], v[212:215], v[66:69]
	v_mfma_f32_16x16x32_bf16 v[122:125], v[154:157], v[174:177], v[122:125]
	v_mfma_f32_16x16x32_bf16 v[116:119], v[166:169], v[174:177], v[116:119]
	v_mfma_f32_16x16x32_bf16 v[102:105], v[154:157], v[182:185], v[102:105]
	v_mfma_f32_16x16x32_bf16 v[98:101], v[166:169], v[182:185], v[98:101]
	v_mfma_f32_16x16x32_bf16 v[86:89], v[154:157], v[190:193], v[86:89]
	v_mfma_f32_16x16x32_bf16 v[82:85], v[166:169], v[190:193], v[82:85]
	s_setprio 2
	s_barrier
	v_mfma_f32_16x16x32_bf16 v[70:73], v[154:157], v[216:219], v[70:73]
	v_mfma_f32_16x16x32_bf16 v[66:69], v[166:169], v[216:219], v[66:69]
	s_setprio 0
	s_nop 0
	ds_read_b128 v[170:173], v203 offset:16384
	ds_read_b128 v[174:177], v203 offset:17408
	ds_read_b128 v[178:181], v203 offset:18432
	ds_read_b128 v[182:185], v203 offset:19456
	ds_read_b128 v[186:189], v203 offset:20480
	ds_read_b128 v[190:193], v203 offset:21504
	ds_read_b128 v[212:215], v203 offset:22528
	ds_read_b128 v[216:219], v203 offset:23552
	s_mov_b32 m0, s13
	s_nop 0
	global_load_lds_dwordx4 v195, s[10:11]
	s_add_u32 m0, s13, 0x2000
	s_nop 0
	global_load_lds_dwordx4 v197, s[10:11]
	s_add_u32 s50, s10, 0x4000
	s_addc_u32 s51, s11, 0
	s_mov_b32 m0, s57
	s_nop 0
	global_load_lds_dwordx4 v195, s[50:51]
	s_add_u32 m0, s57, 0x2000
	s_nop 0
	global_load_lds_dwordx4 v197, s[50:51]
	s_nop 0
	s_mov_b32 m0, s56
	s_nop 0
	global_load_lds_dwordx4 v195, s[46:47]
	s_add_u32 m0, s56, 0x2000
	s_nop 0
	global_load_lds_dwordx4 v197, s[46:47]
	s_waitcnt vmcnt(8)
	s_waitcnt lgkmcnt(0)
	s_setprio 1
	s_barrier
	v_mfma_f32_16x16x32_bf16 v[62:65], v[134:137], v[170:173], v[62:65]
	v_mfma_f32_16x16x32_bf16 v[62:65], v[138:141], v[174:177], v[62:65]
	v_mfma_f32_16x16x32_bf16 v[58:61], v[142:145], v[170:173], v[58:61]
	v_mfma_f32_16x16x32_bf16 v[58:61], v[146:149], v[174:177], v[58:61]
	v_mfma_f32_16x16x32_bf16 v[46:49], v[134:137], v[178:181], v[46:49]
	v_mfma_f32_16x16x32_bf16 v[46:49], v[138:141], v[182:185], v[46:49]
	v_mfma_f32_16x16x32_bf16 v[42:45], v[142:145], v[178:181], v[42:45]
	v_mfma_f32_16x16x32_bf16 v[42:45], v[146:149], v[182:185], v[42:45]
	v_mfma_f32_16x16x32_bf16 v[30:33], v[134:137], v[186:189], v[30:33]
	v_mfma_f32_16x16x32_bf16 v[30:33], v[138:141], v[190:193], v[30:33]
	v_mfma_f32_16x16x32_bf16 v[26:29], v[142:145], v[186:189], v[26:29]
	v_mfma_f32_16x16x32_bf16 v[26:29], v[146:149], v[190:193], v[26:29]
	v_mfma_f32_16x16x32_bf16 v[14:17], v[134:137], v[212:215], v[14:17]
	v_mfma_f32_16x16x32_bf16 v[14:17], v[138:141], v[216:219], v[14:17]
	v_mfma_f32_16x16x32_bf16 v[10:13], v[142:145], v[212:215], v[10:13]
	v_mfma_f32_16x16x32_bf16 v[10:13], v[146:149], v[216:219], v[10:13]
	v_mfma_f32_16x16x32_bf16 v[54:57], v[150:153], v[170:173], v[54:57]
	v_mfma_f32_16x16x32_bf16 v[54:57], v[154:157], v[174:177], v[54:57]
	v_mfma_f32_16x16x32_bf16 v[50:53], v[162:165], v[170:173], v[50:53]
	v_mfma_f32_16x16x32_bf16 v[50:53], v[166:169], v[174:177], v[50:53]
	v_mfma_f32_16x16x32_bf16 v[38:41], v[150:153], v[178:181], v[38:41]
	v_mfma_f32_16x16x32_bf16 v[38:41], v[154:157], v[182:185], v[38:41]
	v_mfma_f32_16x16x32_bf16 v[34:37], v[162:165], v[178:181], v[34:37]
	v_mfma_f32_16x16x32_bf16 v[34:37], v[166:169], v[182:185], v[34:37]
	v_mfma_f32_16x16x32_bf16 v[22:25], v[150:153], v[186:189], v[22:25]
	v_mfma_f32_16x16x32_bf16 v[22:25], v[154:157], v[190:193], v[22:25]
	v_mfma_f32_16x16x32_bf16 v[18:21], v[162:165], v[186:189], v[18:21]
	v_mfma_f32_16x16x32_bf16 v[18:21], v[166:169], v[190:193], v[18:21]
	v_mfma_f32_16x16x32_bf16 v[6:9], v[150:153], v[212:215], v[6:9]
	v_mfma_f32_16x16x32_bf16 v[6:9], v[154:157], v[216:219], v[6:9]
	s_setprio 2
	s_barrier
	v_mfma_f32_16x16x32_bf16 v[2:5], v[162:165], v[212:215], v[2:5]
	v_mfma_f32_16x16x32_bf16 v[2:5], v[166:169], v[216:219], v[2:5]
	s_setprio 0
	s_nop 0
	ds_read_b128 v[134:137], v204
	ds_read_b128 v[138:141], v204 offset:1024
	ds_read_b128 v[142:145], v204 offset:2048
	ds_read_b128 v[146:149], v204 offset:3072
	ds_read_b128 v[150:153], v205
	ds_read_b128 v[154:157], v205 offset:1024
	ds_read_b128 v[162:165], v205 offset:2048
	ds_read_b128 v[166:169], v205 offset:3072
	ds_read_b128 v[170:173], v203 offset:32768
	ds_read_b128 v[174:177], v203 offset:33792
	ds_read_b128 v[178:181], v203 offset:34816
	ds_read_b128 v[182:185], v203 offset:35840
	ds_read_b128 v[186:189], v203 offset:36864
	ds_read_b128 v[190:193], v203 offset:37888
	ds_read_b128 v[212:215], v203 offset:38912
	ds_read_b128 v[216:219], v203 offset:39936
	s_add_u32 s46, s46, 0x4000
	s_addc_u32 s47, s47, 0
	s_mov_b32 m0, s58
	s_nop 0
	global_load_lds_dwordx4 v195, s[46:47]
	s_add_u32 m0, s58, 0x2000
	s_nop 0
	global_load_lds_dwordx4 v197, s[46:47]
	s_waitcnt vmcnt(8)
	s_waitcnt lgkmcnt(0)
	s_setprio 1
	s_barrier
	v_mfma_f32_16x16x32_bf16 v[130:133], v[134:137], v[170:173], v[130:133]
	v_mfma_f32_16x16x32_bf16 v[126:129], v[142:145], v[170:173], v[126:129]
	s_waitcnt lgkmcnt(5)
	v_mfma_f32_16x16x32_bf16 v[110:113], v[134:137], v[178:181], v[110:113]
	v_mfma_f32_16x16x32_bf16 v[106:109], v[142:145], v[178:181], v[106:109]
	s_waitcnt lgkmcnt(3)
	v_mfma_f32_16x16x32_bf16 v[94:97], v[134:137], v[186:189], v[94:97]
	v_mfma_f32_16x16x32_bf16 v[90:93], v[142:145], v[186:189], v[90:93]
	s_waitcnt lgkmcnt(1)
	v_mfma_f32_16x16x32_bf16 v[78:81], v[134:137], v[212:215], v[78:81]
	v_mfma_f32_16x16x32_bf16 v[74:77], v[142:145], v[212:215], v[74:77]
	v_mfma_f32_16x16x32_bf16 v[130:133], v[138:141], v[174:177], v[130:133]
	v_mfma_f32_16x16x32_bf16 v[126:129], v[146:149], v[174:177], v[126:129]
	v_mfma_f32_16x16x32_bf16 v[110:113], v[138:141], v[182:185], v[110:113]
	v_mfma_f32_16x16x32_bf16 v[106:109], v[146:149], v[182:185], v[106:109]
	v_mfma_f32_16x16x32_bf16 v[94:97], v[138:141], v[190:193], v[94:97]
	v_mfma_f32_16x16x32_bf16 v[90:93], v[146:149], v[190:193], v[90:93]
	s_waitcnt lgkmcnt(0)
	v_mfma_f32_16x16x32_bf16 v[78:81], v[138:141], v[216:219], v[78:81]
	v_mfma_f32_16x16x32_bf16 v[74:77], v[146:149], v[216:219], v[74:77]
	s_setprio 0
	s_setprio 1
	v_mfma_f32_16x16x32_bf16 v[120:123], v[150:153], v[170:173], v[122:125]
	v_mfma_f32_16x16x32_bf16 v[116:119], v[162:165], v[170:173], v[116:119]
	v_mfma_f32_16x16x32_bf16 v[102:105], v[150:153], v[178:181], v[102:105]
	v_mfma_f32_16x16x32_bf16 v[98:101], v[162:165], v[178:181], v[98:101]
	v_mfma_f32_16x16x32_bf16 v[86:89], v[150:153], v[186:189], v[86:89]
	v_mfma_f32_16x16x32_bf16 v[82:85], v[162:165], v[186:189], v[82:85]
	v_mfma_f32_16x16x32_bf16 v[70:73], v[150:153], v[212:215], v[70:73]
	v_mfma_f32_16x16x32_bf16 v[66:69], v[162:165], v[212:215], v[66:69]
	v_mfma_f32_16x16x32_bf16 v[122:125], v[154:157], v[174:177], v[120:123]
	v_mfma_f32_16x16x32_bf16 v[118:121], v[166:169], v[174:177], v[116:119]
	v_mfma_f32_16x16x32_bf16 v[102:105], v[154:157], v[182:185], v[102:105]
	v_mfma_f32_16x16x32_bf16 v[98:101], v[166:169], v[182:185], v[98:101]
	v_mfma_f32_16x16x32_bf16 v[86:89], v[154:157], v[190:193], v[86:89]
	v_mfma_f32_16x16x32_bf16 v[82:85], v[166:169], v[190:193], v[82:85]
	s_setprio 2
	s_barrier
	v_mfma_f32_16x16x32_bf16 v[70:73], v[154:157], v[216:219], v[70:73]
	v_mfma_f32_16x16x32_bf16 v[66:69], v[166:169], v[216:219], v[66:69]
	s_setprio 0
	s_nop 0
	ds_read_b128 v[170:173], v203 offset:49152
	ds_read_b128 v[174:177], v203 offset:50176
	ds_read_b128 v[178:181], v203 offset:51200
	ds_read_b128 v[182:185], v203 offset:52224
	ds_read_b128 v[186:189], v203 offset:53248
	ds_read_b128 v[190:193], v203 offset:54272
	ds_read_b128 v[212:215], v203 offset:55296
	ds_read_b128 v[216:219], v203 offset:56320
	s_mov_b32 m0, s62
	s_nop 0
	global_load_lds_dwordx4 v195, s[44:45]
	s_add_u32 m0, s62, 0x2000
	s_nop 0
	global_load_lds_dwordx4 v197, s[44:45]
	s_add_u32 s10, s10, 0xc000
	s_addc_u32 s11, s11, 0
	s_mov_b32 m0, s64
	s_nop 0
	global_load_lds_dwordx4 v195, s[10:11]
	s_add_u32 m0, s64, 0x2000
	s_nop 0
	global_load_lds_dwordx4 v197, s[10:11]
	s_nop 0
	s_mov_b32 m0, s63
	s_nop 0
	global_load_lds_dwordx4 v195, s[42:43]
	s_add_u32 m0, s63, 0x2000
	s_nop 0
	global_load_lds_dwordx4 v197, s[42:43]
	s_waitcnt vmcnt(8)
	s_waitcnt lgkmcnt(0)
	s_setprio 1
	s_barrier
	v_mfma_f32_16x16x32_bf16 v[62:65], v[134:137], v[170:173], v[62:65]
	v_mfma_f32_16x16x32_bf16 v[62:65], v[138:141], v[174:177], v[62:65]
	v_mfma_f32_16x16x32_bf16 v[58:61], v[142:145], v[170:173], v[58:61]
	v_mfma_f32_16x16x32_bf16 v[58:61], v[146:149], v[174:177], v[58:61]
	v_mfma_f32_16x16x32_bf16 v[46:49], v[134:137], v[178:181], v[46:49]
	v_mfma_f32_16x16x32_bf16 v[46:49], v[138:141], v[182:185], v[46:49]
	v_mfma_f32_16x16x32_bf16 v[42:45], v[142:145], v[178:181], v[42:45]
	v_mfma_f32_16x16x32_bf16 v[42:45], v[146:149], v[182:185], v[42:45]
	v_mfma_f32_16x16x32_bf16 v[30:33], v[134:137], v[186:189], v[30:33]
	v_mfma_f32_16x16x32_bf16 v[30:33], v[138:141], v[190:193], v[30:33]
	v_mfma_f32_16x16x32_bf16 v[26:29], v[142:145], v[186:189], v[26:29]
	v_mfma_f32_16x16x32_bf16 v[26:29], v[146:149], v[190:193], v[26:29]
	v_mfma_f32_16x16x32_bf16 v[14:17], v[134:137], v[212:215], v[14:17]
	v_mfma_f32_16x16x32_bf16 v[14:17], v[138:141], v[216:219], v[14:17]
	v_mfma_f32_16x16x32_bf16 v[10:13], v[142:145], v[212:215], v[10:13]
	v_mfma_f32_16x16x32_bf16 v[10:13], v[146:149], v[216:219], v[10:13]
	v_mfma_f32_16x16x32_bf16 v[54:57], v[150:153], v[170:173], v[54:57]
	v_mfma_f32_16x16x32_bf16 v[54:57], v[154:157], v[174:177], v[54:57]
	v_mfma_f32_16x16x32_bf16 v[50:53], v[162:165], v[170:173], v[50:53]
	v_mfma_f32_16x16x32_bf16 v[50:53], v[166:169], v[174:177], v[50:53]
	v_mfma_f32_16x16x32_bf16 v[38:41], v[150:153], v[178:181], v[38:41]
	v_mfma_f32_16x16x32_bf16 v[38:41], v[154:157], v[182:185], v[38:41]
	v_mfma_f32_16x16x32_bf16 v[34:37], v[162:165], v[178:181], v[34:37]
	v_mfma_f32_16x16x32_bf16 v[34:37], v[166:169], v[182:185], v[34:37]
	v_mfma_f32_16x16x32_bf16 v[22:25], v[150:153], v[186:189], v[22:25]
	v_mfma_f32_16x16x32_bf16 v[22:25], v[154:157], v[190:193], v[22:25]
	v_mfma_f32_16x16x32_bf16 v[18:21], v[162:165], v[186:189], v[18:21]
	v_mfma_f32_16x16x32_bf16 v[18:21], v[166:169], v[190:193], v[18:21]
	v_mfma_f32_16x16x32_bf16 v[6:9], v[150:153], v[212:215], v[6:9]
	v_mfma_f32_16x16x32_bf16 v[6:9], v[154:157], v[216:219], v[6:9]
	s_setprio 2
	s_barrier
	v_mfma_f32_16x16x32_bf16 v[2:5], v[162:165], v[212:215], v[2:5]
	v_mfma_f32_16x16x32_bf16 v[2:5], v[166:169], v[216:219], v[2:5]
	s_setprio 0
	s_nop 0
	s_add_i32 s49, s49, 2
	s_add_u32 s6, s6, 0x10000
	s_addc_u32 s7, s7, 0
	s_cmp_gt_u32 s49, 13
	v_mov_b32_e32 v115, v114
	s_cbranch_scc1 .LBB0_1922

.LBB0_2120:
	s_add_u32 s56, s52, 0x10000
	s_addc_u32 s57, s53, 0
	s_and_b64 s[52:53], s[50:51], exec
	s_cselect_b32 s53, s57, s43
	s_cselect_b32 s52, s56, s88
	s_add_u32 s15, s18, s15
	s_addc_u32 s56, s19, 0
	s_add_u32 s15, s15, 0x10000
	s_waitcnt vmcnt(8)
	s_addc_u32 s56, s56, 0
	s_waitcnt lgkmcnt(0)
	s_and_b64 s[50:51], s[50:51], exec
	s_cselect_b32 s51, s56, s41
	s_cselect_b32 s50, s15, s89
	s_setprio 1
	s_barrier
	v_mfma_f32_16x16x32_bf16 v[126:129], v[146:149], v[186:189], v[126:129]
	v_mfma_f32_16x16x32_bf16 v[126:129], v[150:153], v[190:193], v[126:129]
	v_mfma_f32_16x16x32_bf16 v[122:125], v[154:157], v[186:189], v[122:125]
	v_mfma_f32_16x16x32_bf16 v[122:125], v[158:161], v[190:193], v[122:125]
	v_mfma_f32_16x16x32_bf16 v[118:121], v[146:149], v[178:181], v[118:121]
	v_mfma_f32_16x16x32_bf16 v[118:121], v[150:153], v[182:185], v[118:121]
	v_mfma_f32_16x16x32_bf16 v[114:117], v[154:157], v[178:181], v[114:117]
	v_mfma_f32_16x16x32_bf16 v[114:117], v[158:161], v[182:185], v[114:117]
	v_mfma_f32_16x16x32_bf16 v[110:113], v[146:149], v[170:173], v[110:113]
	v_mfma_f32_16x16x32_bf16 v[110:113], v[150:153], v[174:177], v[110:113]
	v_mfma_f32_16x16x32_bf16 v[106:109], v[154:157], v[170:173], v[106:109]
	v_mfma_f32_16x16x32_bf16 v[106:109], v[158:161], v[174:177], v[106:109]
	v_mfma_f32_16x16x32_bf16 v[102:105], v[146:149], v[162:165], v[102:105]
	v_mfma_f32_16x16x32_bf16 v[102:105], v[150:153], v[166:169], v[102:105]
	v_mfma_f32_16x16x32_bf16 v[98:101], v[154:157], v[162:165], v[98:101]
	v_mfma_f32_16x16x32_bf16 v[98:101], v[158:161], v[166:169], v[98:101]
	v_mfma_f32_16x16x32_bf16 v[94:97], v[130:133], v[186:189], v[94:97]
	v_mfma_f32_16x16x32_bf16 v[94:97], v[134:137], v[190:193], v[94:97]
	v_mfma_f32_16x16x32_bf16 v[90:93], v[138:141], v[186:189], v[90:93]
	v_mfma_f32_16x16x32_bf16 v[90:93], v[142:145], v[190:193], v[90:93]
	v_mfma_f32_16x16x32_bf16 v[86:89], v[130:133], v[178:181], v[86:89]
	v_mfma_f32_16x16x32_bf16 v[86:89], v[134:137], v[182:185], v[86:89]
	v_mfma_f32_16x16x32_bf16 v[82:85], v[138:141], v[178:181], v[82:85]
	v_mfma_f32_16x16x32_bf16 v[82:85], v[142:145], v[182:185], v[82:85]
	v_mfma_f32_16x16x32_bf16 v[78:81], v[130:133], v[170:173], v[78:81]
	v_mfma_f32_16x16x32_bf16 v[78:81], v[134:137], v[174:177], v[78:81]
	v_mfma_f32_16x16x32_bf16 v[74:77], v[138:141], v[170:173], v[74:77]
	v_mfma_f32_16x16x32_bf16 v[74:77], v[142:145], v[174:177], v[74:77]
	v_mfma_f32_16x16x32_bf16 v[70:73], v[130:133], v[162:165], v[70:73]
	v_mfma_f32_16x16x32_bf16 v[70:73], v[134:137], v[166:169], v[70:73]
	s_setprio 2
	s_barrier
	v_mfma_f32_16x16x32_bf16 v[66:69], v[138:141], v[162:165], v[66:69]
	v_mfma_f32_16x16x32_bf16 v[66:69], v[142:145], v[166:169], v[66:69]
	s_setprio 0
	s_nop 0
	ds_read_b128 v[186:189], v207 offset:16384
	ds_read_b128 v[190:193], v207 offset:17408
	ds_read_b128 v[178:181], v207 offset:18432
	ds_read_b128 v[182:185], v207 offset:19456
	ds_read_b128 v[170:173], v207 offset:20480
	ds_read_b128 v[174:177], v207 offset:21504
	ds_read_b128 v[162:165], v207 offset:22528
	ds_read_b128 v[166:169], v207 offset:23552
	s_mov_b32 m0, s62
	s_nop 0
	global_load_lds_dwordx4 v195, s[50:51]
	s_add_u32 m0, s62, 0x2000
	s_nop 0
	global_load_lds_dwordx4 v197, s[50:51]
	s_add_u32 s56, s50, 0x4000
	s_addc_u32 s57, s51, 0
	s_mov_b32 m0, s63
	s_nop 0
	global_load_lds_dwordx4 v195, s[56:57]
	s_add_u32 m0, s63, 0x2000
	s_nop 0
	global_load_lds_dwordx4 v197, s[56:57]
	s_andn2_b64 vcc, exec, s[54:55]
	s_mov_b32 m0, s61
	s_nop 0
	global_load_lds_dwordx4 v195, s[52:53]
	s_add_u32 m0, s61, 0x2000
	s_nop 0
	global_load_lds_dwordx4 v197, s[52:53]
	s_cbranch_vccnz .LBB0_2122
	v_mov_b32_e32 v2, 0
	v_mov_b32_e32 v3, v2
	v_mov_b32_e32 v4, v2
	v_mov_b32_e32 v5, v2
	v_mov_b32_e32 v6, v2
	v_mov_b32_e32 v7, v2
	v_mov_b32_e32 v8, v2
	v_mov_b32_e32 v9, v2
	v_mov_b32_e32 v10, v2
	v_mov_b32_e32 v11, v2
	v_mov_b32_e32 v12, v2
	v_mov_b32_e32 v13, v2
	v_mov_b32_e32 v14, v2
	v_mov_b32_e32 v15, v2
	v_mov_b32_e32 v16, v2
	v_mov_b32_e32 v17, v2
	v_mov_b32_e32 v18, v2
	v_mov_b32_e32 v19, v2
	v_mov_b32_e32 v20, v2
	v_mov_b32_e32 v21, v2
	v_mov_b32_e32 v22, v2
	v_mov_b32_e32 v23, v2
	v_mov_b32_e32 v24, v2
	v_mov_b32_e32 v25, v2
	v_mov_b32_e32 v26, v2
	v_mov_b32_e32 v27, v2
	v_mov_b32_e32 v28, v2
	v_mov_b32_e32 v29, v2
	v_mov_b32_e32 v30, v2
	v_mov_b32_e32 v31, v2
	v_mov_b32_e32 v32, v2
	v_mov_b32_e32 v33, v2
	v_mov_b32_e32 v34, v2
	v_mov_b32_e32 v35, v2
	v_mov_b32_e32 v36, v2
	v_mov_b32_e32 v37, v2
	v_mov_b32_e32 v38, v2
	v_mov_b32_e32 v39, v2
	v_mov_b32_e32 v40, v2
	v_mov_b32_e32 v41, v2
	v_mov_b32_e32 v42, v2
	v_mov_b32_e32 v43, v2
	v_mov_b32_e32 v44, v2
	v_mov_b32_e32 v45, v2
	v_mov_b32_e32 v46, v2
	v_mov_b32_e32 v47, v2
	v_mov_b32_e32 v48, v2
	v_mov_b32_e32 v49, v2
	v_mov_b32_e32 v50, v2
	v_mov_b32_e32 v51, v2
	v_mov_b32_e32 v52, v2
	v_mov_b32_e32 v53, v2
	v_mov_b32_e32 v54, v2
	v_mov_b32_e32 v55, v2
	v_mov_b32_e32 v56, v2
	v_mov_b32_e32 v57, v2
	v_mov_b32_e32 v58, v2
	v_mov_b32_e32 v59, v2
	v_mov_b32_e32 v60, v2
	v_mov_b32_e32 v61, v2
	v_mov_b32_e32 v62, v2
	v_mov_b32_e32 v63, v2
	v_mov_b32_e32 v64, v2
	v_mov_b32_e32 v65, v2
.LBB0_2122:
	s_waitcnt vmcnt(8)
	s_add_u32 s54, s52, 0x8000
	s_waitcnt lgkmcnt(0)
	s_addc_u32 s55, s53, 0
	s_add_u32 s56, s50, 0x8000
	s_addc_u32 s57, s51, 0
	s_setprio 1
	s_barrier
	v_mfma_f32_16x16x32_bf16 v[62:65], v[146:149], v[186:189], v[62:65]
	v_mfma_f32_16x16x32_bf16 v[62:65], v[150:153], v[190:193], v[62:65]
	v_mfma_f32_16x16x32_bf16 v[58:61], v[154:157], v[186:189], v[58:61]
	v_mfma_f32_16x16x32_bf16 v[58:61], v[158:161], v[190:193], v[58:61]
	v_mfma_f32_16x16x32_bf16 v[54:57], v[146:149], v[178:181], v[54:57]
	v_mfma_f32_16x16x32_bf16 v[54:57], v[150:153], v[182:185], v[54:57]
	v_mfma_f32_16x16x32_bf16 v[50:53], v[154:157], v[178:181], v[50:53]
	v_mfma_f32_16x16x32_bf16 v[50:53], v[158:161], v[182:185], v[50:53]
	v_mfma_f32_16x16x32_bf16 v[46:49], v[146:149], v[170:173], v[46:49]
	v_mfma_f32_16x16x32_bf16 v[46:49], v[150:153], v[174:177], v[46:49]
	v_mfma_f32_16x16x32_bf16 v[42:45], v[154:157], v[170:173], v[42:45]
	v_mfma_f32_16x16x32_bf16 v[42:45], v[158:161], v[174:177], v[42:45]
	v_mfma_f32_16x16x32_bf16 v[38:41], v[146:149], v[162:165], v[38:41]
	v_mfma_f32_16x16x32_bf16 v[38:41], v[150:153], v[166:169], v[38:41]
	v_mfma_f32_16x16x32_bf16 v[34:37], v[154:157], v[162:165], v[34:37]
	v_mfma_f32_16x16x32_bf16 v[34:37], v[158:161], v[166:169], v[34:37]
	v_mfma_f32_16x16x32_bf16 v[30:33], v[130:133], v[186:189], v[30:33]
	v_mfma_f32_16x16x32_bf16 v[30:33], v[134:137], v[190:193], v[30:33]
	v_mfma_f32_16x16x32_bf16 v[26:29], v[138:141], v[186:189], v[26:29]
	v_mfma_f32_16x16x32_bf16 v[26:29], v[142:145], v[190:193], v[26:29]
	v_mfma_f32_16x16x32_bf16 v[22:25], v[130:133], v[178:181], v[22:25]
	v_mfma_f32_16x16x32_bf16 v[22:25], v[134:137], v[182:185], v[22:25]
	v_mfma_f32_16x16x32_bf16 v[18:21], v[138:141], v[178:181], v[18:21]
	v_mfma_f32_16x16x32_bf16 v[18:21], v[142:145], v[182:185], v[18:21]
	v_mfma_f32_16x16x32_bf16 v[14:17], v[130:133], v[170:173], v[14:17]
	v_mfma_f32_16x16x32_bf16 v[14:17], v[134:137], v[174:177], v[14:17]
	v_mfma_f32_16x16x32_bf16 v[10:13], v[138:141], v[170:173], v[10:13]
	v_mfma_f32_16x16x32_bf16 v[10:13], v[142:145], v[174:177], v[10:13]
	v_mfma_f32_16x16x32_bf16 v[6:9], v[130:133], v[162:165], v[6:9]
	v_mfma_f32_16x16x32_bf16 v[6:9], v[134:137], v[166:169], v[6:9]
	s_setprio 2
	s_barrier
	v_mfma_f32_16x16x32_bf16 v[2:5], v[138:141], v[162:165], v[2:5]
	v_mfma_f32_16x16x32_bf16 v[2:5], v[142:145], v[166:169], v[2:5]
	s_setprio 0
	s_nop 0
	v_add_u32_e32 v142, 0x18000, v206
	v_add_u32_e32 v158, 0x1c000, v206
	ds_read_b128 v[130:133], v142
	ds_read_b128 v[134:137], v142 offset:1024
	ds_read_b128 v[138:141], v142 offset:2048
	ds_read_b128 v[142:145], v142 offset:3072
	ds_read_b128 v[146:149], v158
	ds_read_b128 v[150:153], v158 offset:1024
	ds_read_b128 v[154:157], v158 offset:2048
	ds_read_b128 v[158:161], v158 offset:3072
	ds_read_b128 v[162:165], v207 offset:32768
	ds_read_b128 v[166:169], v207 offset:33792
	ds_read_b128 v[170:173], v207 offset:34816
	ds_read_b128 v[174:177], v207 offset:35840
	ds_read_b128 v[178:181], v207 offset:36864
	ds_read_b128 v[182:185], v207 offset:37888
	ds_read_b128 v[186:189], v207 offset:38912
	ds_read_b128 v[190:193], v207 offset:39936
	s_add_u32 s52, s52, 0x4000
	s_addc_u32 s53, s53, 0
	s_mov_b32 m0, s64
	s_nop 0
	global_load_lds_dwordx4 v195, s[52:53]
	s_add_u32 m0, s64, 0x2000
	s_nop 0
	global_load_lds_dwordx4 v197, s[52:53]
	s_waitcnt vmcnt(8)
	s_waitcnt lgkmcnt(0)
	s_setprio 1
	s_barrier
	v_mfma_f32_16x16x32_bf16 v[126:129], v[130:133], v[162:165], v[126:129]
	v_mfma_f32_16x16x32_bf16 v[126:129], v[134:137], v[166:169], v[126:129]
	v_mfma_f32_16x16x32_bf16 v[122:125], v[138:141], v[162:165], v[122:125]
	v_mfma_f32_16x16x32_bf16 v[122:125], v[142:145], v[166:169], v[122:125]
	v_mfma_f32_16x16x32_bf16 v[118:121], v[130:133], v[170:173], v[118:121]
	v_mfma_f32_16x16x32_bf16 v[118:121], v[134:137], v[174:177], v[118:121]
	v_mfma_f32_16x16x32_bf16 v[114:117], v[138:141], v[170:173], v[114:117]
	v_mfma_f32_16x16x32_bf16 v[114:117], v[142:145], v[174:177], v[114:117]
	v_mfma_f32_16x16x32_bf16 v[110:113], v[130:133], v[178:181], v[110:113]
	v_mfma_f32_16x16x32_bf16 v[110:113], v[134:137], v[182:185], v[110:113]
	v_mfma_f32_16x16x32_bf16 v[106:109], v[138:141], v[178:181], v[106:109]
	v_mfma_f32_16x16x32_bf16 v[106:109], v[142:145], v[182:185], v[106:109]
	v_mfma_f32_16x16x32_bf16 v[102:105], v[130:133], v[186:189], v[102:105]
	v_mfma_f32_16x16x32_bf16 v[102:105], v[134:137], v[190:193], v[102:105]
	v_mfma_f32_16x16x32_bf16 v[98:101], v[138:141], v[186:189], v[98:101]
	v_mfma_f32_16x16x32_bf16 v[98:101], v[142:145], v[190:193], v[98:101]
	v_mfma_f32_16x16x32_bf16 v[94:97], v[146:149], v[162:165], v[94:97]
	v_mfma_f32_16x16x32_bf16 v[94:97], v[150:153], v[166:169], v[94:97]
	v_mfma_f32_16x16x32_bf16 v[90:93], v[154:157], v[162:165], v[90:93]
	v_mfma_f32_16x16x32_bf16 v[90:93], v[158:161], v[166:169], v[90:93]
	v_mfma_f32_16x16x32_bf16 v[86:89], v[146:149], v[170:173], v[86:89]
	v_mfma_f32_16x16x32_bf16 v[86:89], v[150:153], v[174:177], v[86:89]
	v_mfma_f32_16x16x32_bf16 v[82:85], v[154:157], v[170:173], v[82:85]
	v_mfma_f32_16x16x32_bf16 v[82:85], v[158:161], v[174:177], v[82:85]
	v_mfma_f32_16x16x32_bf16 v[78:81], v[146:149], v[178:181], v[78:81]
	v_mfma_f32_16x16x32_bf16 v[78:81], v[150:153], v[182:185], v[78:81]
	v_mfma_f32_16x16x32_bf16 v[74:77], v[154:157], v[178:181], v[74:77]
	v_mfma_f32_16x16x32_bf16 v[74:77], v[158:161], v[182:185], v[74:77]
	v_mfma_f32_16x16x32_bf16 v[70:73], v[146:149], v[186:189], v[70:73]
	v_mfma_f32_16x16x32_bf16 v[70:73], v[150:153], v[190:193], v[70:73]
	s_setprio 2
	s_barrier
	v_mfma_f32_16x16x32_bf16 v[66:69], v[154:157], v[186:189], v[66:69]
	v_mfma_f32_16x16x32_bf16 v[66:69], v[158:161], v[190:193], v[66:69]
	s_setprio 0
	s_nop 0
	ds_read_b128 v[162:165], v207 offset:49152
	ds_read_b128 v[166:169], v207 offset:50176
	ds_read_b128 v[170:173], v207 offset:51200
	ds_read_b128 v[174:177], v207 offset:52224
	ds_read_b128 v[178:181], v207 offset:53248
	ds_read_b128 v[182:185], v207 offset:54272
	ds_read_b128 v[186:189], v207 offset:55296
	ds_read_b128 v[190:193], v207 offset:56320
	s_mov_b32 m0, s70
	s_nop 0
	global_load_lds_dwordx4 v195, s[56:57]
	s_add_u32 m0, s70, 0x2000
	s_nop 0
	global_load_lds_dwordx4 v197, s[56:57]
	s_add_u32 s50, s50, 0xc000
	s_addc_u32 s51, s51, 0
	s_mov_b32 m0, s72
	s_nop 0
	global_load_lds_dwordx4 v195, s[50:51]
	s_add_u32 m0, s72, 0x2000
	s_nop 0
	global_load_lds_dwordx4 v197, s[50:51]
	s_nop 0
	s_mov_b32 m0, s71
	s_nop 0
	global_load_lds_dwordx4 v195, s[54:55]
	s_add_u32 m0, s71, 0x2000
	s_nop 0
	global_load_lds_dwordx4 v197, s[54:55]
	s_waitcnt vmcnt(8)
	s_waitcnt lgkmcnt(0)
	s_setprio 1
	s_barrier
	v_mfma_f32_16x16x32_bf16 v[62:65], v[130:133], v[162:165], v[62:65]
	v_mfma_f32_16x16x32_bf16 v[62:65], v[134:137], v[166:169], v[62:65]
	v_mfma_f32_16x16x32_bf16 v[58:61], v[138:141], v[162:165], v[58:61]
	v_mfma_f32_16x16x32_bf16 v[58:61], v[142:145], v[166:169], v[58:61]
	v_mfma_f32_16x16x32_bf16 v[54:57], v[130:133], v[170:173], v[54:57]
	v_mfma_f32_16x16x32_bf16 v[54:57], v[134:137], v[174:177], v[54:57]
	v_mfma_f32_16x16x32_bf16 v[50:53], v[138:141], v[170:173], v[50:53]
	v_mfma_f32_16x16x32_bf16 v[50:53], v[142:145], v[174:177], v[50:53]
	v_mfma_f32_16x16x32_bf16 v[46:49], v[130:133], v[178:181], v[46:49]
	v_mfma_f32_16x16x32_bf16 v[46:49], v[134:137], v[182:185], v[46:49]
	v_mfma_f32_16x16x32_bf16 v[42:45], v[138:141], v[178:181], v[42:45]
	v_mfma_f32_16x16x32_bf16 v[42:45], v[142:145], v[182:185], v[42:45]
	v_mfma_f32_16x16x32_bf16 v[38:41], v[130:133], v[186:189], v[38:41]
	v_mfma_f32_16x16x32_bf16 v[38:41], v[134:137], v[190:193], v[38:41]
	v_mfma_f32_16x16x32_bf16 v[34:37], v[138:141], v[186:189], v[34:37]
	v_mfma_f32_16x16x32_bf16 v[34:37], v[142:145], v[190:193], v[34:37]
	v_mfma_f32_16x16x32_bf16 v[30:33], v[146:149], v[162:165], v[30:33]
	v_mfma_f32_16x16x32_bf16 v[30:33], v[150:153], v[166:169], v[30:33]
	v_mfma_f32_16x16x32_bf16 v[26:29], v[154:157], v[162:165], v[26:29]
	v_mfma_f32_16x16x32_bf16 v[26:29], v[158:161], v[166:169], v[26:29]
	v_mfma_f32_16x16x32_bf16 v[22:25], v[146:149], v[170:173], v[22:25]
	v_mfma_f32_16x16x32_bf16 v[22:25], v[150:153], v[174:177], v[22:25]
	v_mfma_f32_16x16x32_bf16 v[18:21], v[154:157], v[170:173], v[18:21]
	v_mfma_f32_16x16x32_bf16 v[18:21], v[158:161], v[174:177], v[18:21]
	v_mfma_f32_16x16x32_bf16 v[14:17], v[146:149], v[178:181], v[14:17]
	v_mfma_f32_16x16x32_bf16 v[14:17], v[150:153], v[182:185], v[14:17]
	v_mfma_f32_16x16x32_bf16 v[10:13], v[154:157], v[178:181], v[10:13]
	v_mfma_f32_16x16x32_bf16 v[10:13], v[158:161], v[182:185], v[10:13]
	v_mfma_f32_16x16x32_bf16 v[6:9], v[146:149], v[186:189], v[6:9]
	v_mfma_f32_16x16x32_bf16 v[6:9], v[150:153], v[190:193], v[6:9]
	s_setprio 2
	s_barrier
	v_mfma_f32_16x16x32_bf16 v[2:5], v[154:157], v[186:189], v[2:5]
	v_mfma_f32_16x16x32_bf16 v[2:5], v[158:161], v[190:193], v[2:5]
	s_setprio 0
	s_nop 0
	s_add_i32 s15, s90, 2
	s_cmp_gt_u32 s90, 13
	s_cbranch_scc1 .LBB0_2124
	v_mov_b32_e32 v130, v198
	s_mov_b32 s90, s15
	s_branch .LBB0_2099

.LBB0_2229:
	s_add_i32 s22, s46, 2
	s_lshl_b64 s[42:43], s[22:23], 15
	s_add_u32 s44, s2, s42
	s_addc_u32 s45, s3, s43
	s_and_b64 s[38:39], s[14:15], exec
	s_cselect_b32 s39, s45, s29
	s_cselect_b32 s38, s44, s28
	s_add_u32 s42, s16, s42
	s_waitcnt vmcnt(8)
	s_addc_u32 s43, s17, s43
	s_waitcnt lgkmcnt(0)
	s_and_b64 s[14:15], s[14:15], exec
	s_cselect_b32 s15, s43, s31
	s_cselect_b32 s14, s42, s30
	s_setprio 1
	s_barrier
	v_mfma_f32_16x16x32_bf16 v[126:129], v[146:149], v[186:189], v[126:129]
	v_mfma_f32_16x16x32_bf16 v[126:129], v[150:153], v[190:193], v[126:129]
	v_mfma_f32_16x16x32_bf16 v[122:125], v[154:157], v[186:189], v[122:125]
	v_mfma_f32_16x16x32_bf16 v[122:125], v[158:161], v[190:193], v[122:125]
	v_mfma_f32_16x16x32_bf16 v[118:121], v[146:149], v[178:181], v[118:121]
	v_mfma_f32_16x16x32_bf16 v[118:121], v[150:153], v[182:185], v[118:121]
	v_mfma_f32_16x16x32_bf16 v[114:117], v[154:157], v[178:181], v[114:117]
	v_mfma_f32_16x16x32_bf16 v[114:117], v[158:161], v[182:185], v[114:117]
	v_mfma_f32_16x16x32_bf16 v[110:113], v[146:149], v[170:173], v[110:113]
	v_mfma_f32_16x16x32_bf16 v[110:113], v[150:153], v[174:177], v[110:113]
	v_mfma_f32_16x16x32_bf16 v[106:109], v[154:157], v[170:173], v[106:109]
	v_mfma_f32_16x16x32_bf16 v[106:109], v[158:161], v[174:177], v[106:109]
	v_mfma_f32_16x16x32_bf16 v[102:105], v[146:149], v[162:165], v[102:105]
	v_mfma_f32_16x16x32_bf16 v[102:105], v[150:153], v[166:169], v[102:105]
	v_mfma_f32_16x16x32_bf16 v[98:101], v[154:157], v[162:165], v[98:101]
	v_mfma_f32_16x16x32_bf16 v[98:101], v[158:161], v[166:169], v[98:101]
	v_mfma_f32_16x16x32_bf16 v[94:97], v[130:133], v[186:189], v[94:97]
	v_mfma_f32_16x16x32_bf16 v[94:97], v[134:137], v[190:193], v[94:97]
	v_mfma_f32_16x16x32_bf16 v[90:93], v[138:141], v[186:189], v[90:93]
	v_mfma_f32_16x16x32_bf16 v[90:93], v[142:145], v[190:193], v[90:93]
	v_mfma_f32_16x16x32_bf16 v[86:89], v[130:133], v[178:181], v[86:89]
	v_mfma_f32_16x16x32_bf16 v[86:89], v[134:137], v[182:185], v[86:89]
	v_mfma_f32_16x16x32_bf16 v[82:85], v[138:141], v[178:181], v[82:85]
	v_mfma_f32_16x16x32_bf16 v[82:85], v[142:145], v[182:185], v[82:85]
	v_mfma_f32_16x16x32_bf16 v[78:81], v[130:133], v[170:173], v[78:81]
	v_mfma_f32_16x16x32_bf16 v[78:81], v[134:137], v[174:177], v[78:81]
	v_mfma_f32_16x16x32_bf16 v[74:77], v[138:141], v[170:173], v[74:77]
	v_mfma_f32_16x16x32_bf16 v[74:77], v[142:145], v[174:177], v[74:77]
	v_mfma_f32_16x16x32_bf16 v[70:73], v[130:133], v[162:165], v[70:73]
	v_mfma_f32_16x16x32_bf16 v[70:73], v[134:137], v[166:169], v[70:73]
	s_setprio 2
	s_barrier
	v_mfma_f32_16x16x32_bf16 v[66:69], v[138:141], v[162:165], v[66:69]
	v_mfma_f32_16x16x32_bf16 v[66:69], v[142:145], v[166:169], v[66:69]
	s_setprio 0
	s_nop 0
	ds_read_b128 v[186:189], v215 offset:16384
	ds_read_b128 v[190:193], v215 offset:17408
	ds_read_b128 v[178:181], v215 offset:18432
	ds_read_b128 v[182:185], v215 offset:19456
	ds_read_b128 v[170:173], v215 offset:20480
	ds_read_b128 v[174:177], v215 offset:21504
	ds_read_b128 v[162:165], v215 offset:22528
	ds_read_b128 v[166:169], v215 offset:23552
	s_mov_b32 m0, s57
	s_nop 0
	global_load_lds_dwordx4 v195, s[14:15]
	s_add_u32 m0, s57, 0x2000
	s_nop 0
	global_load_lds_dwordx4 v208, s[14:15]
	s_add_u32 s42, s14, 0x4000
	s_addc_u32 s43, s15, 0
	s_mov_b32 m0, s58
	s_nop 0
	global_load_lds_dwordx4 v195, s[42:43]
	s_add_u32 m0, s58, 0x2000
	s_nop 0
	global_load_lds_dwordx4 v208, s[42:43]
	s_andn2_b64 vcc, exec, s[40:41]
	s_mov_b32 m0, s56
	s_nop 0
	global_load_lds_dwordx4 v195, s[38:39]
	s_add_u32 m0, s56, 0x2000
	s_nop 0
	global_load_lds_dwordx4 v208, s[38:39]
	s_cbranch_vccnz .LBB0_2231
	v_mov_b32_e32 v2, 0
	v_mov_b32_e32 v3, v2
	v_mov_b32_e32 v4, v2
	v_mov_b32_e32 v5, v2
	v_mov_b32_e32 v6, v2
	v_mov_b32_e32 v7, v2
	v_mov_b32_e32 v8, v2
	v_mov_b32_e32 v9, v2
	v_mov_b32_e32 v10, v2
	v_mov_b32_e32 v11, v2
	v_mov_b32_e32 v12, v2
	v_mov_b32_e32 v13, v2
	v_mov_b32_e32 v14, v2
	v_mov_b32_e32 v15, v2
	v_mov_b32_e32 v16, v2
	v_mov_b32_e32 v17, v2
	v_mov_b32_e32 v18, v2
	v_mov_b32_e32 v19, v2
	v_mov_b32_e32 v20, v2
	v_mov_b32_e32 v21, v2
	v_mov_b32_e32 v22, v2
	v_mov_b32_e32 v23, v2
	v_mov_b32_e32 v24, v2
	v_mov_b32_e32 v25, v2
	v_mov_b32_e32 v26, v2
	v_mov_b32_e32 v27, v2
	v_mov_b32_e32 v28, v2
	v_mov_b32_e32 v29, v2
	v_mov_b32_e32 v30, v2
	v_mov_b32_e32 v31, v2
	v_mov_b32_e32 v32, v2
	v_mov_b32_e32 v33, v2
	v_mov_b32_e32 v34, v2
	v_mov_b32_e32 v35, v2
	v_mov_b32_e32 v36, v2
	v_mov_b32_e32 v37, v2
	v_mov_b32_e32 v38, v2
	v_mov_b32_e32 v39, v2
	v_mov_b32_e32 v40, v2
	v_mov_b32_e32 v41, v2
	v_mov_b32_e32 v42, v2
	v_mov_b32_e32 v43, v2
	v_mov_b32_e32 v44, v2
	v_mov_b32_e32 v45, v2
	v_mov_b32_e32 v46, v2
	v_mov_b32_e32 v47, v2
	v_mov_b32_e32 v48, v2
	v_mov_b32_e32 v49, v2
	v_mov_b32_e32 v50, v2
	v_mov_b32_e32 v51, v2
	v_mov_b32_e32 v52, v2
	v_mov_b32_e32 v53, v2
	v_mov_b32_e32 v54, v2
	v_mov_b32_e32 v55, v2
	v_mov_b32_e32 v56, v2
	v_mov_b32_e32 v57, v2
	v_mov_b32_e32 v58, v2
	v_mov_b32_e32 v59, v2
	v_mov_b32_e32 v60, v2
	v_mov_b32_e32 v61, v2
	v_mov_b32_e32 v62, v2
	v_mov_b32_e32 v63, v2
	v_mov_b32_e32 v64, v2
	v_mov_b32_e32 v65, v2
.LBB0_2231:
	s_waitcnt vmcnt(8)
	s_add_u32 s40, s38, 0x8000
	s_waitcnt lgkmcnt(0)
	s_addc_u32 s41, s39, 0
	s_add_u32 s42, s14, 0x8000
	s_addc_u32 s43, s15, 0
	s_setprio 1
	s_barrier
	v_mfma_f32_16x16x32_bf16 v[62:65], v[146:149], v[186:189], v[62:65]
	v_mfma_f32_16x16x32_bf16 v[62:65], v[150:153], v[190:193], v[62:65]
	v_mfma_f32_16x16x32_bf16 v[58:61], v[154:157], v[186:189], v[58:61]
	v_mfma_f32_16x16x32_bf16 v[58:61], v[158:161], v[190:193], v[58:61]
	v_mfma_f32_16x16x32_bf16 v[54:57], v[146:149], v[178:181], v[54:57]
	v_mfma_f32_16x16x32_bf16 v[54:57], v[150:153], v[182:185], v[54:57]
	v_mfma_f32_16x16x32_bf16 v[50:53], v[154:157], v[178:181], v[50:53]
	v_mfma_f32_16x16x32_bf16 v[50:53], v[158:161], v[182:185], v[50:53]
	v_mfma_f32_16x16x32_bf16 v[46:49], v[146:149], v[170:173], v[46:49]
	v_mfma_f32_16x16x32_bf16 v[46:49], v[150:153], v[174:177], v[46:49]
	v_mfma_f32_16x16x32_bf16 v[42:45], v[154:157], v[170:173], v[42:45]
	v_mfma_f32_16x16x32_bf16 v[42:45], v[158:161], v[174:177], v[42:45]
	v_mfma_f32_16x16x32_bf16 v[38:41], v[146:149], v[162:165], v[38:41]
	v_mfma_f32_16x16x32_bf16 v[38:41], v[150:153], v[166:169], v[38:41]
	v_mfma_f32_16x16x32_bf16 v[34:37], v[154:157], v[162:165], v[34:37]
	v_mfma_f32_16x16x32_bf16 v[34:37], v[158:161], v[166:169], v[34:37]
	v_mfma_f32_16x16x32_bf16 v[30:33], v[130:133], v[186:189], v[30:33]
	v_mfma_f32_16x16x32_bf16 v[30:33], v[134:137], v[190:193], v[30:33]
	v_mfma_f32_16x16x32_bf16 v[26:29], v[138:141], v[186:189], v[26:29]
	v_mfma_f32_16x16x32_bf16 v[26:29], v[142:145], v[190:193], v[26:29]
	v_mfma_f32_16x16x32_bf16 v[22:25], v[130:133], v[178:181], v[22:25]
	v_mfma_f32_16x16x32_bf16 v[22:25], v[134:137], v[182:185], v[22:25]
	v_mfma_f32_16x16x32_bf16 v[18:21], v[138:141], v[178:181], v[18:21]
	v_mfma_f32_16x16x32_bf16 v[18:21], v[142:145], v[182:185], v[18:21]
	v_mfma_f32_16x16x32_bf16 v[14:17], v[130:133], v[170:173], v[14:17]
	v_mfma_f32_16x16x32_bf16 v[14:17], v[134:137], v[174:177], v[14:17]
	v_mfma_f32_16x16x32_bf16 v[10:13], v[138:141], v[170:173], v[10:13]
	v_mfma_f32_16x16x32_bf16 v[10:13], v[142:145], v[174:177], v[10:13]
	v_mfma_f32_16x16x32_bf16 v[6:9], v[130:133], v[162:165], v[6:9]
	v_mfma_f32_16x16x32_bf16 v[6:9], v[134:137], v[166:169], v[6:9]
	s_setprio 2
	s_barrier
	v_mfma_f32_16x16x32_bf16 v[2:5], v[138:141], v[162:165], v[2:5]
	v_mfma_f32_16x16x32_bf16 v[2:5], v[142:145], v[166:169], v[2:5]
	s_setprio 0
	s_nop 0
	v_add_u32_e32 v142, 0x18000, v214
	v_add_u32_e32 v158, 0x1c000, v214
	ds_read_b128 v[130:133], v142
	ds_read_b128 v[134:137], v142 offset:1024
	ds_read_b128 v[138:141], v142 offset:2048
	ds_read_b128 v[142:145], v142 offset:3072
	ds_read_b128 v[146:149], v158
	ds_read_b128 v[150:153], v158 offset:1024
	ds_read_b128 v[154:157], v158 offset:2048
	ds_read_b128 v[158:161], v158 offset:3072
	ds_read_b128 v[162:165], v215 offset:32768
	ds_read_b128 v[166:169], v215 offset:33792
	ds_read_b128 v[170:173], v215 offset:34816
	ds_read_b128 v[174:177], v215 offset:35840
	ds_read_b128 v[178:181], v215 offset:36864
	ds_read_b128 v[182:185], v215 offset:37888
	ds_read_b128 v[186:189], v215 offset:38912
	ds_read_b128 v[190:193], v215 offset:39936
	s_add_u32 s38, s38, 0x4000
	s_addc_u32 s39, s39, 0
	s_mov_b32 m0, s59
	s_nop 0
	global_load_lds_dwordx4 v195, s[38:39]
	s_add_u32 m0, s59, 0x2000
	s_nop 0
	global_load_lds_dwordx4 v208, s[38:39]
	s_waitcnt vmcnt(8)
	s_waitcnt lgkmcnt(0)
	s_setprio 1
	s_barrier
	v_mfma_f32_16x16x32_bf16 v[126:129], v[130:133], v[162:165], v[126:129]
	v_mfma_f32_16x16x32_bf16 v[126:129], v[134:137], v[166:169], v[126:129]
	v_mfma_f32_16x16x32_bf16 v[122:125], v[138:141], v[162:165], v[122:125]
	v_mfma_f32_16x16x32_bf16 v[122:125], v[142:145], v[166:169], v[122:125]
	v_mfma_f32_16x16x32_bf16 v[118:121], v[130:133], v[170:173], v[118:121]
	v_mfma_f32_16x16x32_bf16 v[118:121], v[134:137], v[174:177], v[118:121]
	v_mfma_f32_16x16x32_bf16 v[114:117], v[138:141], v[170:173], v[114:117]
	v_mfma_f32_16x16x32_bf16 v[114:117], v[142:145], v[174:177], v[114:117]
	v_mfma_f32_16x16x32_bf16 v[110:113], v[130:133], v[178:181], v[110:113]
	v_mfma_f32_16x16x32_bf16 v[110:113], v[134:137], v[182:185], v[110:113]
	v_mfma_f32_16x16x32_bf16 v[106:109], v[138:141], v[178:181], v[106:109]
	v_mfma_f32_16x16x32_bf16 v[106:109], v[142:145], v[182:185], v[106:109]
	v_mfma_f32_16x16x32_bf16 v[102:105], v[130:133], v[186:189], v[102:105]
	v_mfma_f32_16x16x32_bf16 v[102:105], v[134:137], v[190:193], v[102:105]
	v_mfma_f32_16x16x32_bf16 v[98:101], v[138:141], v[186:189], v[98:101]
	v_mfma_f32_16x16x32_bf16 v[98:101], v[142:145], v[190:193], v[98:101]
	v_mfma_f32_16x16x32_bf16 v[94:97], v[146:149], v[162:165], v[94:97]
	v_mfma_f32_16x16x32_bf16 v[94:97], v[150:153], v[166:169], v[94:97]
	v_mfma_f32_16x16x32_bf16 v[90:93], v[154:157], v[162:165], v[90:93]
	v_mfma_f32_16x16x32_bf16 v[90:93], v[158:161], v[166:169], v[90:93]
	v_mfma_f32_16x16x32_bf16 v[86:89], v[146:149], v[170:173], v[86:89]
	v_mfma_f32_16x16x32_bf16 v[86:89], v[150:153], v[174:177], v[86:89]
	v_mfma_f32_16x16x32_bf16 v[82:85], v[154:157], v[170:173], v[82:85]
	v_mfma_f32_16x16x32_bf16 v[82:85], v[158:161], v[174:177], v[82:85]
	v_mfma_f32_16x16x32_bf16 v[78:81], v[146:149], v[178:181], v[78:81]
	v_mfma_f32_16x16x32_bf16 v[78:81], v[150:153], v[182:185], v[78:81]
	v_mfma_f32_16x16x32_bf16 v[74:77], v[154:157], v[178:181], v[74:77]
	v_mfma_f32_16x16x32_bf16 v[74:77], v[158:161], v[182:185], v[74:77]
	v_mfma_f32_16x16x32_bf16 v[70:73], v[146:149], v[186:189], v[70:73]
	v_mfma_f32_16x16x32_bf16 v[70:73], v[150:153], v[190:193], v[70:73]
	s_setprio 2
	s_barrier
	v_mfma_f32_16x16x32_bf16 v[66:69], v[154:157], v[186:189], v[66:69]
	v_mfma_f32_16x16x32_bf16 v[66:69], v[158:161], v[190:193], v[66:69]
	s_setprio 0
	s_nop 0
	ds_read_b128 v[162:165], v215 offset:49152
	ds_read_b128 v[166:169], v215 offset:50176
	ds_read_b128 v[170:173], v215 offset:51200
	ds_read_b128 v[174:177], v215 offset:52224
	ds_read_b128 v[178:181], v215 offset:53248
	ds_read_b128 v[182:185], v215 offset:54272
	ds_read_b128 v[186:189], v215 offset:55296
	ds_read_b128 v[190:193], v215 offset:56320
	s_mov_b32 m0, s63
	s_nop 0
	global_load_lds_dwordx4 v195, s[42:43]
	s_add_u32 m0, s63, 0x2000
	s_nop 0
	global_load_lds_dwordx4 v208, s[42:43]
	s_add_u32 s14, s14, 0xc000
	s_addc_u32 s15, s15, 0
	s_mov_b32 m0, s65
	s_nop 0
	global_load_lds_dwordx4 v195, s[14:15]
	s_add_u32 m0, s65, 0x2000
	s_nop 0
	global_load_lds_dwordx4 v208, s[14:15]
	s_nop 0
	s_mov_b32 m0, s64
	s_nop 0
	global_load_lds_dwordx4 v195, s[40:41]
	s_add_u32 m0, s64, 0x2000
	s_nop 0
	global_load_lds_dwordx4 v208, s[40:41]
	s_waitcnt vmcnt(8)
	s_waitcnt lgkmcnt(0)
	s_setprio 1
	s_barrier
	v_mfma_f32_16x16x32_bf16 v[62:65], v[130:133], v[162:165], v[62:65]
	v_mfma_f32_16x16x32_bf16 v[62:65], v[134:137], v[166:169], v[62:65]
	v_mfma_f32_16x16x32_bf16 v[58:61], v[138:141], v[162:165], v[58:61]
	v_mfma_f32_16x16x32_bf16 v[58:61], v[142:145], v[166:169], v[58:61]
	v_mfma_f32_16x16x32_bf16 v[54:57], v[130:133], v[170:173], v[54:57]
	v_mfma_f32_16x16x32_bf16 v[54:57], v[134:137], v[174:177], v[54:57]
	v_mfma_f32_16x16x32_bf16 v[50:53], v[138:141], v[170:173], v[50:53]
	v_mfma_f32_16x16x32_bf16 v[50:53], v[142:145], v[174:177], v[50:53]
	v_mfma_f32_16x16x32_bf16 v[46:49], v[130:133], v[178:181], v[46:49]
	v_mfma_f32_16x16x32_bf16 v[46:49], v[134:137], v[182:185], v[46:49]
	v_mfma_f32_16x16x32_bf16 v[42:45], v[138:141], v[178:181], v[42:45]
	v_mfma_f32_16x16x32_bf16 v[42:45], v[142:145], v[182:185], v[42:45]
	v_mfma_f32_16x16x32_bf16 v[38:41], v[130:133], v[186:189], v[38:41]
	v_mfma_f32_16x16x32_bf16 v[38:41], v[134:137], v[190:193], v[38:41]
	v_mfma_f32_16x16x32_bf16 v[34:37], v[138:141], v[186:189], v[34:37]
	v_mfma_f32_16x16x32_bf16 v[34:37], v[142:145], v[190:193], v[34:37]
	v_mfma_f32_16x16x32_bf16 v[30:33], v[146:149], v[162:165], v[30:33]
	v_mfma_f32_16x16x32_bf16 v[30:33], v[150:153], v[166:169], v[30:33]
	v_mfma_f32_16x16x32_bf16 v[26:29], v[154:157], v[162:165], v[26:29]
	v_mfma_f32_16x16x32_bf16 v[26:29], v[158:161], v[166:169], v[26:29]
	v_mfma_f32_16x16x32_bf16 v[22:25], v[146:149], v[170:173], v[22:25]
	v_mfma_f32_16x16x32_bf16 v[22:25], v[150:153], v[174:177], v[22:25]
	v_mfma_f32_16x16x32_bf16 v[18:21], v[154:157], v[170:173], v[18:21]
	v_mfma_f32_16x16x32_bf16 v[18:21], v[158:161], v[174:177], v[18:21]
	v_mfma_f32_16x16x32_bf16 v[14:17], v[146:149], v[178:181], v[14:17]
	v_mfma_f32_16x16x32_bf16 v[14:17], v[150:153], v[182:185], v[14:17]
	v_mfma_f32_16x16x32_bf16 v[10:13], v[154:157], v[178:181], v[10:13]
	v_mfma_f32_16x16x32_bf16 v[10:13], v[158:161], v[182:185], v[10:13]
	v_mfma_f32_16x16x32_bf16 v[6:9], v[146:149], v[186:189], v[6:9]
	v_mfma_f32_16x16x32_bf16 v[6:9], v[150:153], v[190:193], v[6:9]
	s_setprio 2
	s_barrier
	v_mfma_f32_16x16x32_bf16 v[2:5], v[154:157], v[186:189], v[2:5]
	v_mfma_f32_16x16x32_bf16 v[2:5], v[158:161], v[190:193], v[2:5]
	s_setprio 0
	s_nop 0
	s_cmp_gt_u32 s46, 41
	s_cbranch_scc1 .LBB0_2233
	v_mov_b32_e32 v130, v196
	s_mov_b32 s46, s22
	s_branch .LBB0_2208
